# GEMM main loops: duplicate lgkmcnt(0) after the block barrier removed; compute dtype stated at top
# baseline (speedup 1.0000x reference)
; #define PG8_STAGE(bufoff, gbase, voff) do { _Pragma("unroll") for (int _i = 0; _i < 2; ++_i) \
;         __builtin_amdgcn_global_load_lds((const unsigned*)((const char*)(gbase) + (voff)[_i]), (LAS unsigned*)(lds + (bufoff) + ldsw + _i * 8192), 16, 0, 0); } while (0)
; #define PG8_LDA(dst, b, h) do { _Pragma("unroll") for (int m = 0; m < 4; ++m) _Pragma("unroll") for (int k = 0; k < 2; ++k) dst[m][k] = *(const LAS bf16x8*)(lds + PG8_SA(b, h) + aoff + m * 2048 + k * 1024); } while (0)
; #define PG8_LDB(dst, b, h) do { _Pragma("unroll") for (int n = 0; n < 2; ++n) _Pragma("unroll") for (int k = 0; k < 2; ++k) dst[n][k] = *(const LAS bf16x8*)(lds + PG8_SB(b, h) + boff + n * 2048 + k * 1024); } while (0)
; #define PG8_MMA(ai, bj, At, Bt) do { __builtin_amdgcn_s_setprio(1); _Pragma("unroll") for (int m = 0; m < 4; ++m) _Pragma("unroll") for (int n = 0; n < 2; ++n) _Pragma("unroll") for (int k = 0; k < 2; ++k) \
;         acc[ai][bj][m][n] = __builtin_amdgcn_mfma_f32_16x16x32_bf16(Bt[n][k], At[m][k], acc[ai][bj][m][n], 0, 0, 0); __builtin_amdgcn_s_setprio(0); } while (0)
; #define PG8_WAIT_V(n) asm volatile("s_waitcnt vmcnt(" #n ")" ::: "memory")
; #define PG8_WAIT_L(n) asm volatile("s_waitcnt lgkmcnt(" #n ")" ::: "memory")
; #define PG8_BAR __builtin_amdgcn_s_barrier()
; #define PG8_SCHED __builtin_amdgcn_sched_barrier(0)
;     ...
;             PG8_LDB(B0, 0, 0); PG8_LDB(B1, 0, 1); PG8_SCHED; PG8_LDA(At, 0, 0); PG8_STAGE(PG8_SA(1, 1), a1 + hstep, voffA);
;             PG8_WAIT_V(8); PG8_WAIT_L(0); PG8_BAR; PG8_MMA(0, 0, At, B0); PG8_MMA(0, 1, At, B1); PG8_BAR; PG8_SCHED;
;             PG8_LDA(At, 0, 1); PG8_STAGE(PG8_SB(0, 0), b2, voffB); PG8_STAGE(PG8_SB(0, 1), b2 + hstep, voffB); PG8_STAGE(PG8_SA(0, 0), a2, voffA);
;             PG8_WAIT_V(8); PG8_WAIT_L(0); PG8_BAR; PG8_MMA(1, 0, At, B0); PG8_MMA(1, 1, At, B1); PG8_BAR; PG8_SCHED;
.LBB0_58:
	s_add_i32 s30, s10, 2
	s_add_u32 s4, s26, 0x80
	s_addc_u32 s5, s27, 0
	s_add_i32 s6, 0, 0x10000
	s_cmp_eq_u32 s55, s10
	s_cselect_b32 s11, s23, s5
	s_cselect_b32 s10, s22, s4
	s_cselect_b32 s5, s25, s29
	s_cselect_b32 s4, s24, s28
	s_add_i32 s7, 0, 0x14000
	v_add_u32_e32 v154, s6, v171
	v_add_u32_e32 v173, s7, v171
	ds_read_b128 v[142:145], v154
	ds_read_b128 v[146:149], v154 offset:1024
	ds_read_b128 v[150:153], v154 offset:2048
	ds_read_b128 v[154:157], v154 offset:3072
	ds_read_b128 v[158:161], v173
	ds_read_b128 v[162:165], v173 offset:1024
	ds_read_b128 v[166:169], v173 offset:2048
	ds_read_b128 v[174:177], v173 offset:3072
	v_lshl_add_u64 v[214:215], s[26:27], 0, v[138:139]
	s_add_i32 m0, s39, 0xc000
	ds_read_b128 v[188:191], v172
	ds_read_b128 v[192:195], v172 offset:1024
	ds_read_b128 v[196:199], v172 offset:2048
	ds_read_b128 v[200:203], v172 offset:3072
	ds_read_b128 v[204:207], v172 offset:4096
	ds_read_b128 v[208:211], v172 offset:5120
	ds_read_b128 v[226:229], v172 offset:6144
	ds_read_b128 v[230:233], v172 offset:7168
	global_load_lds_dwordx4 v[214:215], off
	v_lshl_add_u64 v[214:215], s[26:27], 0, v[140:141]
	s_add_i32 m0, s39, 0xe000
	s_nop 0
	global_load_lds_dwordx4 v[214:215], off
	s_waitcnt vmcnt(8)
	s_waitcnt lgkmcnt(0)
	s_barrier
	s_setprio 1
	v_mfma_f32_16x16x32_bf16 v[126:129], v[142:145], v[188:191], v[126:129]
	v_mfma_f32_16x16x32_bf16 v[122:125], v[150:153], v[188:191], v[122:125]
	v_mfma_f32_16x16x32_bf16 v[118:121], v[142:145], v[196:199], v[118:121]
	v_mfma_f32_16x16x32_bf16 v[114:117], v[150:153], v[196:199], v[114:117]
	v_mfma_f32_16x16x32_bf16 v[110:113], v[142:145], v[204:207], v[110:113]
	v_mfma_f32_16x16x32_bf16 v[106:109], v[150:153], v[204:207], v[106:109]
	v_mfma_f32_16x16x32_bf16 v[102:105], v[142:145], v[226:229], v[102:105]
	v_mfma_f32_16x16x32_bf16 v[98:101], v[150:153], v[226:229], v[98:101]
	v_mfma_f32_16x16x32_bf16 v[126:129], v[146:149], v[192:195], v[126:129]
	v_mfma_f32_16x16x32_bf16 v[122:125], v[154:157], v[192:195], v[122:125]
	v_mfma_f32_16x16x32_bf16 v[118:121], v[146:149], v[200:203], v[118:121]
	v_mfma_f32_16x16x32_bf16 v[114:117], v[154:157], v[200:203], v[114:117]
	v_mfma_f32_16x16x32_bf16 v[110:113], v[146:149], v[208:211], v[110:113]
	v_mfma_f32_16x16x32_bf16 v[106:109], v[154:157], v[208:211], v[106:109]
	v_mfma_f32_16x16x32_bf16 v[102:105], v[146:149], v[230:233], v[102:105]
	v_mfma_f32_16x16x32_bf16 v[98:101], v[154:157], v[230:233], v[98:101]
	s_setprio 0
	s_setprio 1
	v_mfma_f32_16x16x32_bf16 v[60:63], v[158:161], v[188:191], v[60:63]
	v_mfma_f32_16x16x32_bf16 v[56:59], v[166:169], v[188:191], v[56:59]
	v_mfma_f32_16x16x32_bf16 v[52:55], v[158:161], v[196:199], v[52:55]
	v_mfma_f32_16x16x32_bf16 v[48:51], v[166:169], v[196:199], v[48:51]
	v_mfma_f32_16x16x32_bf16 v[44:47], v[158:161], v[204:207], v[44:47]
	v_mfma_f32_16x16x32_bf16 v[40:43], v[166:169], v[204:207], v[40:43]
	v_mfma_f32_16x16x32_bf16 v[36:39], v[158:161], v[226:229], v[36:39]
	v_mfma_f32_16x16x32_bf16 v[32:35], v[166:169], v[226:229], v[32:35]
	v_mfma_f32_16x16x32_bf16 v[60:63], v[162:165], v[192:195], v[60:63]
	v_mfma_f32_16x16x32_bf16 v[56:59], v[174:177], v[192:195], v[56:59]
	v_mfma_f32_16x16x32_bf16 v[52:55], v[162:165], v[200:203], v[52:55]
	v_mfma_f32_16x16x32_bf16 v[48:51], v[174:177], v[200:203], v[48:51]
	v_mfma_f32_16x16x32_bf16 v[44:47], v[162:165], v[208:211], v[44:47]
	v_mfma_f32_16x16x32_bf16 v[40:43], v[174:177], v[208:211], v[40:43]
	v_mfma_f32_16x16x32_bf16 v[36:39], v[162:165], v[230:233], v[36:39]
	v_mfma_f32_16x16x32_bf16 v[32:35], v[174:177], v[230:233], v[32:35]
	s_setprio 0
	s_barrier
	s_add_i32 s6, s6, s38
	v_lshl_add_u64 v[214:215], s[4:5], 0, v[134:135]
	s_mov_b32 m0, s6
	ds_read_b128 v[188:191], v172 offset:16384
	ds_read_b128 v[192:195], v172 offset:17408
	ds_read_b128 v[196:199], v172 offset:18432
	ds_read_b128 v[200:203], v172 offset:19456
	ds_read_b128 v[204:207], v172 offset:20480
	ds_read_b128 v[208:211], v172 offset:21504
	ds_read_b128 v[226:229], v172 offset:22528
	ds_read_b128 v[230:233], v172 offset:23552
	global_load_lds_dwordx4 v[214:215], off
	s_add_i32 m0, s6, 0x2000
	v_lshl_add_u64 v[234:235], s[4:5], 0, v[130:131]
	s_add_u32 s4, s4, s16
	s_addc_u32 s5, s5, 0
	s_add_i32 s6, s7, s38
	global_load_lds_dwordx4 v[234:235], off
	v_lshl_add_u64 v[236:237], s[4:5], 0, v[134:135]
	s_mov_b32 m0, s6
	v_lshl_add_u64 v[238:239], s[4:5], 0, v[130:131]
	global_load_lds_dwordx4 v[236:237], off
	s_add_i32 m0, s6, 0x2000
	v_lshl_add_u64 v[240:241], s[10:11], 0, v[136:137]
	global_load_lds_dwordx4 v[238:239], off
	s_mov_b32 m0, s39
	v_lshl_add_u64 v[242:243], s[10:11], 0, v[132:133]
	global_load_lds_dwordx4 v[240:241], off
	s_mov_b32 m0, s40
	s_nop 0
	global_load_lds_dwordx4 v[242:243], off
	s_waitcnt vmcnt(8)
	s_waitcnt lgkmcnt(0)
	s_barrier
; #define PG8_STAGE(bufoff, gbase, voff) do { _Pragma("unroll") for (int _i = 0; _i < 2; ++_i) \
;         __builtin_amdgcn_global_load_lds((const unsigned*)((const char*)(gbase) + (voff)[_i]), (LAS unsigned*)(lds + (bufoff) + ldsw + _i * 8192), 16, 0, 0); } while (0)
; #define PG8_LDA(dst, b, h) do { _Pragma("unroll") for (int m = 0; m < 4; ++m) _Pragma("unroll") for (int k = 0; k < 2; ++k) dst[m][k] = *(const LAS bf16x8*)(lds + PG8_SA(b, h) + aoff + m * 2048 + k * 1024); } while (0)
; #define PG8_LDB(dst, b, h) do { _Pragma("unroll") for (int n = 0; n < 2; ++n) _Pragma("unroll") for (int k = 0; k < 2; ++k) dst[n][k] = *(const LAS bf16x8*)(lds + PG8_SB(b, h) + boff + n * 2048 + k * 1024); } while (0)
; #define PG8_MMA(ai, bj, At, Bt) do { __builtin_amdgcn_s_setprio(1); _Pragma("unroll") for (int m = 0; m < 4; ++m) _Pragma("unroll") for (int n = 0; n < 2; ++n) _Pragma("unroll") for (int k = 0; k < 2; ++k) \
;         acc[ai][bj][m][n] = __builtin_amdgcn_mfma_f32_16x16x32_bf16(Bt[n][k], At[m][k], acc[ai][bj][m][n], 0, 0, 0); __builtin_amdgcn_s_setprio(0); } while (0)
; #define PG8_WAIT_V(n) asm volatile("s_waitcnt vmcnt(" #n ")" ::: "memory")
; #define PG8_WAIT_L(n) asm volatile("s_waitcnt lgkmcnt(" #n ")" ::: "memory")
; #define PG8_BAR __builtin_amdgcn_s_barrier()
; #define PG8_SCHED __builtin_amdgcn_sched_barrier(0)
;     ...
;             PG8_WAIT_V(8); PG8_WAIT_L(0); PG8_BAR; PG8_MMA(1, 0, At, B0); PG8_MMA(1, 1, At, B1); PG8_BAR; PG8_SCHED;
;             PG8_LDB(B0, 1, 0); PG8_LDB(B1, 1, 1); PG8_SCHED; PG8_LDA(At, 1, 0); PG8_STAGE(PG8_SA(0, 1), a2 + hstep, voffA);
;             PG8_WAIT_V(8); PG8_WAIT_L(0); PG8_BAR; PG8_MMA(0, 0, At, B0); PG8_MMA(0, 1, At, B1); PG8_BAR; PG8_SCHED;
	s_setprio 1
	v_mfma_f32_16x16x32_bf16 v[92:95], v[142:145], v[188:191], v[92:95]
	v_mfma_f32_16x16x32_bf16 v[88:91], v[150:153], v[188:191], v[88:91]
	v_mfma_f32_16x16x32_bf16 v[84:87], v[142:145], v[196:199], v[84:87]
	v_mfma_f32_16x16x32_bf16 v[80:83], v[150:153], v[196:199], v[80:83]
	v_mfma_f32_16x16x32_bf16 v[76:79], v[142:145], v[204:207], v[76:79]
	v_mfma_f32_16x16x32_bf16 v[72:75], v[150:153], v[204:207], v[72:75]
	v_mfma_f32_16x16x32_bf16 v[68:71], v[142:145], v[226:229], v[68:71]
	v_mfma_f32_16x16x32_bf16 v[64:67], v[150:153], v[226:229], v[64:67]
	v_mfma_f32_16x16x32_bf16 v[92:95], v[146:149], v[192:195], v[92:95]
	v_mfma_f32_16x16x32_bf16 v[88:91], v[154:157], v[192:195], v[88:91]
	v_mfma_f32_16x16x32_bf16 v[84:87], v[146:149], v[200:203], v[84:87]
	v_mfma_f32_16x16x32_bf16 v[80:83], v[154:157], v[200:203], v[80:83]
	v_mfma_f32_16x16x32_bf16 v[76:79], v[146:149], v[208:211], v[76:79]
	v_mfma_f32_16x16x32_bf16 v[72:75], v[154:157], v[208:211], v[72:75]
	v_mfma_f32_16x16x32_bf16 v[68:71], v[146:149], v[230:233], v[68:71]
	v_mfma_f32_16x16x32_bf16 v[64:67], v[154:157], v[230:233], v[64:67]
	s_setprio 0
	s_setprio 1
	v_mfma_f32_16x16x32_bf16 v[28:31], v[158:161], v[188:191], v[28:31]
	v_mfma_f32_16x16x32_bf16 v[24:27], v[166:169], v[188:191], v[24:27]
	v_mfma_f32_16x16x32_bf16 v[20:23], v[158:161], v[196:199], v[20:23]
	v_mfma_f32_16x16x32_bf16 v[16:19], v[166:169], v[196:199], v[16:19]
	v_mfma_f32_16x16x32_bf16 v[12:15], v[158:161], v[204:207], v[12:15]
	v_mfma_f32_16x16x32_bf16 v[8:11], v[166:169], v[204:207], v[8:11]
	v_mfma_f32_16x16x32_bf16 v[4:7], v[158:161], v[226:229], v[4:7]
	v_mfma_f32_16x16x32_bf16 v[0:3], v[166:169], v[226:229], v[0:3]
	v_mfma_f32_16x16x32_bf16 v[28:31], v[162:165], v[192:195], v[28:31]
	v_mfma_f32_16x16x32_bf16 v[24:27], v[174:177], v[192:195], v[24:27]
	v_mfma_f32_16x16x32_bf16 v[20:23], v[162:165], v[200:203], v[20:23]
	v_mfma_f32_16x16x32_bf16 v[16:19], v[174:177], v[200:203], v[16:19]
	v_mfma_f32_16x16x32_bf16 v[12:15], v[162:165], v[208:211], v[12:15]
	v_mfma_f32_16x16x32_bf16 v[8:11], v[174:177], v[208:211], v[8:11]
	v_mfma_f32_16x16x32_bf16 v[4:7], v[162:165], v[230:233], v[4:7]
	v_mfma_f32_16x16x32_bf16 v[0:3], v[174:177], v[230:233], v[0:3]
	s_setprio 0
	s_barrier
	s_add_i32 s6, 0, 0x18000
	s_add_i32 s7, 0, 0x1c000
	v_add_u32_e32 v154, s6, v171
	v_add_u32_e32 v173, s7, v171
	ds_read_b128 v[142:145], v154
	ds_read_b128 v[146:149], v154 offset:1024
	ds_read_b128 v[150:153], v154 offset:2048
	ds_read_b128 v[154:157], v154 offset:3072
	ds_read_b128 v[158:161], v173
	ds_read_b128 v[162:165], v173 offset:1024
	ds_read_b128 v[166:169], v173 offset:2048
	ds_read_b128 v[174:177], v173 offset:3072
	s_add_u32 s4, s10, s16
	s_addc_u32 s5, s11, 0
	s_mov_b32 m0, s41
	v_lshl_add_u64 v[244:245], s[4:5], 0, v[136:137]
	ds_read_b128 v[188:191], v172 offset:32768
	ds_read_b128 v[192:195], v172 offset:33792
	ds_read_b128 v[196:199], v172 offset:34816
	ds_read_b128 v[200:203], v172 offset:35840
	ds_read_b128 v[204:207], v172 offset:36864
	ds_read_b128 v[208:211], v172 offset:37888
	ds_read_b128 v[226:229], v172 offset:38912
	ds_read_b128 v[230:233], v172 offset:39936
	global_load_lds_dwordx4 v[244:245], off
	v_lshl_add_u64 v[244:245], s[4:5], 0, v[132:133]
	s_mov_b32 m0, s42
	s_nop 0
	global_load_lds_dwordx4 v[244:245], off
	s_waitcnt vmcnt(8)
	s_waitcnt lgkmcnt(0)
	s_barrier
	s_setprio 1
	v_mfma_f32_16x16x32_bf16 v[126:129], v[142:145], v[188:191], v[126:129]
	v_mfma_f32_16x16x32_bf16 v[122:125], v[150:153], v[188:191], v[122:125]
	v_mfma_f32_16x16x32_bf16 v[118:121], v[142:145], v[196:199], v[118:121]
	v_mfma_f32_16x16x32_bf16 v[114:117], v[150:153], v[196:199], v[114:117]
	v_mfma_f32_16x16x32_bf16 v[110:113], v[142:145], v[204:207], v[110:113]
	v_mfma_f32_16x16x32_bf16 v[106:109], v[150:153], v[204:207], v[106:109]
	v_mfma_f32_16x16x32_bf16 v[102:105], v[142:145], v[226:229], v[102:105]
	v_mfma_f32_16x16x32_bf16 v[98:101], v[150:153], v[226:229], v[98:101]
	v_mfma_f32_16x16x32_bf16 v[126:129], v[146:149], v[192:195], v[126:129]
	v_mfma_f32_16x16x32_bf16 v[122:125], v[154:157], v[192:195], v[122:125]
	v_mfma_f32_16x16x32_bf16 v[118:121], v[146:149], v[200:203], v[118:121]
	v_mfma_f32_16x16x32_bf16 v[114:117], v[154:157], v[200:203], v[114:117]
	v_mfma_f32_16x16x32_bf16 v[110:113], v[146:149], v[208:211], v[110:113]
	v_mfma_f32_16x16x32_bf16 v[106:109], v[154:157], v[208:211], v[106:109]
	v_mfma_f32_16x16x32_bf16 v[102:105], v[146:149], v[230:233], v[102:105]
	v_mfma_f32_16x16x32_bf16 v[98:101], v[154:157], v[230:233], v[98:101]
	s_setprio 0
	s_setprio 1
	v_mfma_f32_16x16x32_bf16 v[60:63], v[158:161], v[188:191], v[60:63]
	v_mfma_f32_16x16x32_bf16 v[56:59], v[166:169], v[188:191], v[56:59]
	v_mfma_f32_16x16x32_bf16 v[52:55], v[158:161], v[196:199], v[52:55]
	v_mfma_f32_16x16x32_bf16 v[48:51], v[166:169], v[196:199], v[48:51]
	v_mfma_f32_16x16x32_bf16 v[44:47], v[158:161], v[204:207], v[44:47]
	v_mfma_f32_16x16x32_bf16 v[40:43], v[166:169], v[204:207], v[40:43]
	v_mfma_f32_16x16x32_bf16 v[36:39], v[158:161], v[226:229], v[36:39]
	v_mfma_f32_16x16x32_bf16 v[32:35], v[166:169], v[226:229], v[32:35]
	v_mfma_f32_16x16x32_bf16 v[60:63], v[162:165], v[192:195], v[60:63]
	v_mfma_f32_16x16x32_bf16 v[56:59], v[174:177], v[192:195], v[56:59]
	v_mfma_f32_16x16x32_bf16 v[52:55], v[162:165], v[200:203], v[52:55]
	v_mfma_f32_16x16x32_bf16 v[48:51], v[174:177], v[200:203], v[48:51]
	v_mfma_f32_16x16x32_bf16 v[44:47], v[162:165], v[208:211], v[44:47]
	v_mfma_f32_16x16x32_bf16 v[40:43], v[174:177], v[208:211], v[40:43]
	v_mfma_f32_16x16x32_bf16 v[36:39], v[162:165], v[230:233], v[36:39]
	v_mfma_f32_16x16x32_bf16 v[32:35], v[174:177], v[230:233], v[32:35]
	s_setprio 0
	s_barrier
; #define PG8_STAGE(bufoff, gbase, voff) do { _Pragma("unroll") for (int _i = 0; _i < 2; ++_i) \
;         __builtin_amdgcn_global_load_lds((const unsigned*)((const char*)(gbase) + (voff)[_i]), (LAS unsigned*)(lds + (bufoff) + ldsw + _i * 8192), 16, 0, 0); } while (0)
; #define PG8_LDA(dst, b, h) do { _Pragma("unroll") for (int m = 0; m < 4; ++m) _Pragma("unroll") for (int k = 0; k < 2; ++k) dst[m][k] = *(const LAS bf16x8*)(lds + PG8_SA(b, h) + aoff + m * 2048 + k * 1024); } while (0)
; #define PG8_MMA(ai, bj, At, Bt) do { __builtin_amdgcn_s_setprio(1); _Pragma("unroll") for (int m = 0; m < 4; ++m) _Pragma("unroll") for (int n = 0; n < 2; ++n) _Pragma("unroll") for (int k = 0; k < 2; ++k) \
;         acc[ai][bj][m][n] = __builtin_amdgcn_mfma_f32_16x16x32_bf16(Bt[n][k], At[m][k], acc[ai][bj][m][n], 0, 0, 0); __builtin_amdgcn_s_setprio(0); } while (0)
; #define PG8_WAIT_V(n) asm volatile("s_waitcnt vmcnt(" #n ")" ::: "memory")
; #define PG8_WAIT_L(n) asm volatile("s_waitcnt lgkmcnt(" #n ")" ::: "memory")
; #define PG8_BAR __builtin_amdgcn_s_barrier()
; #define PG8_SCHED __builtin_amdgcn_sched_barrier(0)
;     ...
;         for (int t = 0; t < nt; t += 2) {
;     ...
;             PG8_LDA(At, 1, 1); PG8_STAGE(PG8_SB(1, 0), b3, voffB); PG8_STAGE(PG8_SB(1, 1), b3 + hstep, voffB); PG8_STAGE(PG8_SA(1, 0), a3, voffA);
;             PG8_WAIT_V(8); PG8_WAIT_L(0); PG8_BAR; PG8_MMA(1, 0, At, B0); PG8_MMA(1, 1, At, B1); PG8_BAR; PG8_SCHED;
;         }
	s_add_i32 s4, s6, s38
	v_lshl_add_u64 v[214:215], v[214:215], 0, s[46:47]
	s_mov_b32 m0, s4
	ds_read_b128 v[188:191], v172 offset:49152
	ds_read_b128 v[192:195], v172 offset:50176
	ds_read_b128 v[196:199], v172 offset:51200
	ds_read_b128 v[200:203], v172 offset:52224
	ds_read_b128 v[204:207], v172 offset:53248
	ds_read_b128 v[208:211], v172 offset:54272
	ds_read_b128 v[226:229], v172 offset:55296
	ds_read_b128 v[230:233], v172 offset:56320
	global_load_lds_dwordx4 v[214:215], off
	v_lshl_add_u64 v[214:215], v[234:235], 0, s[46:47]
	s_add_i32 m0, s4, 0x2000
	s_add_i32 s4, s7, s38
	global_load_lds_dwordx4 v[214:215], off
	v_lshl_add_u64 v[214:215], v[236:237], 0, s[46:47]
	s_mov_b32 m0, s4
	s_nop 0
	global_load_lds_dwordx4 v[214:215], off
	v_lshl_add_u64 v[214:215], v[238:239], 0, s[46:47]
	s_add_i32 m0, s4, 0x2000
	s_nop 0
	global_load_lds_dwordx4 v[214:215], off
	v_lshl_add_u64 v[214:215], v[240:241], 0, s[46:47]
	s_mov_b32 m0, s43
	s_nop 0
	global_load_lds_dwordx4 v[214:215], off
	v_lshl_add_u64 v[214:215], v[242:243], 0, s[46:47]
	s_mov_b32 m0, s50
	s_nop 0
	global_load_lds_dwordx4 v[214:215], off
	s_waitcnt vmcnt(8)
	s_waitcnt lgkmcnt(0)
	s_barrier
	s_setprio 1
	v_mfma_f32_16x16x32_bf16 v[92:95], v[142:145], v[188:191], v[92:95]
	v_mfma_f32_16x16x32_bf16 v[88:91], v[150:153], v[188:191], v[88:91]
	v_mfma_f32_16x16x32_bf16 v[84:87], v[142:145], v[196:199], v[84:87]
	v_mfma_f32_16x16x32_bf16 v[80:83], v[150:153], v[196:199], v[80:83]
	v_mfma_f32_16x16x32_bf16 v[76:79], v[142:145], v[204:207], v[76:79]
	v_mfma_f32_16x16x32_bf16 v[72:75], v[150:153], v[204:207], v[72:75]
	v_mfma_f32_16x16x32_bf16 v[68:71], v[142:145], v[226:229], v[68:71]
	v_mfma_f32_16x16x32_bf16 v[64:67], v[150:153], v[226:229], v[64:67]
	v_mfma_f32_16x16x32_bf16 v[92:95], v[146:149], v[192:195], v[92:95]
	v_mfma_f32_16x16x32_bf16 v[88:91], v[154:157], v[192:195], v[88:91]
	v_mfma_f32_16x16x32_bf16 v[84:87], v[146:149], v[200:203], v[84:87]
	v_mfma_f32_16x16x32_bf16 v[80:83], v[154:157], v[200:203], v[80:83]
	v_mfma_f32_16x16x32_bf16 v[76:79], v[146:149], v[208:211], v[76:79]
	v_mfma_f32_16x16x32_bf16 v[72:75], v[154:157], v[208:211], v[72:75]
	v_mfma_f32_16x16x32_bf16 v[68:71], v[146:149], v[230:233], v[68:71]
	v_mfma_f32_16x16x32_bf16 v[64:67], v[154:157], v[230:233], v[64:67]
	s_setprio 0
	s_setprio 1
	v_mfma_f32_16x16x32_bf16 v[28:31], v[158:161], v[188:191], v[28:31]
	v_mfma_f32_16x16x32_bf16 v[24:27], v[166:169], v[188:191], v[24:27]
	v_mfma_f32_16x16x32_bf16 v[20:23], v[158:161], v[196:199], v[20:23]
	v_mfma_f32_16x16x32_bf16 v[16:19], v[166:169], v[196:199], v[16:19]
	v_mfma_f32_16x16x32_bf16 v[12:15], v[158:161], v[204:207], v[12:15]
	v_mfma_f32_16x16x32_bf16 v[8:11], v[166:169], v[204:207], v[8:11]
	v_mfma_f32_16x16x32_bf16 v[4:7], v[158:161], v[226:229], v[4:7]
	v_mfma_f32_16x16x32_bf16 v[0:3], v[166:169], v[226:229], v[0:3]
	v_mfma_f32_16x16x32_bf16 v[28:31], v[162:165], v[192:195], v[28:31]
	v_mfma_f32_16x16x32_bf16 v[24:27], v[174:177], v[192:195], v[24:27]
	v_mfma_f32_16x16x32_bf16 v[20:23], v[162:165], v[200:203], v[20:23]
	v_mfma_f32_16x16x32_bf16 v[16:19], v[174:177], v[200:203], v[16:19]
	v_mfma_f32_16x16x32_bf16 v[12:15], v[162:165], v[208:211], v[12:15]
	v_mfma_f32_16x16x32_bf16 v[8:11], v[174:177], v[208:211], v[8:11]
	v_mfma_f32_16x16x32_bf16 v[4:7], v[162:165], v[230:233], v[4:7]
	v_mfma_f32_16x16x32_bf16 v[0:3], v[174:177], v[230:233], v[0:3]
	s_setprio 0
	s_barrier
	s_add_u32 s26, s26, 0x100
	s_addc_u32 s27, s27, 0
	s_add_u32 s28, s28, 0x100
	s_addc_u32 s29, s29, 0
	s_cmp_ge_u32 s30, s51
	s_mov_b32 s10, s30
	s_cbranch_scc0 .LBB0_58
	s_and_b64 vcc, exec, s[12:13]
	s_cbranch_vccz .LBB0_61

; #define PG8_STAGE(bufoff, gbase, voff) do { _Pragma("unroll") for (int _i = 0; _i < 2; ++_i) \
;         __builtin_amdgcn_global_load_lds((const unsigned*)((const char*)(gbase) + (voff)[_i]), (LAS unsigned*)(lds + (bufoff) + ldsw + _i * 8192), 16, 0, 0); } while (0)
; #define PG8_LDA(dst, b, h) do { _Pragma("unroll") for (int m = 0; m < 4; ++m) _Pragma("unroll") for (int k = 0; k < 2; ++k) dst[m][k] = *(const LAS bf16x8*)(lds + PG8_SA(b, h) + aoff + m * 2048 + k * 1024); } while (0)
; #define PG8_LDB(dst, b, h) do { _Pragma("unroll") for (int n = 0; n < 2; ++n) _Pragma("unroll") for (int k = 0; k < 2; ++k) dst[n][k] = *(const LAS bf16x8*)(lds + PG8_SB(b, h) + boff + n * 2048 + k * 1024); } while (0)
; #define PG8_MMA(ai, bj, At, Bt) do { __builtin_amdgcn_s_setprio(1); _Pragma("unroll") for (int m = 0; m < 4; ++m) _Pragma("unroll") for (int n = 0; n < 2; ++n) _Pragma("unroll") for (int k = 0; k < 2; ++k) \
;         acc[ai][bj][m][n] = __builtin_amdgcn_mfma_f32_16x16x32_bf16(Bt[n][k], At[m][k], acc[ai][bj][m][n], 0, 0, 0); __builtin_amdgcn_s_setprio(0); } while (0)
; #define PG8_WAIT_V(n) asm volatile("s_waitcnt vmcnt(" #n ")" ::: "memory")
; #define PG8_WAIT_L(n) asm volatile("s_waitcnt lgkmcnt(" #n ")" ::: "memory")
; #define PG8_BAR __builtin_amdgcn_s_barrier()
; #define PG8_SCHED __builtin_amdgcn_sched_barrier(0)
;     ...
;             PG8_LDB(B0, 0, 0); PG8_LDB(B1, 0, 1); PG8_SCHED; PG8_LDA(At, 0, 0); PG8_STAGE(PG8_SA(1, 1), a1 + hstep, voffA);
;             PG8_WAIT_V(8); PG8_WAIT_L(0); PG8_BAR; PG8_MMA(0, 0, At, B0); PG8_MMA(0, 1, At, B1); PG8_BAR; PG8_SCHED;
;             PG8_LDA(At, 0, 1); PG8_STAGE(PG8_SB(0, 0), b2, voffB); PG8_STAGE(PG8_SB(0, 1), b2 + hstep, voffB); PG8_STAGE(PG8_SA(0, 0), a2, voffA);
;             PG8_WAIT_V(8); PG8_WAIT_L(0); PG8_BAR; PG8_MMA(1, 0, At, B0); PG8_MMA(1, 1, At, B1); PG8_BAR; PG8_SCHED;
.LBB0_79:
	s_add_i32 s55, s10, 2
	s_add_u32 s11, s26, 0xfff00080
	s_addc_u32 s28, s27, -1
	s_add_i32 s56, 0, 0x10000
	s_cmp_eq_u32 s41, s10
	s_cselect_b32 s29, s21, s28
	s_cselect_b32 s28, s20, s11
	s_cselect_b32 s11, s23, s54
	s_cselect_b32 s10, s22, s15
	s_add_i32 s58, 0, 0x14000
	v_add_u32_e32 v160, s56, v143
	v_add_u32_e32 v176, s58, v143
	ds_read_b128 v[148:151], v160
	ds_read_b128 v[152:155], v160 offset:1024
	ds_read_b128 v[156:159], v160 offset:2048
	ds_read_b128 v[160:163], v160 offset:3072
	ds_read_b128 v[164:167], v176
	ds_read_b128 v[168:171], v176 offset:1024
	ds_read_b128 v[172:175], v176 offset:2048
	ds_read_b128 v[188:191], v176 offset:3072
	v_lshl_add_u64 v[176:177], s[26:27], 0, v[138:139]
	s_add_i32 m0, s25, 0xc000
	ds_read_b128 v[192:195], v147
	ds_read_b128 v[196:199], v147 offset:1024
	ds_read_b128 v[200:203], v147 offset:2048
	ds_read_b128 v[204:207], v147 offset:3072
	ds_read_b128 v[208:211], v147 offset:4096
	ds_read_b128 v[226:229], v147 offset:5120
	ds_read_b128 v[230:233], v147 offset:6144
	ds_read_b128 v[234:237], v147 offset:7168
	global_load_lds_dwordx4 v[176:177], off
	v_lshl_add_u64 v[176:177], s[26:27], 0, v[140:141]
	s_add_i32 m0, s25, 0xe000
	s_nop 0
	global_load_lds_dwordx4 v[176:177], off
	s_waitcnt vmcnt(8)
	s_waitcnt lgkmcnt(0)
	s_barrier
	s_setprio 1
	v_mfma_f32_16x16x32_bf16 v[126:129], v[148:151], v[192:195], v[126:129]
	v_mfma_f32_16x16x32_bf16 v[122:125], v[156:159], v[192:195], v[122:125]
	v_mfma_f32_16x16x32_bf16 v[110:113], v[148:151], v[200:203], v[110:113]
	v_mfma_f32_16x16x32_bf16 v[106:109], v[156:159], v[200:203], v[106:109]
	v_mfma_f32_16x16x32_bf16 v[92:95], v[148:151], v[208:211], v[92:95]
	v_mfma_f32_16x16x32_bf16 v[88:91], v[156:159], v[208:211], v[88:91]
	v_mfma_f32_16x16x32_bf16 v[76:79], v[148:151], v[230:233], v[76:79]
	v_mfma_f32_16x16x32_bf16 v[72:75], v[156:159], v[230:233], v[72:75]
	v_mfma_f32_16x16x32_bf16 v[126:129], v[152:155], v[196:199], v[126:129]
	v_mfma_f32_16x16x32_bf16 v[122:125], v[160:163], v[196:199], v[122:125]
	v_mfma_f32_16x16x32_bf16 v[110:113], v[152:155], v[204:207], v[110:113]
	v_mfma_f32_16x16x32_bf16 v[106:109], v[160:163], v[204:207], v[106:109]
	v_mfma_f32_16x16x32_bf16 v[92:95], v[152:155], v[226:229], v[92:95]
	v_mfma_f32_16x16x32_bf16 v[88:91], v[160:163], v[226:229], v[88:91]
	v_mfma_f32_16x16x32_bf16 v[76:79], v[152:155], v[234:237], v[76:79]
	v_mfma_f32_16x16x32_bf16 v[72:75], v[160:163], v[234:237], v[72:75]
	s_setprio 0
	s_setprio 1
	v_mfma_f32_16x16x32_bf16 v[118:121], v[164:167], v[192:195], v[118:121]
	v_mfma_f32_16x16x32_bf16 v[114:117], v[172:175], v[192:195], v[114:117]
	v_mfma_f32_16x16x32_bf16 v[102:105], v[164:167], v[200:203], v[102:105]
	v_mfma_f32_16x16x32_bf16 v[98:101], v[172:175], v[200:203], v[98:101]
	v_mfma_f32_16x16x32_bf16 v[84:87], v[164:167], v[208:211], v[84:87]
	v_mfma_f32_16x16x32_bf16 v[80:83], v[172:175], v[208:211], v[80:83]
	v_mfma_f32_16x16x32_bf16 v[68:71], v[164:167], v[230:233], v[68:71]
	v_mfma_f32_16x16x32_bf16 v[64:67], v[172:175], v[230:233], v[64:67]
	v_mfma_f32_16x16x32_bf16 v[118:121], v[168:171], v[196:199], v[118:121]
	v_mfma_f32_16x16x32_bf16 v[114:117], v[188:191], v[196:199], v[114:117]
	v_mfma_f32_16x16x32_bf16 v[102:105], v[168:171], v[204:207], v[102:105]
	v_mfma_f32_16x16x32_bf16 v[98:101], v[188:191], v[204:207], v[98:101]
	v_mfma_f32_16x16x32_bf16 v[84:87], v[168:171], v[226:229], v[84:87]
	v_mfma_f32_16x16x32_bf16 v[80:83], v[188:191], v[226:229], v[80:83]
	v_mfma_f32_16x16x32_bf16 v[68:71], v[168:171], v[234:237], v[68:71]
	v_mfma_f32_16x16x32_bf16 v[64:67], v[188:191], v[234:237], v[64:67]
	s_setprio 0
	s_barrier
	s_add_i32 s56, s56, s19
	v_lshl_add_u64 v[176:177], s[10:11], 0, v[134:135]
	s_mov_b32 m0, s56
	ds_read_b128 v[192:195], v147 offset:16384
	ds_read_b128 v[196:199], v147 offset:17408
	ds_read_b128 v[200:203], v147 offset:18432
	ds_read_b128 v[204:207], v147 offset:19456
	ds_read_b128 v[208:211], v147 offset:20480
	ds_read_b128 v[226:229], v147 offset:21504
	ds_read_b128 v[230:233], v147 offset:22528
	ds_read_b128 v[234:237], v147 offset:23552
	global_load_lds_dwordx4 v[176:177], off
	s_add_i32 m0, s56, 0x2000
	s_add_u32 s56, s10, 0x100000
	v_lshl_add_u64 v[214:215], s[10:11], 0, v[130:131]
	s_addc_u32 s57, s11, 0
	s_add_i32 s58, s58, s19
	global_load_lds_dwordx4 v[214:215], off
	v_lshl_add_u64 v[238:239], s[56:57], 0, v[134:135]
	s_mov_b32 m0, s58
	v_lshl_add_u64 v[240:241], s[28:29], 0, v[132:133]
	global_load_lds_dwordx4 v[238:239], off
	v_lshl_add_u64 v[238:239], s[56:57], 0, v[130:131]
	s_add_i32 m0, s58, 0x2000
	s_nop 0
	global_load_lds_dwordx4 v[238:239], off
	v_lshl_add_u64 v[238:239], s[28:29], 0, v[136:137]
	s_mov_b32 m0, s25
	s_nop 0
	global_load_lds_dwordx4 v[238:239], off
	s_mov_b32 m0, s30
	s_nop 0
	global_load_lds_dwordx4 v[240:241], off
	s_waitcnt vmcnt(8)
	s_waitcnt lgkmcnt(0)
	s_barrier
; #define PG8_STAGE(bufoff, gbase, voff) do { _Pragma("unroll") for (int _i = 0; _i < 2; ++_i) \
;         __builtin_amdgcn_global_load_lds((const unsigned*)((const char*)(gbase) + (voff)[_i]), (LAS unsigned*)(lds + (bufoff) + ldsw + _i * 8192), 16, 0, 0); } while (0)
; #define PG8_LDA(dst, b, h) do { _Pragma("unroll") for (int m = 0; m < 4; ++m) _Pragma("unroll") for (int k = 0; k < 2; ++k) dst[m][k] = *(const LAS bf16x8*)(lds + PG8_SA(b, h) + aoff + m * 2048 + k * 1024); } while (0)
; #define PG8_LDB(dst, b, h) do { _Pragma("unroll") for (int n = 0; n < 2; ++n) _Pragma("unroll") for (int k = 0; k < 2; ++k) dst[n][k] = *(const LAS bf16x8*)(lds + PG8_SB(b, h) + boff + n * 2048 + k * 1024); } while (0)
; #define PG8_MMA(ai, bj, At, Bt) do { __builtin_amdgcn_s_setprio(1); _Pragma("unroll") for (int m = 0; m < 4; ++m) _Pragma("unroll") for (int n = 0; n < 2; ++n) _Pragma("unroll") for (int k = 0; k < 2; ++k) \
;         acc[ai][bj][m][n] = __builtin_amdgcn_mfma_f32_16x16x32_bf16(Bt[n][k], At[m][k], acc[ai][bj][m][n], 0, 0, 0); __builtin_amdgcn_s_setprio(0); } while (0)
; #define PG8_WAIT_V(n) asm volatile("s_waitcnt vmcnt(" #n ")" ::: "memory")
; #define PG8_WAIT_L(n) asm volatile("s_waitcnt lgkmcnt(" #n ")" ::: "memory")
; #define PG8_BAR __builtin_amdgcn_s_barrier()
; #define PG8_SCHED __builtin_amdgcn_sched_barrier(0)
;     ...
;             PG8_WAIT_V(8); PG8_WAIT_L(0); PG8_BAR; PG8_MMA(1, 0, At, B0); PG8_MMA(1, 1, At, B1); PG8_BAR; PG8_SCHED;
;             PG8_LDB(B0, 1, 0); PG8_LDB(B1, 1, 1); PG8_SCHED; PG8_LDA(At, 1, 0); PG8_STAGE(PG8_SA(0, 1), a2 + hstep, voffA);
;             PG8_WAIT_V(8); PG8_WAIT_L(0); PG8_BAR; PG8_MMA(0, 0, At, B0); PG8_MMA(0, 1, At, B1); PG8_BAR; PG8_SCHED;
	s_setprio 1
	v_mfma_f32_16x16x32_bf16 v[60:63], v[148:151], v[192:195], v[60:63]
	v_mfma_f32_16x16x32_bf16 v[56:59], v[156:159], v[192:195], v[56:59]
	v_mfma_f32_16x16x32_bf16 v[44:47], v[148:151], v[200:203], v[44:47]
	v_mfma_f32_16x16x32_bf16 v[40:43], v[156:159], v[200:203], v[40:43]
	v_mfma_f32_16x16x32_bf16 v[28:31], v[148:151], v[208:211], v[28:31]
	v_mfma_f32_16x16x32_bf16 v[24:27], v[156:159], v[208:211], v[24:27]
	v_mfma_f32_16x16x32_bf16 v[12:15], v[148:151], v[230:233], v[12:15]
	v_mfma_f32_16x16x32_bf16 v[8:11], v[156:159], v[230:233], v[8:11]
	v_mfma_f32_16x16x32_bf16 v[60:63], v[152:155], v[196:199], v[60:63]
	v_mfma_f32_16x16x32_bf16 v[56:59], v[160:163], v[196:199], v[56:59]
	v_mfma_f32_16x16x32_bf16 v[44:47], v[152:155], v[204:207], v[44:47]
	v_mfma_f32_16x16x32_bf16 v[40:43], v[160:163], v[204:207], v[40:43]
	v_mfma_f32_16x16x32_bf16 v[28:31], v[152:155], v[226:229], v[28:31]
	v_mfma_f32_16x16x32_bf16 v[24:27], v[160:163], v[226:229], v[24:27]
	v_mfma_f32_16x16x32_bf16 v[12:15], v[152:155], v[234:237], v[12:15]
	v_mfma_f32_16x16x32_bf16 v[8:11], v[160:163], v[234:237], v[8:11]
	s_setprio 0
	s_setprio 1
	v_mfma_f32_16x16x32_bf16 v[52:55], v[164:167], v[192:195], v[52:55]
	v_mfma_f32_16x16x32_bf16 v[48:51], v[172:175], v[192:195], v[48:51]
	v_mfma_f32_16x16x32_bf16 v[36:39], v[164:167], v[200:203], v[36:39]
	v_mfma_f32_16x16x32_bf16 v[32:35], v[172:175], v[200:203], v[32:35]
	v_mfma_f32_16x16x32_bf16 v[20:23], v[164:167], v[208:211], v[20:23]
	v_mfma_f32_16x16x32_bf16 v[16:19], v[172:175], v[208:211], v[16:19]
	v_mfma_f32_16x16x32_bf16 v[4:7], v[164:167], v[230:233], v[4:7]
	v_mfma_f32_16x16x32_bf16 v[0:3], v[172:175], v[230:233], v[0:3]
	v_mfma_f32_16x16x32_bf16 v[52:55], v[168:171], v[196:199], v[52:55]
	v_mfma_f32_16x16x32_bf16 v[48:51], v[188:191], v[196:199], v[48:51]
	v_mfma_f32_16x16x32_bf16 v[36:39], v[168:171], v[204:207], v[36:39]
	v_mfma_f32_16x16x32_bf16 v[32:35], v[188:191], v[204:207], v[32:35]
	v_mfma_f32_16x16x32_bf16 v[20:23], v[168:171], v[226:229], v[20:23]
	v_mfma_f32_16x16x32_bf16 v[16:19], v[188:191], v[226:229], v[16:19]
	v_mfma_f32_16x16x32_bf16 v[4:7], v[168:171], v[234:237], v[4:7]
	v_mfma_f32_16x16x32_bf16 v[0:3], v[188:191], v[234:237], v[0:3]
	s_setprio 0
	s_barrier
	s_add_i32 s56, 0, 0x18000
	s_add_i32 s57, 0, 0x1c000
	v_add_u32_e32 v160, s56, v143
	v_add_u32_e32 v188, s57, v143
	ds_read_b128 v[148:151], v160
	ds_read_b128 v[152:155], v160 offset:1024
	ds_read_b128 v[156:159], v160 offset:2048
	ds_read_b128 v[160:163], v160 offset:3072
	ds_read_b128 v[164:167], v188
	ds_read_b128 v[168:171], v188 offset:1024
	ds_read_b128 v[172:175], v188 offset:2048
	ds_read_b128 v[188:191], v188 offset:3072
	s_add_u32 s28, s28, 0x100000
	s_addc_u32 s29, s29, 0
	s_mov_b32 m0, s31
	v_lshl_add_u64 v[242:243], s[28:29], 0, v[136:137]
	ds_read_b128 v[192:195], v147 offset:32768
	ds_read_b128 v[196:199], v147 offset:33792
	ds_read_b128 v[200:203], v147 offset:34816
	ds_read_b128 v[204:207], v147 offset:35840
	ds_read_b128 v[208:211], v147 offset:36864
	ds_read_b128 v[226:229], v147 offset:37888
	ds_read_b128 v[230:233], v147 offset:38912
	ds_read_b128 v[234:237], v147 offset:39936
	global_load_lds_dwordx4 v[242:243], off
	v_lshl_add_u64 v[242:243], s[28:29], 0, v[132:133]
	s_mov_b32 m0, s36
	s_nop 0
	global_load_lds_dwordx4 v[242:243], off
	s_waitcnt vmcnt(8)
	s_waitcnt lgkmcnt(0)
	s_barrier
	s_setprio 1
	v_mfma_f32_16x16x32_bf16 v[126:129], v[148:151], v[192:195], v[126:129]
	v_mfma_f32_16x16x32_bf16 v[122:125], v[156:159], v[192:195], v[122:125]
	v_mfma_f32_16x16x32_bf16 v[110:113], v[148:151], v[200:203], v[110:113]
	v_mfma_f32_16x16x32_bf16 v[106:109], v[156:159], v[200:203], v[106:109]
	v_mfma_f32_16x16x32_bf16 v[92:95], v[148:151], v[208:211], v[92:95]
	v_mfma_f32_16x16x32_bf16 v[88:91], v[156:159], v[208:211], v[88:91]
	v_mfma_f32_16x16x32_bf16 v[76:79], v[148:151], v[230:233], v[76:79]
	v_mfma_f32_16x16x32_bf16 v[72:75], v[156:159], v[230:233], v[72:75]
	v_mfma_f32_16x16x32_bf16 v[126:129], v[152:155], v[196:199], v[126:129]
	v_mfma_f32_16x16x32_bf16 v[122:125], v[160:163], v[196:199], v[122:125]
	v_mfma_f32_16x16x32_bf16 v[110:113], v[152:155], v[204:207], v[110:113]
	v_mfma_f32_16x16x32_bf16 v[106:109], v[160:163], v[204:207], v[106:109]
	v_mfma_f32_16x16x32_bf16 v[92:95], v[152:155], v[226:229], v[92:95]
	v_mfma_f32_16x16x32_bf16 v[88:91], v[160:163], v[226:229], v[88:91]
	v_mfma_f32_16x16x32_bf16 v[76:79], v[152:155], v[234:237], v[76:79]
	v_mfma_f32_16x16x32_bf16 v[72:75], v[160:163], v[234:237], v[72:75]
	s_setprio 0
	s_setprio 1
	v_mfma_f32_16x16x32_bf16 v[118:121], v[164:167], v[192:195], v[118:121]
	v_mfma_f32_16x16x32_bf16 v[114:117], v[172:175], v[192:195], v[114:117]
	v_mfma_f32_16x16x32_bf16 v[102:105], v[164:167], v[200:203], v[102:105]
	v_mfma_f32_16x16x32_bf16 v[98:101], v[172:175], v[200:203], v[98:101]
	v_mfma_f32_16x16x32_bf16 v[84:87], v[164:167], v[208:211], v[84:87]
	v_mfma_f32_16x16x32_bf16 v[80:83], v[172:175], v[208:211], v[80:83]
	v_mfma_f32_16x16x32_bf16 v[68:71], v[164:167], v[230:233], v[68:71]
	v_mfma_f32_16x16x32_bf16 v[64:67], v[172:175], v[230:233], v[64:67]
	v_mfma_f32_16x16x32_bf16 v[118:121], v[168:171], v[196:199], v[118:121]
	v_mfma_f32_16x16x32_bf16 v[114:117], v[188:191], v[196:199], v[114:117]
	v_mfma_f32_16x16x32_bf16 v[102:105], v[168:171], v[204:207], v[102:105]
	v_mfma_f32_16x16x32_bf16 v[98:101], v[188:191], v[204:207], v[98:101]
	v_mfma_f32_16x16x32_bf16 v[84:87], v[168:171], v[226:229], v[84:87]
	v_mfma_f32_16x16x32_bf16 v[80:83], v[188:191], v[226:229], v[80:83]
	v_mfma_f32_16x16x32_bf16 v[68:71], v[168:171], v[234:237], v[68:71]
	v_mfma_f32_16x16x32_bf16 v[64:67], v[188:191], v[234:237], v[64:67]
	s_setprio 0
	s_barrier
; #define PG8_STAGE(bufoff, gbase, voff) do { _Pragma("unroll") for (int _i = 0; _i < 2; ++_i) \
;         __builtin_amdgcn_global_load_lds((const unsigned*)((const char*)(gbase) + (voff)[_i]), (LAS unsigned*)(lds + (bufoff) + ldsw + _i * 8192), 16, 0, 0); } while (0)
; #define PG8_LDA(dst, b, h) do { _Pragma("unroll") for (int m = 0; m < 4; ++m) _Pragma("unroll") for (int k = 0; k < 2; ++k) dst[m][k] = *(const LAS bf16x8*)(lds + PG8_SA(b, h) + aoff + m * 2048 + k * 1024); } while (0)
; #define PG8_MMA(ai, bj, At, Bt) do { __builtin_amdgcn_s_setprio(1); _Pragma("unroll") for (int m = 0; m < 4; ++m) _Pragma("unroll") for (int n = 0; n < 2; ++n) _Pragma("unroll") for (int k = 0; k < 2; ++k) \
;         acc[ai][bj][m][n] = __builtin_amdgcn_mfma_f32_16x16x32_bf16(Bt[n][k], At[m][k], acc[ai][bj][m][n], 0, 0, 0); __builtin_amdgcn_s_setprio(0); } while (0)
; #define PG8_WAIT_V(n) asm volatile("s_waitcnt vmcnt(" #n ")" ::: "memory")
; #define PG8_WAIT_L(n) asm volatile("s_waitcnt lgkmcnt(" #n ")" ::: "memory")
; #define PG8_BAR __builtin_amdgcn_s_barrier()
; #define PG8_SCHED __builtin_amdgcn_sched_barrier(0)
;     ...
;         for (int t = 0; t < nt; t += 2) {
;     ...
;             PG8_LDA(At, 1, 1); PG8_STAGE(PG8_SB(1, 0), b3, voffB); PG8_STAGE(PG8_SB(1, 1), b3 + hstep, voffB); PG8_STAGE(PG8_SA(1, 0), a3, voffA);
;             PG8_WAIT_V(8); PG8_WAIT_L(0); PG8_BAR; PG8_MMA(1, 0, At, B0); PG8_MMA(1, 1, At, B1); PG8_BAR; PG8_SCHED;
;         }
	s_add_i32 s28, s56, s19
	v_lshl_add_u64 v[176:177], v[176:177], 0, s[46:47]
	s_mov_b32 m0, s28
	ds_read_b128 v[192:195], v147 offset:49152
	ds_read_b128 v[196:199], v147 offset:50176
	ds_read_b128 v[200:203], v147 offset:51200
	ds_read_b128 v[204:207], v147 offset:52224
	ds_read_b128 v[208:211], v147 offset:53248
	ds_read_b128 v[226:229], v147 offset:54272
	ds_read_b128 v[230:233], v147 offset:55296
	ds_read_b128 v[234:237], v147 offset:56320
	global_load_lds_dwordx4 v[176:177], off
	s_add_i32 m0, s28, 0x2000
	s_add_u32 s10, s10, 0x100080
	v_lshl_add_u64 v[176:177], v[214:215], 0, s[46:47]
	s_addc_u32 s11, s11, 0
	s_add_i32 s28, s57, s19
	global_load_lds_dwordx4 v[176:177], off
	v_lshl_add_u64 v[176:177], s[10:11], 0, v[134:135]
	s_mov_b32 m0, s28
	s_nop 0
	global_load_lds_dwordx4 v[176:177], off
	v_lshl_add_u64 v[176:177], s[10:11], 0, v[130:131]
	s_add_i32 m0, s28, 0x2000
	s_nop 0
	global_load_lds_dwordx4 v[176:177], off
	v_lshl_add_u64 v[176:177], v[238:239], 0, s[46:47]
	s_mov_b32 m0, s38
	s_nop 0
	global_load_lds_dwordx4 v[176:177], off
	v_lshl_add_u64 v[176:177], v[240:241], 0, s[46:47]
	s_mov_b32 m0, s39
	s_nop 0
	global_load_lds_dwordx4 v[176:177], off
	s_waitcnt vmcnt(8)
	s_waitcnt lgkmcnt(0)
	s_barrier
	s_setprio 1
	v_mfma_f32_16x16x32_bf16 v[60:63], v[148:151], v[192:195], v[60:63]
	v_mfma_f32_16x16x32_bf16 v[56:59], v[156:159], v[192:195], v[56:59]
	v_mfma_f32_16x16x32_bf16 v[44:47], v[148:151], v[200:203], v[44:47]
	v_mfma_f32_16x16x32_bf16 v[40:43], v[156:159], v[200:203], v[40:43]
	v_mfma_f32_16x16x32_bf16 v[28:31], v[148:151], v[208:211], v[28:31]
	v_mfma_f32_16x16x32_bf16 v[24:27], v[156:159], v[208:211], v[24:27]
	v_mfma_f32_16x16x32_bf16 v[12:15], v[148:151], v[230:233], v[12:15]
	v_mfma_f32_16x16x32_bf16 v[8:11], v[156:159], v[230:233], v[8:11]
	v_mfma_f32_16x16x32_bf16 v[60:63], v[152:155], v[196:199], v[60:63]
	v_mfma_f32_16x16x32_bf16 v[56:59], v[160:163], v[196:199], v[56:59]
	v_mfma_f32_16x16x32_bf16 v[44:47], v[152:155], v[204:207], v[44:47]
	v_mfma_f32_16x16x32_bf16 v[40:43], v[160:163], v[204:207], v[40:43]
	v_mfma_f32_16x16x32_bf16 v[28:31], v[152:155], v[226:229], v[28:31]
	v_mfma_f32_16x16x32_bf16 v[24:27], v[160:163], v[226:229], v[24:27]
	v_mfma_f32_16x16x32_bf16 v[12:15], v[152:155], v[234:237], v[12:15]
	v_mfma_f32_16x16x32_bf16 v[8:11], v[160:163], v[234:237], v[8:11]
	s_setprio 0
	s_setprio 1
	v_mfma_f32_16x16x32_bf16 v[52:55], v[164:167], v[192:195], v[52:55]
	v_mfma_f32_16x16x32_bf16 v[48:51], v[172:175], v[192:195], v[48:51]
	v_mfma_f32_16x16x32_bf16 v[36:39], v[164:167], v[200:203], v[36:39]
	v_mfma_f32_16x16x32_bf16 v[32:35], v[172:175], v[200:203], v[32:35]
	v_mfma_f32_16x16x32_bf16 v[20:23], v[164:167], v[208:211], v[20:23]
	v_mfma_f32_16x16x32_bf16 v[16:19], v[172:175], v[208:211], v[16:19]
	v_mfma_f32_16x16x32_bf16 v[4:7], v[164:167], v[230:233], v[4:7]
	v_mfma_f32_16x16x32_bf16 v[0:3], v[172:175], v[230:233], v[0:3]
	v_mfma_f32_16x16x32_bf16 v[52:55], v[168:171], v[196:199], v[52:55]
	v_mfma_f32_16x16x32_bf16 v[48:51], v[188:191], v[196:199], v[48:51]
	v_mfma_f32_16x16x32_bf16 v[36:39], v[168:171], v[204:207], v[36:39]
	v_mfma_f32_16x16x32_bf16 v[32:35], v[188:191], v[204:207], v[32:35]
	v_mfma_f32_16x16x32_bf16 v[20:23], v[168:171], v[226:229], v[20:23]
	v_mfma_f32_16x16x32_bf16 v[16:19], v[188:191], v[226:229], v[16:19]
	v_mfma_f32_16x16x32_bf16 v[4:7], v[168:171], v[234:237], v[4:7]
	v_mfma_f32_16x16x32_bf16 v[0:3], v[188:191], v[234:237], v[0:3]
	s_setprio 0
	s_barrier
	s_add_u32 s26, s26, 0x100
	s_addc_u32 s27, s27, 0
	s_add_u32 s15, s15, 0x100
	s_addc_u32 s54, s54, 0
	s_cmp_ge_u32 s55, s37
	s_mov_b32 s10, s55
	s_cbranch_scc0 .LBB0_79
	s_movk_i32 s54, 0x2000
	s_and_b64 vcc, exec, s[12:13]
	s_cbranch_vccz .LBB0_82

; #define PG8_STAGE(bufoff, gbase, voff) do { _Pragma("unroll") for (int _i = 0; _i < 2; ++_i) \
;         __builtin_amdgcn_global_load_lds((const unsigned*)((const char*)(gbase) + (voff)[_i]), (LAS unsigned*)(lds + (bufoff) + ldsw + _i * 8192), 16, 0, 0); } while (0)
; #define PG8_LDA(dst, b, h) do { _Pragma("unroll") for (int m = 0; m < 4; ++m) _Pragma("unroll") for (int k = 0; k < 2; ++k) dst[m][k] = *(const LAS bf16x8*)(lds + PG8_SA(b, h) + aoff + m * 2048 + k * 1024); } while (0)
; #define PG8_LDB(dst, b, h) do { _Pragma("unroll") for (int n = 0; n < 2; ++n) _Pragma("unroll") for (int k = 0; k < 2; ++k) dst[n][k] = *(const LAS bf16x8*)(lds + PG8_SB(b, h) + boff + n * 2048 + k * 1024); } while (0)
; #define PG8_MMA(ai, bj, At, Bt) do { __builtin_amdgcn_s_setprio(1); _Pragma("unroll") for (int m = 0; m < 4; ++m) _Pragma("unroll") for (int n = 0; n < 2; ++n) _Pragma("unroll") for (int k = 0; k < 2; ++k) \
;         acc[ai][bj][m][n] = __builtin_amdgcn_mfma_f32_16x16x32_bf16(Bt[n][k], At[m][k], acc[ai][bj][m][n], 0, 0, 0); __builtin_amdgcn_s_setprio(0); } while (0)
; #define PG8_WAIT_V(n) asm volatile("s_waitcnt vmcnt(" #n ")" ::: "memory")
; #define PG8_WAIT_L(n) asm volatile("s_waitcnt lgkmcnt(" #n ")" ::: "memory")
; #define PG8_BAR __builtin_amdgcn_s_barrier()
; #define PG8_SCHED __builtin_amdgcn_sched_barrier(0)
;     ...
;             PG8_LDB(B0, 0, 0); PG8_LDB(B1, 0, 1); PG8_SCHED; PG8_LDA(At, 0, 0); PG8_STAGE(PG8_SA(1, 1), a1 + hstep, voffA);
;             PG8_WAIT_V(8); PG8_WAIT_L(0); PG8_BAR; PG8_MMA(0, 0, At, B0); PG8_MMA(0, 1, At, B1); PG8_BAR; PG8_SCHED;
;             PG8_LDA(At, 0, 1); PG8_STAGE(PG8_SB(0, 0), b2, voffB); PG8_STAGE(PG8_SB(0, 1), b2 + hstep, voffB); PG8_STAGE(PG8_SA(0, 0), a2, voffA);
;             PG8_WAIT_V(8); PG8_WAIT_L(0); PG8_BAR; PG8_MMA(1, 0, At, B0); PG8_MMA(1, 1, At, B1); PG8_BAR; PG8_SCHED;
.LBB0_98:
	s_add_i32 s21, s10, 2
	s_add_u32 s23, s28, 0x80
	s_addc_u32 s11, s29, 0
	s_add_i32 s61, 0, 0x10000
	s_cmp_eq_u32 s55, s10
	s_cselect_b32 s11, s25, s11
	s_cselect_b32 s10, s24, s23
	v_add_u32_e32 v142, s61, v145
	s_cselect_b32 s31, s27, s9
	s_cselect_b32 s30, s26, s8
	s_add_i32 s23, 0, 0x14000
	ds_read_b128 v[148:151], v142
	ds_read_b128 v[152:155], v142 offset:1024
	ds_read_b128 v[156:159], v142 offset:2048
	ds_read_b128 v[160:163], v142 offset:3072
	v_add_u32_e32 v142, s23, v145
	ds_read_b128 v[164:167], v142
	ds_read_b128 v[168:171], v142 offset:1024
	ds_read_b128 v[172:175], v142 offset:2048
	ds_read_b128 v[188:191], v142 offset:3072
	v_lshl_add_u64 v[142:143], s[28:29], 0, v[138:139]
	s_add_i32 m0, s39, 0xc000
	ds_read_b128 v[192:195], v146
	ds_read_b128 v[196:199], v146 offset:1024
	ds_read_b128 v[200:203], v146 offset:2048
	ds_read_b128 v[204:207], v146 offset:3072
	ds_read_b128 v[208:211], v146 offset:4096
	ds_read_b128 v[226:229], v146 offset:5120
	ds_read_b128 v[230:233], v146 offset:6144
	ds_read_b128 v[234:237], v146 offset:7168
	global_load_lds_dwordx4 v[142:143], off
	v_lshl_add_u64 v[142:143], s[28:29], 0, v[140:141]
	s_add_i32 m0, s39, 0xe000
	s_nop 0
	global_load_lds_dwordx4 v[142:143], off
	s_waitcnt vmcnt(8)
	s_waitcnt lgkmcnt(0)
	s_barrier
	s_setprio 1
	v_mfma_f32_16x16x32_bf16 v[126:129], v[148:151], v[192:195], v[126:129]
	v_mfma_f32_16x16x32_bf16 v[122:125], v[156:159], v[192:195], v[122:125]
	v_mfma_f32_16x16x32_bf16 v[110:113], v[148:151], v[200:203], v[110:113]
	v_mfma_f32_16x16x32_bf16 v[106:109], v[156:159], v[200:203], v[106:109]
	v_mfma_f32_16x16x32_bf16 v[92:95], v[148:151], v[208:211], v[92:95]
	v_mfma_f32_16x16x32_bf16 v[88:91], v[156:159], v[208:211], v[88:91]
	v_mfma_f32_16x16x32_bf16 v[76:79], v[148:151], v[230:233], v[76:79]
	v_mfma_f32_16x16x32_bf16 v[72:75], v[156:159], v[230:233], v[72:75]
	v_mfma_f32_16x16x32_bf16 v[126:129], v[152:155], v[196:199], v[126:129]
	v_mfma_f32_16x16x32_bf16 v[122:125], v[160:163], v[196:199], v[122:125]
	v_mfma_f32_16x16x32_bf16 v[110:113], v[152:155], v[204:207], v[110:113]
	v_mfma_f32_16x16x32_bf16 v[106:109], v[160:163], v[204:207], v[106:109]
	v_mfma_f32_16x16x32_bf16 v[92:95], v[152:155], v[226:229], v[92:95]
	v_mfma_f32_16x16x32_bf16 v[88:91], v[160:163], v[226:229], v[88:91]
	v_mfma_f32_16x16x32_bf16 v[76:79], v[152:155], v[234:237], v[76:79]
	v_mfma_f32_16x16x32_bf16 v[72:75], v[160:163], v[234:237], v[72:75]
	s_setprio 0
	s_setprio 1
	v_mfma_f32_16x16x32_bf16 v[118:121], v[164:167], v[192:195], v[118:121]
	v_mfma_f32_16x16x32_bf16 v[114:117], v[172:175], v[192:195], v[114:117]
	v_mfma_f32_16x16x32_bf16 v[102:105], v[164:167], v[200:203], v[102:105]
	v_mfma_f32_16x16x32_bf16 v[98:101], v[172:175], v[200:203], v[98:101]
	v_mfma_f32_16x16x32_bf16 v[84:87], v[164:167], v[208:211], v[84:87]
	v_mfma_f32_16x16x32_bf16 v[80:83], v[172:175], v[208:211], v[80:83]
	v_mfma_f32_16x16x32_bf16 v[68:71], v[164:167], v[230:233], v[68:71]
	v_mfma_f32_16x16x32_bf16 v[64:67], v[172:175], v[230:233], v[64:67]
	v_mfma_f32_16x16x32_bf16 v[118:121], v[168:171], v[196:199], v[118:121]
	v_mfma_f32_16x16x32_bf16 v[114:117], v[188:191], v[196:199], v[114:117]
	v_mfma_f32_16x16x32_bf16 v[102:105], v[168:171], v[204:207], v[102:105]
	v_mfma_f32_16x16x32_bf16 v[98:101], v[188:191], v[204:207], v[98:101]
	v_mfma_f32_16x16x32_bf16 v[84:87], v[168:171], v[226:229], v[84:87]
	v_mfma_f32_16x16x32_bf16 v[80:83], v[188:191], v[226:229], v[80:83]
	v_mfma_f32_16x16x32_bf16 v[68:71], v[168:171], v[234:237], v[68:71]
	v_mfma_f32_16x16x32_bf16 v[64:67], v[188:191], v[234:237], v[64:67]
	s_setprio 0
	s_barrier
	s_add_i32 s61, s61, s37
	v_lshl_add_u64 v[142:143], s[30:31], 0, v[134:135]
	s_mov_b32 m0, s61
	ds_read_b128 v[192:195], v146 offset:16384
	ds_read_b128 v[196:199], v146 offset:17408
	ds_read_b128 v[200:203], v146 offset:18432
	ds_read_b128 v[204:207], v146 offset:19456
	ds_read_b128 v[208:211], v146 offset:20480
	ds_read_b128 v[226:229], v146 offset:21504
	ds_read_b128 v[230:233], v146 offset:22528
	ds_read_b128 v[234:237], v146 offset:23552
	global_load_lds_dwordx4 v[142:143], off
	s_add_i32 m0, s61, 0x2000
	v_lshl_add_u64 v[176:177], s[30:31], 0, v[130:131]
	s_add_u32 s30, s30, s16
	s_addc_u32 s31, s31, 0
	s_add_i32 s23, s23, s37
	global_load_lds_dwordx4 v[176:177], off
	v_lshl_add_u64 v[214:215], s[30:31], 0, v[134:135]
	s_mov_b32 m0, s23
	v_lshl_add_u64 v[238:239], s[30:31], 0, v[130:131]
	global_load_lds_dwordx4 v[214:215], off
	s_add_i32 m0, s23, 0x2000
	v_lshl_add_u64 v[240:241], s[10:11], 0, v[136:137]
	global_load_lds_dwordx4 v[238:239], off
	s_mov_b32 m0, s39
	v_lshl_add_u64 v[242:243], s[10:11], 0, v[132:133]
	global_load_lds_dwordx4 v[240:241], off
	s_mov_b32 m0, s40
	s_nop 0
	global_load_lds_dwordx4 v[242:243], off
	s_waitcnt vmcnt(8)
	s_waitcnt lgkmcnt(0)
	s_barrier
; #define PG8_STAGE(bufoff, gbase, voff) do { _Pragma("unroll") for (int _i = 0; _i < 2; ++_i) \
;         __builtin_amdgcn_global_load_lds((const unsigned*)((const char*)(gbase) + (voff)[_i]), (LAS unsigned*)(lds + (bufoff) + ldsw + _i * 8192), 16, 0, 0); } while (0)
; #define PG8_LDA(dst, b, h) do { _Pragma("unroll") for (int m = 0; m < 4; ++m) _Pragma("unroll") for (int k = 0; k < 2; ++k) dst[m][k] = *(const LAS bf16x8*)(lds + PG8_SA(b, h) + aoff + m * 2048 + k * 1024); } while (0)
; #define PG8_LDB(dst, b, h) do { _Pragma("unroll") for (int n = 0; n < 2; ++n) _Pragma("unroll") for (int k = 0; k < 2; ++k) dst[n][k] = *(const LAS bf16x8*)(lds + PG8_SB(b, h) + boff + n * 2048 + k * 1024); } while (0)
; #define PG8_MMA(ai, bj, At, Bt) do { __builtin_amdgcn_s_setprio(1); _Pragma("unroll") for (int m = 0; m < 4; ++m) _Pragma("unroll") for (int n = 0; n < 2; ++n) _Pragma("unroll") for (int k = 0; k < 2; ++k) \
;         acc[ai][bj][m][n] = __builtin_amdgcn_mfma_f32_16x16x32_bf16(Bt[n][k], At[m][k], acc[ai][bj][m][n], 0, 0, 0); __builtin_amdgcn_s_setprio(0); } while (0)
; #define PG8_WAIT_V(n) asm volatile("s_waitcnt vmcnt(" #n ")" ::: "memory")
; #define PG8_WAIT_L(n) asm volatile("s_waitcnt lgkmcnt(" #n ")" ::: "memory")
; #define PG8_BAR __builtin_amdgcn_s_barrier()
; #define PG8_SCHED __builtin_amdgcn_sched_barrier(0)
;     ...
;             PG8_WAIT_V(8); PG8_WAIT_L(0); PG8_BAR; PG8_MMA(1, 0, At, B0); PG8_MMA(1, 1, At, B1); PG8_BAR; PG8_SCHED;
;             PG8_LDB(B0, 1, 0); PG8_LDB(B1, 1, 1); PG8_SCHED; PG8_LDA(At, 1, 0); PG8_STAGE(PG8_SA(0, 1), a2 + hstep, voffA);
;             PG8_WAIT_V(8); PG8_WAIT_L(0); PG8_BAR; PG8_MMA(0, 0, At, B0); PG8_MMA(0, 1, At, B1); PG8_BAR; PG8_SCHED;
	s_setprio 1
	v_mfma_f32_16x16x32_bf16 v[60:63], v[148:151], v[192:195], v[60:63]
	v_mfma_f32_16x16x32_bf16 v[56:59], v[156:159], v[192:195], v[56:59]
	v_mfma_f32_16x16x32_bf16 v[44:47], v[148:151], v[200:203], v[44:47]
	v_mfma_f32_16x16x32_bf16 v[40:43], v[156:159], v[200:203], v[40:43]
	v_mfma_f32_16x16x32_bf16 v[28:31], v[148:151], v[208:211], v[28:31]
	v_mfma_f32_16x16x32_bf16 v[24:27], v[156:159], v[208:211], v[24:27]
	v_mfma_f32_16x16x32_bf16 v[12:15], v[148:151], v[230:233], v[12:15]
	v_mfma_f32_16x16x32_bf16 v[8:11], v[156:159], v[230:233], v[8:11]
	v_mfma_f32_16x16x32_bf16 v[60:63], v[152:155], v[196:199], v[60:63]
	v_mfma_f32_16x16x32_bf16 v[56:59], v[160:163], v[196:199], v[56:59]
	v_mfma_f32_16x16x32_bf16 v[44:47], v[152:155], v[204:207], v[44:47]
	v_mfma_f32_16x16x32_bf16 v[40:43], v[160:163], v[204:207], v[40:43]
	v_mfma_f32_16x16x32_bf16 v[28:31], v[152:155], v[226:229], v[28:31]
	v_mfma_f32_16x16x32_bf16 v[24:27], v[160:163], v[226:229], v[24:27]
	v_mfma_f32_16x16x32_bf16 v[12:15], v[152:155], v[234:237], v[12:15]
	v_mfma_f32_16x16x32_bf16 v[8:11], v[160:163], v[234:237], v[8:11]
	s_setprio 0
	s_setprio 1
	v_mfma_f32_16x16x32_bf16 v[52:55], v[164:167], v[192:195], v[52:55]
	v_mfma_f32_16x16x32_bf16 v[48:51], v[172:175], v[192:195], v[48:51]
	v_mfma_f32_16x16x32_bf16 v[36:39], v[164:167], v[200:203], v[36:39]
	v_mfma_f32_16x16x32_bf16 v[32:35], v[172:175], v[200:203], v[32:35]
	v_mfma_f32_16x16x32_bf16 v[20:23], v[164:167], v[208:211], v[20:23]
	v_mfma_f32_16x16x32_bf16 v[16:19], v[172:175], v[208:211], v[16:19]
	v_mfma_f32_16x16x32_bf16 v[4:7], v[164:167], v[230:233], v[4:7]
	v_mfma_f32_16x16x32_bf16 v[0:3], v[172:175], v[230:233], v[0:3]
	v_mfma_f32_16x16x32_bf16 v[52:55], v[168:171], v[196:199], v[52:55]
	v_mfma_f32_16x16x32_bf16 v[48:51], v[188:191], v[196:199], v[48:51]
	v_mfma_f32_16x16x32_bf16 v[36:39], v[168:171], v[204:207], v[36:39]
	v_mfma_f32_16x16x32_bf16 v[32:35], v[188:191], v[204:207], v[32:35]
	v_mfma_f32_16x16x32_bf16 v[20:23], v[168:171], v[226:229], v[20:23]
	v_mfma_f32_16x16x32_bf16 v[16:19], v[188:191], v[226:229], v[16:19]
	v_mfma_f32_16x16x32_bf16 v[4:7], v[168:171], v[234:237], v[4:7]
	v_mfma_f32_16x16x32_bf16 v[0:3], v[188:191], v[234:237], v[0:3]
	s_setprio 0
	s_barrier
	s_add_i32 s23, 0, 0x18000
	v_add_u32_e32 v147, s23, v145
	s_add_i32 s30, 0, 0x1c000
	ds_read_b128 v[148:151], v147
	ds_read_b128 v[152:155], v147 offset:1024
	ds_read_b128 v[156:159], v147 offset:2048
	ds_read_b128 v[160:163], v147 offset:3072
	v_add_u32_e32 v147, s30, v145
	ds_read_b128 v[164:167], v147
	ds_read_b128 v[168:171], v147 offset:1024
	ds_read_b128 v[172:175], v147 offset:2048
	ds_read_b128 v[188:191], v147 offset:3072
	s_add_u32 s10, s10, s16
	s_addc_u32 s11, s11, 0
	s_mov_b32 m0, s41
	v_lshl_add_u64 v[244:245], s[10:11], 0, v[136:137]
	ds_read_b128 v[192:195], v146 offset:32768
	ds_read_b128 v[196:199], v146 offset:33792
	ds_read_b128 v[200:203], v146 offset:34816
	ds_read_b128 v[204:207], v146 offset:35840
	ds_read_b128 v[208:211], v146 offset:36864
	ds_read_b128 v[226:229], v146 offset:37888
	ds_read_b128 v[230:233], v146 offset:38912
	ds_read_b128 v[234:237], v146 offset:39936
	global_load_lds_dwordx4 v[244:245], off
	v_lshl_add_u64 v[244:245], s[10:11], 0, v[132:133]
	s_mov_b32 m0, s42
	s_nop 0
	global_load_lds_dwordx4 v[244:245], off
	s_waitcnt vmcnt(8)
	s_waitcnt lgkmcnt(0)
	s_barrier
	s_setprio 1
	v_mfma_f32_16x16x32_bf16 v[126:129], v[148:151], v[192:195], v[126:129]
	v_mfma_f32_16x16x32_bf16 v[122:125], v[156:159], v[192:195], v[122:125]
	v_mfma_f32_16x16x32_bf16 v[110:113], v[148:151], v[200:203], v[110:113]
	v_mfma_f32_16x16x32_bf16 v[106:109], v[156:159], v[200:203], v[106:109]
	v_mfma_f32_16x16x32_bf16 v[92:95], v[148:151], v[208:211], v[92:95]
	v_mfma_f32_16x16x32_bf16 v[88:91], v[156:159], v[208:211], v[88:91]
	v_mfma_f32_16x16x32_bf16 v[76:79], v[148:151], v[230:233], v[76:79]
	v_mfma_f32_16x16x32_bf16 v[72:75], v[156:159], v[230:233], v[72:75]
	v_mfma_f32_16x16x32_bf16 v[126:129], v[152:155], v[196:199], v[126:129]
	v_mfma_f32_16x16x32_bf16 v[122:125], v[160:163], v[196:199], v[122:125]
	v_mfma_f32_16x16x32_bf16 v[110:113], v[152:155], v[204:207], v[110:113]
	v_mfma_f32_16x16x32_bf16 v[106:109], v[160:163], v[204:207], v[106:109]
	v_mfma_f32_16x16x32_bf16 v[92:95], v[152:155], v[226:229], v[92:95]
	v_mfma_f32_16x16x32_bf16 v[88:91], v[160:163], v[226:229], v[88:91]
	v_mfma_f32_16x16x32_bf16 v[76:79], v[152:155], v[234:237], v[76:79]
	v_mfma_f32_16x16x32_bf16 v[72:75], v[160:163], v[234:237], v[72:75]
	s_setprio 0
	s_setprio 1
	v_mfma_f32_16x16x32_bf16 v[118:121], v[164:167], v[192:195], v[118:121]
	v_mfma_f32_16x16x32_bf16 v[114:117], v[172:175], v[192:195], v[114:117]
	v_mfma_f32_16x16x32_bf16 v[102:105], v[164:167], v[200:203], v[102:105]
	v_mfma_f32_16x16x32_bf16 v[98:101], v[172:175], v[200:203], v[98:101]
	v_mfma_f32_16x16x32_bf16 v[84:87], v[164:167], v[208:211], v[84:87]
	v_mfma_f32_16x16x32_bf16 v[80:83], v[172:175], v[208:211], v[80:83]
	v_mfma_f32_16x16x32_bf16 v[68:71], v[164:167], v[230:233], v[68:71]
	v_mfma_f32_16x16x32_bf16 v[64:67], v[172:175], v[230:233], v[64:67]
	v_mfma_f32_16x16x32_bf16 v[118:121], v[168:171], v[196:199], v[118:121]
	v_mfma_f32_16x16x32_bf16 v[114:117], v[188:191], v[196:199], v[114:117]
	v_mfma_f32_16x16x32_bf16 v[102:105], v[168:171], v[204:207], v[102:105]
	v_mfma_f32_16x16x32_bf16 v[98:101], v[188:191], v[204:207], v[98:101]
	v_mfma_f32_16x16x32_bf16 v[84:87], v[168:171], v[226:229], v[84:87]
	v_mfma_f32_16x16x32_bf16 v[80:83], v[188:191], v[226:229], v[80:83]
	v_mfma_f32_16x16x32_bf16 v[68:71], v[168:171], v[234:237], v[68:71]
	v_mfma_f32_16x16x32_bf16 v[64:67], v[188:191], v[234:237], v[64:67]
	s_setprio 0
	s_barrier
; #define PG8_STAGE(bufoff, gbase, voff) do { _Pragma("unroll") for (int _i = 0; _i < 2; ++_i) \
;         __builtin_amdgcn_global_load_lds((const unsigned*)((const char*)(gbase) + (voff)[_i]), (LAS unsigned*)(lds + (bufoff) + ldsw + _i * 8192), 16, 0, 0); } while (0)
; #define PG8_LDA(dst, b, h) do { _Pragma("unroll") for (int m = 0; m < 4; ++m) _Pragma("unroll") for (int k = 0; k < 2; ++k) dst[m][k] = *(const LAS bf16x8*)(lds + PG8_SA(b, h) + aoff + m * 2048 + k * 1024); } while (0)
; #define PG8_MMA(ai, bj, At, Bt) do { __builtin_amdgcn_s_setprio(1); _Pragma("unroll") for (int m = 0; m < 4; ++m) _Pragma("unroll") for (int n = 0; n < 2; ++n) _Pragma("unroll") for (int k = 0; k < 2; ++k) \
;         acc[ai][bj][m][n] = __builtin_amdgcn_mfma_f32_16x16x32_bf16(Bt[n][k], At[m][k], acc[ai][bj][m][n], 0, 0, 0); __builtin_amdgcn_s_setprio(0); } while (0)
; #define PG8_WAIT_V(n) asm volatile("s_waitcnt vmcnt(" #n ")" ::: "memory")
; #define PG8_WAIT_L(n) asm volatile("s_waitcnt lgkmcnt(" #n ")" ::: "memory")
; #define PG8_BAR __builtin_amdgcn_s_barrier()
; #define PG8_SCHED __builtin_amdgcn_sched_barrier(0)
;     ...
;             PG8_LDA(At, 1, 1); PG8_STAGE(PG8_SB(1, 0), b3, voffB); PG8_STAGE(PG8_SB(1, 1), b3 + hstep, voffB); PG8_STAGE(PG8_SA(1, 0), a3, voffA);
;             PG8_WAIT_V(8); PG8_WAIT_L(0); PG8_BAR; PG8_MMA(1, 0, At, B0); PG8_MMA(1, 1, At, B1); PG8_BAR; PG8_SCHED;
;         }
	s_add_i32 s10, s23, s37
	v_lshl_add_u64 v[142:143], v[142:143], 0, s[46:47]
	s_mov_b32 m0, s10
	ds_read_b128 v[192:195], v146 offset:49152
	ds_read_b128 v[196:199], v146 offset:50176
	ds_read_b128 v[200:203], v146 offset:51200
	ds_read_b128 v[204:207], v146 offset:52224
	ds_read_b128 v[208:211], v146 offset:53248
	ds_read_b128 v[226:229], v146 offset:54272
	ds_read_b128 v[230:233], v146 offset:55296
	ds_read_b128 v[234:237], v146 offset:56320
	global_load_lds_dwordx4 v[142:143], off
	v_lshl_add_u64 v[142:143], v[176:177], 0, s[46:47]
	s_add_i32 m0, s10, 0x2000
	s_add_i32 s10, s30, s37
	global_load_lds_dwordx4 v[142:143], off
	v_lshl_add_u64 v[142:143], v[214:215], 0, s[46:47]
	s_mov_b32 m0, s10
	s_nop 0
	global_load_lds_dwordx4 v[142:143], off
	v_lshl_add_u64 v[142:143], v[238:239], 0, s[46:47]
	s_add_i32 m0, s10, 0x2000
	s_nop 0
	global_load_lds_dwordx4 v[142:143], off
	v_lshl_add_u64 v[142:143], v[240:241], 0, s[46:47]
	s_mov_b32 m0, s43
	s_nop 0
	global_load_lds_dwordx4 v[142:143], off
	v_lshl_add_u64 v[142:143], v[242:243], 0, s[46:47]
	s_mov_b32 m0, s50
	s_nop 0
	global_load_lds_dwordx4 v[142:143], off
	s_waitcnt vmcnt(8)
	s_waitcnt lgkmcnt(0)
	s_barrier
	s_setprio 1
	v_mfma_f32_16x16x32_bf16 v[60:63], v[148:151], v[192:195], v[60:63]
	v_mfma_f32_16x16x32_bf16 v[56:59], v[156:159], v[192:195], v[56:59]
	v_mfma_f32_16x16x32_bf16 v[44:47], v[148:151], v[200:203], v[44:47]
	v_mfma_f32_16x16x32_bf16 v[40:43], v[156:159], v[200:203], v[40:43]
	v_mfma_f32_16x16x32_bf16 v[28:31], v[148:151], v[208:211], v[28:31]
	v_mfma_f32_16x16x32_bf16 v[24:27], v[156:159], v[208:211], v[24:27]
	v_mfma_f32_16x16x32_bf16 v[12:15], v[148:151], v[230:233], v[12:15]
	v_mfma_f32_16x16x32_bf16 v[8:11], v[156:159], v[230:233], v[8:11]
	v_mfma_f32_16x16x32_bf16 v[60:63], v[152:155], v[196:199], v[60:63]
	v_mfma_f32_16x16x32_bf16 v[56:59], v[160:163], v[196:199], v[56:59]
	v_mfma_f32_16x16x32_bf16 v[44:47], v[152:155], v[204:207], v[44:47]
	v_mfma_f32_16x16x32_bf16 v[40:43], v[160:163], v[204:207], v[40:43]
	v_mfma_f32_16x16x32_bf16 v[28:31], v[152:155], v[226:229], v[28:31]
	v_mfma_f32_16x16x32_bf16 v[24:27], v[160:163], v[226:229], v[24:27]
	v_mfma_f32_16x16x32_bf16 v[12:15], v[152:155], v[234:237], v[12:15]
	v_mfma_f32_16x16x32_bf16 v[8:11], v[160:163], v[234:237], v[8:11]
	s_setprio 0
	s_setprio 1
	v_mfma_f32_16x16x32_bf16 v[52:55], v[164:167], v[192:195], v[52:55]
	v_mfma_f32_16x16x32_bf16 v[48:51], v[172:175], v[192:195], v[48:51]
	v_mfma_f32_16x16x32_bf16 v[36:39], v[164:167], v[200:203], v[36:39]
	v_mfma_f32_16x16x32_bf16 v[32:35], v[172:175], v[200:203], v[32:35]
	v_mfma_f32_16x16x32_bf16 v[20:23], v[164:167], v[208:211], v[20:23]
	v_mfma_f32_16x16x32_bf16 v[16:19], v[172:175], v[208:211], v[16:19]
	v_mfma_f32_16x16x32_bf16 v[4:7], v[164:167], v[230:233], v[4:7]
	v_mfma_f32_16x16x32_bf16 v[0:3], v[172:175], v[230:233], v[0:3]
	v_mfma_f32_16x16x32_bf16 v[52:55], v[168:171], v[196:199], v[52:55]
	v_mfma_f32_16x16x32_bf16 v[48:51], v[188:191], v[196:199], v[48:51]
	v_mfma_f32_16x16x32_bf16 v[36:39], v[168:171], v[204:207], v[36:39]
	v_mfma_f32_16x16x32_bf16 v[32:35], v[188:191], v[204:207], v[32:35]
	v_mfma_f32_16x16x32_bf16 v[20:23], v[168:171], v[226:229], v[20:23]
	v_mfma_f32_16x16x32_bf16 v[16:19], v[188:191], v[226:229], v[16:19]
	v_mfma_f32_16x16x32_bf16 v[4:7], v[168:171], v[234:237], v[4:7]
	v_mfma_f32_16x16x32_bf16 v[0:3], v[188:191], v[234:237], v[0:3]
	s_setprio 0
	s_barrier
	s_add_u32 s28, s28, 0x100
	s_addc_u32 s29, s29, 0
	s_add_u32 s8, s8, 0x100
	s_addc_u32 s9, s9, 0
	s_cmp_ge_u32 s21, s51
	s_mov_b32 s10, s21
	s_cbranch_scc0 .LBB0_98
	s_and_b64 vcc, exec, s[14:15]
	s_cbranch_vccz .LBB0_101

; #define PG8_STAGE(bufoff, gbase, voff) do { _Pragma("unroll") for (int _i = 0; _i < 2; ++_i) \
;         __builtin_amdgcn_global_load_lds((const unsigned*)((const char*)(gbase) + (voff)[_i]), (LAS unsigned*)(lds + (bufoff) + ldsw + _i * 8192), 16, 0, 0); } while (0)
; #define PG8_LDA(dst, b, h) do { _Pragma("unroll") for (int m = 0; m < 4; ++m) _Pragma("unroll") for (int k = 0; k < 2; ++k) dst[m][k] = *(const LAS bf16x8*)(lds + PG8_SA(b, h) + aoff + m * 2048 + k * 1024); } while (0)
; #define PG8_LDB(dst, b, h) do { _Pragma("unroll") for (int n = 0; n < 2; ++n) _Pragma("unroll") for (int k = 0; k < 2; ++k) dst[n][k] = *(const LAS bf16x8*)(lds + PG8_SB(b, h) + boff + n * 2048 + k * 1024); } while (0)
; #define PG8_MMA(ai, bj, At, Bt) do { __builtin_amdgcn_s_setprio(1); _Pragma("unroll") for (int m = 0; m < 4; ++m) _Pragma("unroll") for (int n = 0; n < 2; ++n) _Pragma("unroll") for (int k = 0; k < 2; ++k) \
;         acc[ai][bj][m][n] = __builtin_amdgcn_mfma_f32_16x16x32_bf16(Bt[n][k], At[m][k], acc[ai][bj][m][n], 0, 0, 0); __builtin_amdgcn_s_setprio(0); } while (0)
; #define PG8_WAIT_V(n) asm volatile("s_waitcnt vmcnt(" #n ")" ::: "memory")
; #define PG8_WAIT_L(n) asm volatile("s_waitcnt lgkmcnt(" #n ")" ::: "memory")
; #define PG8_BAR __builtin_amdgcn_s_barrier()
; #define PG8_SCHED __builtin_amdgcn_sched_barrier(0)
;     ...
;         for (int t = 0; t < nt; t += 2) {
;             const bool last = (t == nt - 2);
;             const char* a1 = cA + (size_t)(t + 1) * kstep;
;             const char* a2 = last ? nA : cA + (size_t)(t + 2) * kstep; const char* b2 = last ? nB : cB + (size_t)(t + 2) * kstep;
;             const char* a3 = a2 + kstep; const char* b3 = b2 + kstep;
;             PG8_LDB(B0, 0, 0); PG8_LDB(B1, 0, 1); PG8_SCHED; PG8_LDA(At, 0, 0); PG8_STAGE(PG8_SA(1, 1), a1 + hstep, voffA);
;             PG8_WAIT_V(8); PG8_WAIT_L(0); PG8_BAR; PG8_MMA(0, 0, At, B0); PG8_MMA(0, 1, At, B1); PG8_BAR; PG8_SCHED;
;             PG8_LDA(At, 0, 1); PG8_STAGE(PG8_SB(0, 0), b2, voffB); PG8_STAGE(PG8_SB(0, 1), b2 + hstep, voffB); PG8_STAGE(PG8_SA(0, 0), a2, voffA);
;             PG8_WAIT_V(8); PG8_WAIT_L(0); PG8_BAR; PG8_MMA(1, 0, At, B0); PG8_MMA(1, 1, At, B1); PG8_BAR; PG8_SCHED;
.LBB0_138:
	s_add_i32 s14, s9, 2
	s_add_u32 s10, s12, 0x80
	s_addc_u32 s11, s13, 0
	s_add_i32 s15, 0, 0x10000
	s_cmp_eq_u32 s38, s9
	s_cselect_b32 s11, s71, s11
	s_cselect_b32 s10, s70, s10
	s_cselect_b32 s35, s43, s8
	s_cselect_b32 s34, s42, s5
	s_add_i32 s9, 0, 0x14000
	v_add_u32_e32 v76, s15, v209
	v_add_u32_e32 v170, s9, v209
	ds_read_b128 v[64:67], v76
	ds_read_b128 v[68:71], v76 offset:1024
	ds_read_b128 v[72:75], v76 offset:2048
	ds_read_b128 v[76:79], v76 offset:3072
	ds_read_b128 v[158:161], v170
	ds_read_b128 v[162:165], v170 offset:1024
	ds_read_b128 v[166:169], v170 offset:2048
	ds_read_b128 v[170:173], v170 offset:3072
	v_lshl_add_u64 v[204:205], s[12:13], 0, v[154:155]
	s_add_i32 m0, s97, 0xc000
	ds_read_b128 v[174:177], v226
	ds_read_b128 v[188:191], v226 offset:1024
	ds_read_b128 v[192:195], v226 offset:2048
	ds_read_b128 v[196:199], v226 offset:3072
	ds_read_b128 v[200:203], v226 offset:4096
	ds_read_b128 v[228:231], v226 offset:5120
	ds_read_b128 v[232:235], v226 offset:6144
	ds_read_b128 v[236:239], v226 offset:7168
	global_load_lds_dwordx4 v[204:205], off
	v_lshl_add_u64 v[204:205], s[12:13], 0, v[156:157]
	s_add_i32 m0, s97, 0xe000
	s_nop 0
	global_load_lds_dwordx4 v[204:205], off
	s_waitcnt vmcnt(8)
	s_waitcnt lgkmcnt(0)
	s_barrier
	s_setprio 1
	v_mfma_f32_16x16x32_bf16 v[134:137], v[64:67], v[174:177], v[134:137]
	v_mfma_f32_16x16x32_bf16 v[130:133], v[72:75], v[174:177], v[130:133]
	v_mfma_f32_16x16x32_bf16 v[118:121], v[64:67], v[192:195], v[118:121]
	v_mfma_f32_16x16x32_bf16 v[114:117], v[72:75], v[192:195], v[114:117]
	v_mfma_f32_16x16x32_bf16 v[102:105], v[64:67], v[200:203], v[102:105]
	v_mfma_f32_16x16x32_bf16 v[98:101], v[72:75], v[200:203], v[98:101]
	v_mfma_f32_16x16x32_bf16 v[84:87], v[64:67], v[232:235], v[84:87]
	v_mfma_f32_16x16x32_bf16 v[80:83], v[72:75], v[232:235], v[80:83]
	v_mfma_f32_16x16x32_bf16 v[134:137], v[68:71], v[188:191], v[134:137]
	v_mfma_f32_16x16x32_bf16 v[130:133], v[76:79], v[188:191], v[130:133]
	v_mfma_f32_16x16x32_bf16 v[118:121], v[68:71], v[196:199], v[118:121]
	v_mfma_f32_16x16x32_bf16 v[114:117], v[76:79], v[196:199], v[114:117]
	v_mfma_f32_16x16x32_bf16 v[102:105], v[68:71], v[228:231], v[102:105]
	v_mfma_f32_16x16x32_bf16 v[98:101], v[76:79], v[228:231], v[98:101]
	v_mfma_f32_16x16x32_bf16 v[84:87], v[68:71], v[236:239], v[84:87]
	v_mfma_f32_16x16x32_bf16 v[80:83], v[76:79], v[236:239], v[80:83]
	s_setprio 0
	s_setprio 1
	v_mfma_f32_16x16x32_bf16 v[142:145], v[158:161], v[174:177], v[142:145]
	v_mfma_f32_16x16x32_bf16 v[138:141], v[166:169], v[174:177], v[138:141]
	v_mfma_f32_16x16x32_bf16 v[126:129], v[158:161], v[192:195], v[126:129]
	v_mfma_f32_16x16x32_bf16 v[122:125], v[166:169], v[192:195], v[122:125]
	v_mfma_f32_16x16x32_bf16 v[110:113], v[158:161], v[200:203], v[110:113]
	v_mfma_f32_16x16x32_bf16 v[106:109], v[166:169], v[200:203], v[106:109]
	v_mfma_f32_16x16x32_bf16 v[92:95], v[158:161], v[232:235], v[92:95]
	v_mfma_f32_16x16x32_bf16 v[88:91], v[166:169], v[232:235], v[88:91]
	v_mfma_f32_16x16x32_bf16 v[142:145], v[162:165], v[188:191], v[142:145]
	v_mfma_f32_16x16x32_bf16 v[138:141], v[170:173], v[188:191], v[138:141]
	v_mfma_f32_16x16x32_bf16 v[126:129], v[162:165], v[196:199], v[126:129]
	v_mfma_f32_16x16x32_bf16 v[122:125], v[170:173], v[196:199], v[122:125]
	v_mfma_f32_16x16x32_bf16 v[110:113], v[162:165], v[228:231], v[110:113]
	v_mfma_f32_16x16x32_bf16 v[106:109], v[170:173], v[228:231], v[106:109]
	v_mfma_f32_16x16x32_bf16 v[92:95], v[162:165], v[236:239], v[92:95]
	v_mfma_f32_16x16x32_bf16 v[88:91], v[170:173], v[236:239], v[88:91]
	s_setprio 0
	s_barrier
	s_add_i32 s15, s15, s91
	v_lshl_add_u64 v[204:205], s[34:35], 0, v[148:149]
	s_mov_b32 m0, s15
	ds_read_b128 v[174:177], v226 offset:16384
	ds_read_b128 v[188:191], v226 offset:17408
	ds_read_b128 v[192:195], v226 offset:18432
	ds_read_b128 v[196:199], v226 offset:19456
	ds_read_b128 v[200:203], v226 offset:20480
	ds_read_b128 v[228:231], v226 offset:21504
	ds_read_b128 v[232:235], v226 offset:22528
	ds_read_b128 v[236:239], v226 offset:23552
	global_load_lds_dwordx4 v[204:205], off
	s_add_i32 m0, s15, 0x2000
	v_lshl_add_u64 v[210:211], s[34:35], 0, v[152:153]
	s_add_u32 s34, s34, s20
	s_addc_u32 s35, s35, 0
	s_add_i32 s9, s9, s91
	global_load_lds_dwordx4 v[210:211], off
	v_lshl_add_u64 v[214:215], s[34:35], 0, v[148:149]
	s_mov_b32 m0, s9
	v_lshl_add_u64 v[240:241], s[34:35], 0, v[152:153]
	global_load_lds_dwordx4 v[214:215], off
	s_add_i32 m0, s9, 0x2000
	v_lshl_add_u64 v[242:243], s[10:11], 0, v[146:147]
	global_load_lds_dwordx4 v[240:241], off
	s_mov_b32 m0, s97
	v_lshl_add_u64 v[244:245], s[10:11], 0, v[150:151]
	global_load_lds_dwordx4 v[242:243], off
	s_mov_b32 m0, s18
	s_nop 0
	global_load_lds_dwordx4 v[244:245], off
	s_waitcnt vmcnt(8)
	s_waitcnt lgkmcnt(0)
	s_barrier
; #define PG8_STAGE(bufoff, gbase, voff) do { _Pragma("unroll") for (int _i = 0; _i < 2; ++_i) \
;         __builtin_amdgcn_global_load_lds((const unsigned*)((const char*)(gbase) + (voff)[_i]), (LAS unsigned*)(lds + (bufoff) + ldsw + _i * 8192), 16, 0, 0); } while (0)
; #define PG8_LDA(dst, b, h) do { _Pragma("unroll") for (int m = 0; m < 4; ++m) _Pragma("unroll") for (int k = 0; k < 2; ++k) dst[m][k] = *(const LAS bf16x8*)(lds + PG8_SA(b, h) + aoff + m * 2048 + k * 1024); } while (0)
; #define PG8_LDB(dst, b, h) do { _Pragma("unroll") for (int n = 0; n < 2; ++n) _Pragma("unroll") for (int k = 0; k < 2; ++k) dst[n][k] = *(const LAS bf16x8*)(lds + PG8_SB(b, h) + boff + n * 2048 + k * 1024); } while (0)
; #define PG8_MMA(ai, bj, At, Bt) do { __builtin_amdgcn_s_setprio(1); _Pragma("unroll") for (int m = 0; m < 4; ++m) _Pragma("unroll") for (int n = 0; n < 2; ++n) _Pragma("unroll") for (int k = 0; k < 2; ++k) \
;         acc[ai][bj][m][n] = __builtin_amdgcn_mfma_f32_16x16x32_bf16(Bt[n][k], At[m][k], acc[ai][bj][m][n], 0, 0, 0); __builtin_amdgcn_s_setprio(0); } while (0)
; #define PG8_WAIT_V(n) asm volatile("s_waitcnt vmcnt(" #n ")" ::: "memory")
; #define PG8_WAIT_L(n) asm volatile("s_waitcnt lgkmcnt(" #n ")" ::: "memory")
; #define PG8_BAR __builtin_amdgcn_s_barrier()
; #define PG8_SCHED __builtin_amdgcn_sched_barrier(0)
;     ...
;             PG8_WAIT_V(8); PG8_WAIT_L(0); PG8_BAR; PG8_MMA(1, 0, At, B0); PG8_MMA(1, 1, At, B1); PG8_BAR; PG8_SCHED;
;             PG8_LDB(B0, 1, 0); PG8_LDB(B1, 1, 1); PG8_SCHED; PG8_LDA(At, 1, 0); PG8_STAGE(PG8_SA(0, 1), a2 + hstep, voffA);
;             PG8_WAIT_V(8); PG8_WAIT_L(0); PG8_BAR; PG8_MMA(0, 0, At, B0); PG8_MMA(0, 1, At, B1); PG8_BAR; PG8_SCHED;
	s_setprio 1
	v_mfma_f32_16x16x32_bf16 v[52:55], v[64:67], v[174:177], v[52:55]
	v_mfma_f32_16x16x32_bf16 v[48:51], v[72:75], v[174:177], v[48:51]
	v_mfma_f32_16x16x32_bf16 v[36:39], v[64:67], v[192:195], v[36:39]
	v_mfma_f32_16x16x32_bf16 v[32:35], v[72:75], v[192:195], v[32:35]
	v_mfma_f32_16x16x32_bf16 v[20:23], v[64:67], v[200:203], v[20:23]
	v_mfma_f32_16x16x32_bf16 v[16:19], v[72:75], v[200:203], v[16:19]
	v_mfma_f32_16x16x32_bf16 v[8:11], v[64:67], v[232:235], v[8:11]
	v_mfma_f32_16x16x32_bf16 v[4:7], v[72:75], v[232:235], v[4:7]
	v_mfma_f32_16x16x32_bf16 v[52:55], v[68:71], v[188:191], v[52:55]
	v_mfma_f32_16x16x32_bf16 v[48:51], v[76:79], v[188:191], v[48:51]
	v_mfma_f32_16x16x32_bf16 v[36:39], v[68:71], v[196:199], v[36:39]
	v_mfma_f32_16x16x32_bf16 v[32:35], v[76:79], v[196:199], v[32:35]
	v_mfma_f32_16x16x32_bf16 v[20:23], v[68:71], v[228:231], v[20:23]
	v_mfma_f32_16x16x32_bf16 v[16:19], v[76:79], v[228:231], v[16:19]
	v_mfma_f32_16x16x32_bf16 v[8:11], v[68:71], v[236:239], v[8:11]
	v_mfma_f32_16x16x32_bf16 v[4:7], v[76:79], v[236:239], v[4:7]
	s_setprio 0
	s_setprio 1
	v_mfma_f32_16x16x32_bf16 v[60:63], v[158:161], v[174:177], v[60:63]
	v_mfma_f32_16x16x32_bf16 v[56:59], v[166:169], v[174:177], v[56:59]
	v_mfma_f32_16x16x32_bf16 v[44:47], v[158:161], v[192:195], v[44:47]
	v_mfma_f32_16x16x32_bf16 v[40:43], v[166:169], v[192:195], v[40:43]
	v_mfma_f32_16x16x32_bf16 v[28:31], v[158:161], v[200:203], v[28:31]
	v_mfma_f32_16x16x32_bf16 v[24:27], v[166:169], v[200:203], v[24:27]
	v_mfma_f32_16x16x32_bf16 v[12:15], v[158:161], v[232:235], v[12:15]
	v_mfma_f32_16x16x32_bf16 v[0:3], v[166:169], v[232:235], v[0:3]
	v_mfma_f32_16x16x32_bf16 v[60:63], v[162:165], v[188:191], v[60:63]
	v_mfma_f32_16x16x32_bf16 v[56:59], v[170:173], v[188:191], v[56:59]
	v_mfma_f32_16x16x32_bf16 v[44:47], v[162:165], v[196:199], v[44:47]
	v_mfma_f32_16x16x32_bf16 v[40:43], v[170:173], v[196:199], v[40:43]
	v_mfma_f32_16x16x32_bf16 v[28:31], v[162:165], v[228:231], v[28:31]
	v_mfma_f32_16x16x32_bf16 v[24:27], v[170:173], v[228:231], v[24:27]
	v_mfma_f32_16x16x32_bf16 v[12:15], v[162:165], v[236:239], v[12:15]
	v_mfma_f32_16x16x32_bf16 v[0:3], v[170:173], v[236:239], v[0:3]
	s_setprio 0
	s_barrier
	s_add_i32 s9, 0, 0x18000
	s_add_i32 s15, 0, 0x1c000
	v_add_u32_e32 v76, s9, v209
	v_add_u32_e32 v170, s15, v209
	ds_read_b128 v[64:67], v76
	ds_read_b128 v[68:71], v76 offset:1024
	ds_read_b128 v[72:75], v76 offset:2048
	ds_read_b128 v[76:79], v76 offset:3072
	ds_read_b128 v[158:161], v170
	ds_read_b128 v[162:165], v170 offset:1024
	ds_read_b128 v[166:169], v170 offset:2048
	ds_read_b128 v[170:173], v170 offset:3072
	s_add_u32 s10, s10, s20
	s_addc_u32 s11, s11, 0
	s_mov_b32 m0, s19
	v_lshl_add_u64 v[246:247], s[10:11], 0, v[146:147]
	ds_read_b128 v[174:177], v226 offset:32768
	ds_read_b128 v[188:191], v226 offset:33792
	ds_read_b128 v[192:195], v226 offset:34816
	ds_read_b128 v[196:199], v226 offset:35840
	ds_read_b128 v[200:203], v226 offset:36864
	ds_read_b128 v[228:231], v226 offset:37888
	ds_read_b128 v[232:235], v226 offset:38912
	ds_read_b128 v[236:239], v226 offset:39936
	global_load_lds_dwordx4 v[246:247], off
	v_lshl_add_u64 v[246:247], s[10:11], 0, v[150:151]
	s_mov_b32 m0, s22
	s_nop 0
	global_load_lds_dwordx4 v[246:247], off
	s_waitcnt vmcnt(8)
	s_waitcnt lgkmcnt(0)
	s_barrier
	s_setprio 1
	v_mfma_f32_16x16x32_bf16 v[134:137], v[64:67], v[174:177], v[134:137]
	v_mfma_f32_16x16x32_bf16 v[130:133], v[72:75], v[174:177], v[130:133]
	v_mfma_f32_16x16x32_bf16 v[118:121], v[64:67], v[192:195], v[118:121]
	v_mfma_f32_16x16x32_bf16 v[114:117], v[72:75], v[192:195], v[114:117]
	v_mfma_f32_16x16x32_bf16 v[102:105], v[64:67], v[200:203], v[102:105]
	v_mfma_f32_16x16x32_bf16 v[98:101], v[72:75], v[200:203], v[98:101]
	v_mfma_f32_16x16x32_bf16 v[84:87], v[64:67], v[232:235], v[84:87]
	v_mfma_f32_16x16x32_bf16 v[80:83], v[72:75], v[232:235], v[80:83]
	v_mfma_f32_16x16x32_bf16 v[134:137], v[68:71], v[188:191], v[134:137]
	v_mfma_f32_16x16x32_bf16 v[130:133], v[76:79], v[188:191], v[130:133]
	v_mfma_f32_16x16x32_bf16 v[118:121], v[68:71], v[196:199], v[118:121]
	v_mfma_f32_16x16x32_bf16 v[114:117], v[76:79], v[196:199], v[114:117]
	v_mfma_f32_16x16x32_bf16 v[102:105], v[68:71], v[228:231], v[102:105]
	v_mfma_f32_16x16x32_bf16 v[98:101], v[76:79], v[228:231], v[98:101]
	v_mfma_f32_16x16x32_bf16 v[84:87], v[68:71], v[236:239], v[84:87]
	v_mfma_f32_16x16x32_bf16 v[80:83], v[76:79], v[236:239], v[80:83]
	s_setprio 0
	s_setprio 1
	v_mfma_f32_16x16x32_bf16 v[142:145], v[158:161], v[174:177], v[142:145]
	v_mfma_f32_16x16x32_bf16 v[138:141], v[166:169], v[174:177], v[138:141]
	v_mfma_f32_16x16x32_bf16 v[126:129], v[158:161], v[192:195], v[126:129]
	v_mfma_f32_16x16x32_bf16 v[122:125], v[166:169], v[192:195], v[122:125]
	v_mfma_f32_16x16x32_bf16 v[110:113], v[158:161], v[200:203], v[110:113]
	v_mfma_f32_16x16x32_bf16 v[106:109], v[166:169], v[200:203], v[106:109]
	v_mfma_f32_16x16x32_bf16 v[92:95], v[158:161], v[232:235], v[92:95]
	v_mfma_f32_16x16x32_bf16 v[88:91], v[166:169], v[232:235], v[88:91]
	v_mfma_f32_16x16x32_bf16 v[142:145], v[162:165], v[188:191], v[142:145]
	v_mfma_f32_16x16x32_bf16 v[138:141], v[170:173], v[188:191], v[138:141]
	v_mfma_f32_16x16x32_bf16 v[126:129], v[162:165], v[196:199], v[126:129]
	v_mfma_f32_16x16x32_bf16 v[122:125], v[170:173], v[196:199], v[122:125]
	v_mfma_f32_16x16x32_bf16 v[110:113], v[162:165], v[228:231], v[110:113]
	v_mfma_f32_16x16x32_bf16 v[106:109], v[170:173], v[228:231], v[106:109]
	v_mfma_f32_16x16x32_bf16 v[92:95], v[162:165], v[236:239], v[92:95]
	v_mfma_f32_16x16x32_bf16 v[88:91], v[170:173], v[236:239], v[88:91]
	s_setprio 0
	s_barrier
; #define PG8_STAGE(bufoff, gbase, voff) do { _Pragma("unroll") for (int _i = 0; _i < 2; ++_i) \
;         __builtin_amdgcn_global_load_lds((const unsigned*)((const char*)(gbase) + (voff)[_i]), (LAS unsigned*)(lds + (bufoff) + ldsw + _i * 8192), 16, 0, 0); } while (0)
; #define PG8_LDA(dst, b, h) do { _Pragma("unroll") for (int m = 0; m < 4; ++m) _Pragma("unroll") for (int k = 0; k < 2; ++k) dst[m][k] = *(const LAS bf16x8*)(lds + PG8_SA(b, h) + aoff + m * 2048 + k * 1024); } while (0)
; #define PG8_MMA(ai, bj, At, Bt) do { __builtin_amdgcn_s_setprio(1); _Pragma("unroll") for (int m = 0; m < 4; ++m) _Pragma("unroll") for (int n = 0; n < 2; ++n) _Pragma("unroll") for (int k = 0; k < 2; ++k) \
;         acc[ai][bj][m][n] = __builtin_amdgcn_mfma_f32_16x16x32_bf16(Bt[n][k], At[m][k], acc[ai][bj][m][n], 0, 0, 0); __builtin_amdgcn_s_setprio(0); } while (0)
; #define PG8_WAIT_V(n) asm volatile("s_waitcnt vmcnt(" #n ")" ::: "memory")
; #define PG8_WAIT_L(n) asm volatile("s_waitcnt lgkmcnt(" #n ")" ::: "memory")
; #define PG8_BAR __builtin_amdgcn_s_barrier()
; #define PG8_SCHED __builtin_amdgcn_sched_barrier(0)
;     ...
;             PG8_LDA(At, 1, 1); PG8_STAGE(PG8_SB(1, 0), b3, voffB); PG8_STAGE(PG8_SB(1, 1), b3 + hstep, voffB); PG8_STAGE(PG8_SA(1, 0), a3, voffA);
;             PG8_WAIT_V(8); PG8_WAIT_L(0); PG8_BAR; PG8_MMA(1, 0, At, B0); PG8_MMA(1, 1, At, B1); PG8_BAR; PG8_SCHED;
;         }
	s_add_i32 s9, s9, s91
	v_lshl_add_u64 v[204:205], v[204:205], 0, s[46:47]
	s_mov_b32 m0, s9
	ds_read_b128 v[174:177], v226 offset:49152
	ds_read_b128 v[188:191], v226 offset:50176
	ds_read_b128 v[192:195], v226 offset:51200
	ds_read_b128 v[196:199], v226 offset:52224
	ds_read_b128 v[200:203], v226 offset:53248
	ds_read_b128 v[228:231], v226 offset:54272
	ds_read_b128 v[232:235], v226 offset:55296
	ds_read_b128 v[236:239], v226 offset:56320
	global_load_lds_dwordx4 v[204:205], off
	v_lshl_add_u64 v[204:205], v[210:211], 0, s[46:47]
	s_add_i32 m0, s9, 0x2000
	s_add_i32 s9, s15, s91
	global_load_lds_dwordx4 v[204:205], off
	v_lshl_add_u64 v[204:205], v[214:215], 0, s[46:47]
	s_mov_b32 m0, s9
	s_nop 0
	global_load_lds_dwordx4 v[204:205], off
	v_lshl_add_u64 v[204:205], v[240:241], 0, s[46:47]
	s_add_i32 m0, s9, 0x2000
	s_nop 0
	global_load_lds_dwordx4 v[204:205], off
	v_lshl_add_u64 v[204:205], v[242:243], 0, s[46:47]
	s_mov_b32 m0, s23
	s_nop 0
	global_load_lds_dwordx4 v[204:205], off
	v_lshl_add_u64 v[204:205], v[244:245], 0, s[46:47]
	s_mov_b32 m0, s37
	s_nop 0
	global_load_lds_dwordx4 v[204:205], off
	s_waitcnt vmcnt(8)
	s_waitcnt lgkmcnt(0)
	s_barrier
	s_setprio 1
	v_mfma_f32_16x16x32_bf16 v[52:55], v[64:67], v[174:177], v[52:55]
	v_mfma_f32_16x16x32_bf16 v[48:51], v[72:75], v[174:177], v[48:51]
	v_mfma_f32_16x16x32_bf16 v[36:39], v[64:67], v[192:195], v[36:39]
	v_mfma_f32_16x16x32_bf16 v[32:35], v[72:75], v[192:195], v[32:35]
	v_mfma_f32_16x16x32_bf16 v[20:23], v[64:67], v[200:203], v[20:23]
	v_mfma_f32_16x16x32_bf16 v[16:19], v[72:75], v[200:203], v[16:19]
	v_mfma_f32_16x16x32_bf16 v[8:11], v[64:67], v[232:235], v[8:11]
	v_mfma_f32_16x16x32_bf16 v[4:7], v[72:75], v[232:235], v[4:7]
	v_mfma_f32_16x16x32_bf16 v[52:55], v[68:71], v[188:191], v[52:55]
	v_mfma_f32_16x16x32_bf16 v[48:51], v[76:79], v[188:191], v[48:51]
	v_mfma_f32_16x16x32_bf16 v[36:39], v[68:71], v[196:199], v[36:39]
	v_mfma_f32_16x16x32_bf16 v[32:35], v[76:79], v[196:199], v[32:35]
	v_mfma_f32_16x16x32_bf16 v[20:23], v[68:71], v[228:231], v[20:23]
	v_mfma_f32_16x16x32_bf16 v[16:19], v[76:79], v[228:231], v[16:19]
	v_mfma_f32_16x16x32_bf16 v[8:11], v[68:71], v[236:239], v[8:11]
	v_mfma_f32_16x16x32_bf16 v[4:7], v[76:79], v[236:239], v[4:7]
	s_setprio 0
	s_setprio 1
	v_mfma_f32_16x16x32_bf16 v[60:63], v[158:161], v[174:177], v[60:63]
	v_mfma_f32_16x16x32_bf16 v[56:59], v[166:169], v[174:177], v[56:59]
	v_mfma_f32_16x16x32_bf16 v[44:47], v[158:161], v[192:195], v[44:47]
	v_mfma_f32_16x16x32_bf16 v[40:43], v[166:169], v[192:195], v[40:43]
	v_mfma_f32_16x16x32_bf16 v[28:31], v[158:161], v[200:203], v[28:31]
	v_mfma_f32_16x16x32_bf16 v[24:27], v[166:169], v[200:203], v[24:27]
	v_mfma_f32_16x16x32_bf16 v[12:15], v[158:161], v[232:235], v[12:15]
	v_mfma_f32_16x16x32_bf16 v[0:3], v[166:169], v[232:235], v[0:3]
	v_mfma_f32_16x16x32_bf16 v[60:63], v[162:165], v[188:191], v[60:63]
	v_mfma_f32_16x16x32_bf16 v[56:59], v[170:173], v[188:191], v[56:59]
	v_mfma_f32_16x16x32_bf16 v[44:47], v[162:165], v[196:199], v[44:47]
	v_mfma_f32_16x16x32_bf16 v[40:43], v[170:173], v[196:199], v[40:43]
	v_mfma_f32_16x16x32_bf16 v[28:31], v[162:165], v[228:231], v[28:31]
	v_mfma_f32_16x16x32_bf16 v[24:27], v[170:173], v[228:231], v[24:27]
	v_mfma_f32_16x16x32_bf16 v[12:15], v[162:165], v[236:239], v[12:15]
	v_mfma_f32_16x16x32_bf16 v[0:3], v[170:173], v[236:239], v[0:3]
	s_setprio 0
	s_barrier
	s_add_u32 s12, s12, 0x100
	s_addc_u32 s13, s13, 0
	s_add_u32 s5, s5, 0x100
	s_addc_u32 s8, s8, 0
	s_cmp_ge_u32 s14, s81
	s_mov_b32 s9, s14
	s_cbranch_scc0 .LBB0_138
	s_branch .LBB0_140

; #define PG8_STAGE(bufoff, gbase, voff) do { _Pragma("unroll") for (int _i = 0; _i < 2; ++_i) \
;         __builtin_amdgcn_global_load_lds((const unsigned*)((const char*)(gbase) + (voff)[_i]), (LAS unsigned*)(lds + (bufoff) + ldsw + _i * 8192), 16, 0, 0); } while (0)
; #define PG8_LDA(dst, b, h) do { _Pragma("unroll") for (int m = 0; m < 4; ++m) _Pragma("unroll") for (int k = 0; k < 2; ++k) dst[m][k] = *(const LAS bf16x8*)(lds + PG8_SA(b, h) + aoff + m * 2048 + k * 1024); } while (0)
; #define PG8_LDB(dst, b, h) do { _Pragma("unroll") for (int n = 0; n < 2; ++n) _Pragma("unroll") for (int k = 0; k < 2; ++k) dst[n][k] = *(const LAS bf16x8*)(lds + PG8_SB(b, h) + boff + n * 2048 + k * 1024); } while (0)
; #define PG8_MMA(ai, bj, At, Bt) do { __builtin_amdgcn_s_setprio(1); _Pragma("unroll") for (int m = 0; m < 4; ++m) _Pragma("unroll") for (int n = 0; n < 2; ++n) _Pragma("unroll") for (int k = 0; k < 2; ++k) \
;         acc[ai][bj][m][n] = __builtin_amdgcn_mfma_f32_16x16x32_bf16(Bt[n][k], At[m][k], acc[ai][bj][m][n], 0, 0, 0); __builtin_amdgcn_s_setprio(0); } while (0)
; #define PG8_WAIT_V(n) asm volatile("s_waitcnt vmcnt(" #n ")" ::: "memory")
; #define PG8_WAIT_L(n) asm volatile("s_waitcnt lgkmcnt(" #n ")" ::: "memory")
; #define PG8_BAR __builtin_amdgcn_s_barrier()
; #define PG8_SCHED __builtin_amdgcn_sched_barrier(0)
;     ...
;         for (int t = 0; t < nt; t += 2) {
;             const bool last = (t == nt - 2);
;             const char* a1 = cA + (size_t)(t + 1) * kstep;
;             const char* a2 = last ? nA : cA + (size_t)(t + 2) * kstep; const char* b2 = last ? nB : cB + (size_t)(t + 2) * kstep;
;             const char* a3 = a2 + kstep; const char* b3 = b2 + kstep;
;             PG8_LDB(B0, 0, 0); PG8_LDB(B1, 0, 1); PG8_SCHED; PG8_LDA(At, 0, 0); PG8_STAGE(PG8_SA(1, 1), a1 + hstep, voffA);
;             PG8_WAIT_V(8); PG8_WAIT_L(0); PG8_BAR; PG8_MMA(0, 0, At, B0); PG8_MMA(0, 1, At, B1); PG8_BAR; PG8_SCHED;
;             PG8_LDA(At, 0, 1); PG8_STAGE(PG8_SB(0, 0), b2, voffB); PG8_STAGE(PG8_SB(0, 1), b2 + hstep, voffB); PG8_STAGE(PG8_SA(0, 0), a2, voffA);
;             PG8_WAIT_V(8); PG8_WAIT_L(0); PG8_BAR; PG8_MMA(1, 0, At, B0); PG8_MMA(1, 1, At, B1); PG8_BAR; PG8_SCHED;
.LBB0_197:
	s_add_i32 s9, s6, 2
	s_add_u32 s11, s34, 0x80
	s_addc_u32 s7, s35, 0
	s_add_i32 s23, 0, 0x10000
	s_cmp_eq_u32 s15, s6
	s_cselect_b32 s7, s29, s7
	s_cselect_b32 s6, s28, s11
	s_cselect_b32 s43, s27, s8
	s_cselect_b32 s42, s26, s5
	s_add_i32 s11, 0, 0x14000
	v_add_u32_e32 v142, s23, v227
	v_add_u32_e32 v158, s11, v227
	s_waitcnt lgkmcnt(0)
	ds_read_b128 v[130:133], v142
	ds_read_b128 v[134:137], v142 offset:1024
	ds_read_b128 v[138:141], v142 offset:2048
	ds_read_b128 v[142:145], v142 offset:3072
	ds_read_b128 v[146:149], v158
	ds_read_b128 v[150:153], v158 offset:1024
	ds_read_b128 v[154:157], v158 offset:2048
	ds_read_b128 v[158:161], v158 offset:3072
	v_lshl_add_u64 v[214:215], s[34:35], 0, v[196:197]
	s_add_i32 m0, s56, 0xc000
	ds_read_b128 v[162:165], v228
	ds_read_b128 v[166:169], v228 offset:1024
	ds_read_b128 v[170:173], v228 offset:2048
	ds_read_b128 v[174:177], v228 offset:3072
	ds_read_b128 v[200:203], v228 offset:4096
	ds_read_b128 v[204:207], v228 offset:5120
	ds_read_b128 v[208:211], v228 offset:6144
	ds_read_b128 v[230:233], v228 offset:7168
	global_load_lds_dwordx4 v[214:215], off
	v_lshl_add_u64 v[214:215], s[34:35], 0, v[198:199]
	s_add_i32 m0, s56, 0xe000
	s_nop 0
	global_load_lds_dwordx4 v[214:215], off
	s_waitcnt vmcnt(8)
	s_waitcnt lgkmcnt(0)
	s_barrier
	s_setprio 1
	v_mfma_f32_16x16x32_bf16 v[126:129], v[130:133], v[162:165], v[126:129]
	v_mfma_f32_16x16x32_bf16 v[122:125], v[138:141], v[162:165], v[122:125]
	v_mfma_f32_16x16x32_bf16 v[118:121], v[130:133], v[170:173], v[118:121]
	v_mfma_f32_16x16x32_bf16 v[114:117], v[138:141], v[170:173], v[114:117]
	v_mfma_f32_16x16x32_bf16 v[110:113], v[130:133], v[200:203], v[110:113]
	v_mfma_f32_16x16x32_bf16 v[106:109], v[138:141], v[200:203], v[106:109]
	v_mfma_f32_16x16x32_bf16 v[102:105], v[130:133], v[208:211], v[102:105]
	v_mfma_f32_16x16x32_bf16 v[98:101], v[138:141], v[208:211], v[98:101]
	v_mfma_f32_16x16x32_bf16 v[126:129], v[134:137], v[166:169], v[126:129]
	v_mfma_f32_16x16x32_bf16 v[122:125], v[142:145], v[166:169], v[122:125]
	v_mfma_f32_16x16x32_bf16 v[118:121], v[134:137], v[174:177], v[118:121]
	v_mfma_f32_16x16x32_bf16 v[114:117], v[142:145], v[174:177], v[114:117]
	v_mfma_f32_16x16x32_bf16 v[110:113], v[134:137], v[204:207], v[110:113]
	v_mfma_f32_16x16x32_bf16 v[106:109], v[142:145], v[204:207], v[106:109]
	v_mfma_f32_16x16x32_bf16 v[102:105], v[134:137], v[230:233], v[102:105]
	v_mfma_f32_16x16x32_bf16 v[98:101], v[142:145], v[230:233], v[98:101]
	s_setprio 0
	s_setprio 1
	v_mfma_f32_16x16x32_bf16 v[92:95], v[146:149], v[162:165], v[92:95]
	v_mfma_f32_16x16x32_bf16 v[88:91], v[154:157], v[162:165], v[88:91]
	v_mfma_f32_16x16x32_bf16 v[84:87], v[146:149], v[170:173], v[84:87]
	v_mfma_f32_16x16x32_bf16 v[80:83], v[154:157], v[170:173], v[80:83]
	v_mfma_f32_16x16x32_bf16 v[76:79], v[146:149], v[200:203], v[76:79]
	v_mfma_f32_16x16x32_bf16 v[72:75], v[154:157], v[200:203], v[72:75]
	v_mfma_f32_16x16x32_bf16 v[68:71], v[146:149], v[208:211], v[68:71]
	v_mfma_f32_16x16x32_bf16 v[64:67], v[154:157], v[208:211], v[64:67]
	v_mfma_f32_16x16x32_bf16 v[92:95], v[150:153], v[166:169], v[92:95]
	v_mfma_f32_16x16x32_bf16 v[88:91], v[158:161], v[166:169], v[88:91]
	v_mfma_f32_16x16x32_bf16 v[84:87], v[150:153], v[174:177], v[84:87]
	v_mfma_f32_16x16x32_bf16 v[80:83], v[158:161], v[174:177], v[80:83]
	v_mfma_f32_16x16x32_bf16 v[76:79], v[150:153], v[204:207], v[76:79]
	v_mfma_f32_16x16x32_bf16 v[72:75], v[158:161], v[204:207], v[72:75]
	v_mfma_f32_16x16x32_bf16 v[68:71], v[150:153], v[230:233], v[68:71]
	v_mfma_f32_16x16x32_bf16 v[64:67], v[158:161], v[230:233], v[64:67]
	s_setprio 0
	s_barrier
	s_add_i32 s23, s23, s41
	v_lshl_add_u64 v[214:215], s[42:43], 0, v[190:191]
	s_mov_b32 m0, s23
	ds_read_b128 v[162:165], v228 offset:16384
	ds_read_b128 v[166:169], v228 offset:17408
	ds_read_b128 v[170:173], v228 offset:18432
	ds_read_b128 v[174:177], v228 offset:19456
	ds_read_b128 v[200:203], v228 offset:20480
	ds_read_b128 v[204:207], v228 offset:21504
	ds_read_b128 v[208:211], v228 offset:22528
	ds_read_b128 v[230:233], v228 offset:23552
	global_load_lds_dwordx4 v[214:215], off
	s_add_i32 m0, s23, 0x2000
	v_lshl_add_u64 v[234:235], s[42:43], 0, v[194:195]
	s_add_u32 s42, s42, s16
	s_addc_u32 s43, s43, 0
	s_add_i32 s11, s11, s41
	global_load_lds_dwordx4 v[234:235], off
	v_lshl_add_u64 v[236:237], s[42:43], 0, v[190:191]
	s_mov_b32 m0, s11
	v_lshl_add_u64 v[238:239], s[42:43], 0, v[194:195]
	global_load_lds_dwordx4 v[236:237], off
	s_add_i32 m0, s11, 0x2000
	v_lshl_add_u64 v[240:241], s[6:7], 0, v[188:189]
	global_load_lds_dwordx4 v[238:239], off
	s_mov_b32 m0, s56
	v_lshl_add_u64 v[242:243], s[6:7], 0, v[192:193]
	global_load_lds_dwordx4 v[240:241], off
	s_mov_b32 m0, s57
	s_nop 0
	global_load_lds_dwordx4 v[242:243], off
	s_waitcnt vmcnt(8)
	s_waitcnt lgkmcnt(0)
	s_barrier
; #define PG8_STAGE(bufoff, gbase, voff) do { _Pragma("unroll") for (int _i = 0; _i < 2; ++_i) \
;         __builtin_amdgcn_global_load_lds((const unsigned*)((const char*)(gbase) + (voff)[_i]), (LAS unsigned*)(lds + (bufoff) + ldsw + _i * 8192), 16, 0, 0); } while (0)
; #define PG8_LDA(dst, b, h) do { _Pragma("unroll") for (int m = 0; m < 4; ++m) _Pragma("unroll") for (int k = 0; k < 2; ++k) dst[m][k] = *(const LAS bf16x8*)(lds + PG8_SA(b, h) + aoff + m * 2048 + k * 1024); } while (0)
; #define PG8_LDB(dst, b, h) do { _Pragma("unroll") for (int n = 0; n < 2; ++n) _Pragma("unroll") for (int k = 0; k < 2; ++k) dst[n][k] = *(const LAS bf16x8*)(lds + PG8_SB(b, h) + boff + n * 2048 + k * 1024); } while (0)
; #define PG8_MMA(ai, bj, At, Bt) do { __builtin_amdgcn_s_setprio(1); _Pragma("unroll") for (int m = 0; m < 4; ++m) _Pragma("unroll") for (int n = 0; n < 2; ++n) _Pragma("unroll") for (int k = 0; k < 2; ++k) \
;         acc[ai][bj][m][n] = __builtin_amdgcn_mfma_f32_16x16x32_bf16(Bt[n][k], At[m][k], acc[ai][bj][m][n], 0, 0, 0); __builtin_amdgcn_s_setprio(0); } while (0)
; #define PG8_WAIT_V(n) asm volatile("s_waitcnt vmcnt(" #n ")" ::: "memory")
; #define PG8_WAIT_L(n) asm volatile("s_waitcnt lgkmcnt(" #n ")" ::: "memory")
; #define PG8_BAR __builtin_amdgcn_s_barrier()
; #define PG8_SCHED __builtin_amdgcn_sched_barrier(0)
;     ...
;             PG8_WAIT_V(8); PG8_WAIT_L(0); PG8_BAR; PG8_MMA(1, 0, At, B0); PG8_MMA(1, 1, At, B1); PG8_BAR; PG8_SCHED;
;             PG8_LDB(B0, 1, 0); PG8_LDB(B1, 1, 1); PG8_SCHED; PG8_LDA(At, 1, 0); PG8_STAGE(PG8_SA(0, 1), a2 + hstep, voffA);
;             PG8_WAIT_V(8); PG8_WAIT_L(0); PG8_BAR; PG8_MMA(0, 0, At, B0); PG8_MMA(0, 1, At, B1); PG8_BAR; PG8_SCHED;
	s_setprio 1
	v_mfma_f32_16x16x32_bf16 v[60:63], v[130:133], v[162:165], v[60:63]
	v_mfma_f32_16x16x32_bf16 v[56:59], v[138:141], v[162:165], v[56:59]
	v_mfma_f32_16x16x32_bf16 v[52:55], v[130:133], v[170:173], v[52:55]
	v_mfma_f32_16x16x32_bf16 v[48:51], v[138:141], v[170:173], v[48:51]
	v_mfma_f32_16x16x32_bf16 v[44:47], v[130:133], v[200:203], v[44:47]
	v_mfma_f32_16x16x32_bf16 v[40:43], v[138:141], v[200:203], v[40:43]
	v_mfma_f32_16x16x32_bf16 v[36:39], v[130:133], v[208:211], v[36:39]
	v_mfma_f32_16x16x32_bf16 v[32:35], v[138:141], v[208:211], v[32:35]
	v_mfma_f32_16x16x32_bf16 v[60:63], v[134:137], v[166:169], v[60:63]
	v_mfma_f32_16x16x32_bf16 v[56:59], v[142:145], v[166:169], v[56:59]
	v_mfma_f32_16x16x32_bf16 v[52:55], v[134:137], v[174:177], v[52:55]
	v_mfma_f32_16x16x32_bf16 v[48:51], v[142:145], v[174:177], v[48:51]
	v_mfma_f32_16x16x32_bf16 v[44:47], v[134:137], v[204:207], v[44:47]
	v_mfma_f32_16x16x32_bf16 v[40:43], v[142:145], v[204:207], v[40:43]
	v_mfma_f32_16x16x32_bf16 v[36:39], v[134:137], v[230:233], v[36:39]
	v_mfma_f32_16x16x32_bf16 v[32:35], v[142:145], v[230:233], v[32:35]
	s_setprio 0
	s_setprio 1
	v_mfma_f32_16x16x32_bf16 v[28:31], v[146:149], v[162:165], v[28:31]
	v_mfma_f32_16x16x32_bf16 v[24:27], v[154:157], v[162:165], v[24:27]
	v_mfma_f32_16x16x32_bf16 v[20:23], v[146:149], v[170:173], v[20:23]
	v_mfma_f32_16x16x32_bf16 v[16:19], v[154:157], v[170:173], v[16:19]
	v_mfma_f32_16x16x32_bf16 v[12:15], v[146:149], v[200:203], v[12:15]
	v_mfma_f32_16x16x32_bf16 v[8:11], v[154:157], v[200:203], v[8:11]
	v_mfma_f32_16x16x32_bf16 v[4:7], v[146:149], v[208:211], v[4:7]
	v_mfma_f32_16x16x32_bf16 v[0:3], v[154:157], v[208:211], v[0:3]
	v_mfma_f32_16x16x32_bf16 v[28:31], v[150:153], v[166:169], v[28:31]
	v_mfma_f32_16x16x32_bf16 v[24:27], v[158:161], v[166:169], v[24:27]
	v_mfma_f32_16x16x32_bf16 v[20:23], v[150:153], v[174:177], v[20:23]
	v_mfma_f32_16x16x32_bf16 v[16:19], v[158:161], v[174:177], v[16:19]
	v_mfma_f32_16x16x32_bf16 v[12:15], v[150:153], v[204:207], v[12:15]
	v_mfma_f32_16x16x32_bf16 v[8:11], v[158:161], v[204:207], v[8:11]
	v_mfma_f32_16x16x32_bf16 v[4:7], v[150:153], v[230:233], v[4:7]
	v_mfma_f32_16x16x32_bf16 v[0:3], v[158:161], v[230:233], v[0:3]
	s_setprio 0
	s_barrier
	s_add_i32 s11, 0, 0x18000
	s_add_i32 s23, 0, 0x1c000
	v_add_u32_e32 v142, s11, v227
	v_add_u32_e32 v158, s23, v227
	ds_read_b128 v[130:133], v142
	ds_read_b128 v[134:137], v142 offset:1024
	ds_read_b128 v[138:141], v142 offset:2048
	ds_read_b128 v[142:145], v142 offset:3072
	ds_read_b128 v[146:149], v158
	ds_read_b128 v[150:153], v158 offset:1024
	ds_read_b128 v[154:157], v158 offset:2048
	ds_read_b128 v[158:161], v158 offset:3072
	s_add_u32 s6, s6, s16
	s_addc_u32 s7, s7, 0
	s_mov_b32 m0, s60
	v_lshl_add_u64 v[244:245], s[6:7], 0, v[188:189]
	ds_read_b128 v[162:165], v228 offset:32768
	ds_read_b128 v[166:169], v228 offset:33792
	ds_read_b128 v[170:173], v228 offset:34816
	ds_read_b128 v[174:177], v228 offset:35840
	ds_read_b128 v[200:203], v228 offset:36864
	ds_read_b128 v[204:207], v228 offset:37888
	ds_read_b128 v[208:211], v228 offset:38912
	ds_read_b128 v[230:233], v228 offset:39936
	global_load_lds_dwordx4 v[244:245], off
	v_lshl_add_u64 v[244:245], s[6:7], 0, v[192:193]
	s_mov_b32 m0, s61
	s_nop 0
	global_load_lds_dwordx4 v[244:245], off
	s_waitcnt vmcnt(8)
	s_waitcnt lgkmcnt(0)
	s_barrier
	s_setprio 1
	v_mfma_f32_16x16x32_bf16 v[126:129], v[130:133], v[162:165], v[126:129]
	v_mfma_f32_16x16x32_bf16 v[122:125], v[138:141], v[162:165], v[122:125]
	v_mfma_f32_16x16x32_bf16 v[118:121], v[130:133], v[170:173], v[118:121]
	v_mfma_f32_16x16x32_bf16 v[114:117], v[138:141], v[170:173], v[114:117]
	v_mfma_f32_16x16x32_bf16 v[110:113], v[130:133], v[200:203], v[110:113]
	v_mfma_f32_16x16x32_bf16 v[106:109], v[138:141], v[200:203], v[106:109]
	v_mfma_f32_16x16x32_bf16 v[102:105], v[130:133], v[208:211], v[102:105]
	v_mfma_f32_16x16x32_bf16 v[98:101], v[138:141], v[208:211], v[98:101]
	v_mfma_f32_16x16x32_bf16 v[126:129], v[134:137], v[166:169], v[126:129]
	v_mfma_f32_16x16x32_bf16 v[122:125], v[142:145], v[166:169], v[122:125]
	v_mfma_f32_16x16x32_bf16 v[118:121], v[134:137], v[174:177], v[118:121]
	v_mfma_f32_16x16x32_bf16 v[114:117], v[142:145], v[174:177], v[114:117]
	v_mfma_f32_16x16x32_bf16 v[110:113], v[134:137], v[204:207], v[110:113]
	v_mfma_f32_16x16x32_bf16 v[106:109], v[142:145], v[204:207], v[106:109]
	v_mfma_f32_16x16x32_bf16 v[102:105], v[134:137], v[230:233], v[102:105]
	v_mfma_f32_16x16x32_bf16 v[98:101], v[142:145], v[230:233], v[98:101]
	s_setprio 0
	s_setprio 1
	v_mfma_f32_16x16x32_bf16 v[92:95], v[146:149], v[162:165], v[92:95]
	v_mfma_f32_16x16x32_bf16 v[88:91], v[154:157], v[162:165], v[88:91]
	v_mfma_f32_16x16x32_bf16 v[84:87], v[146:149], v[170:173], v[84:87]
	v_mfma_f32_16x16x32_bf16 v[80:83], v[154:157], v[170:173], v[80:83]
	v_mfma_f32_16x16x32_bf16 v[76:79], v[146:149], v[200:203], v[76:79]
	v_mfma_f32_16x16x32_bf16 v[72:75], v[154:157], v[200:203], v[72:75]
	v_mfma_f32_16x16x32_bf16 v[68:71], v[146:149], v[208:211], v[68:71]
	v_mfma_f32_16x16x32_bf16 v[64:67], v[154:157], v[208:211], v[64:67]
	v_mfma_f32_16x16x32_bf16 v[92:95], v[150:153], v[166:169], v[92:95]
	v_mfma_f32_16x16x32_bf16 v[88:91], v[158:161], v[166:169], v[88:91]
	v_mfma_f32_16x16x32_bf16 v[84:87], v[150:153], v[174:177], v[84:87]
	v_mfma_f32_16x16x32_bf16 v[80:83], v[158:161], v[174:177], v[80:83]
	v_mfma_f32_16x16x32_bf16 v[76:79], v[150:153], v[204:207], v[76:79]
	v_mfma_f32_16x16x32_bf16 v[72:75], v[158:161], v[204:207], v[72:75]
	v_mfma_f32_16x16x32_bf16 v[68:71], v[150:153], v[230:233], v[68:71]
	v_mfma_f32_16x16x32_bf16 v[64:67], v[158:161], v[230:233], v[64:67]
	s_setprio 0
	s_barrier
; #define PG8_STAGE(bufoff, gbase, voff) do { _Pragma("unroll") for (int _i = 0; _i < 2; ++_i) \
;         __builtin_amdgcn_global_load_lds((const unsigned*)((const char*)(gbase) + (voff)[_i]), (LAS unsigned*)(lds + (bufoff) + ldsw + _i * 8192), 16, 0, 0); } while (0)
; #define PG8_LDA(dst, b, h) do { _Pragma("unroll") for (int m = 0; m < 4; ++m) _Pragma("unroll") for (int k = 0; k < 2; ++k) dst[m][k] = *(const LAS bf16x8*)(lds + PG8_SA(b, h) + aoff + m * 2048 + k * 1024); } while (0)
; #define PG8_MMA(ai, bj, At, Bt) do { __builtin_amdgcn_s_setprio(1); _Pragma("unroll") for (int m = 0; m < 4; ++m) _Pragma("unroll") for (int n = 0; n < 2; ++n) _Pragma("unroll") for (int k = 0; k < 2; ++k) \
;         acc[ai][bj][m][n] = __builtin_amdgcn_mfma_f32_16x16x32_bf16(Bt[n][k], At[m][k], acc[ai][bj][m][n], 0, 0, 0); __builtin_amdgcn_s_setprio(0); } while (0)
; #define PG8_WAIT_V(n) asm volatile("s_waitcnt vmcnt(" #n ")" ::: "memory")
; #define PG8_WAIT_L(n) asm volatile("s_waitcnt lgkmcnt(" #n ")" ::: "memory")
; #define PG8_BAR __builtin_amdgcn_s_barrier()
; #define PG8_SCHED __builtin_amdgcn_sched_barrier(0)
;     ...
;             PG8_LDA(At, 1, 1); PG8_STAGE(PG8_SB(1, 0), b3, voffB); PG8_STAGE(PG8_SB(1, 1), b3 + hstep, voffB); PG8_STAGE(PG8_SA(1, 0), a3, voffA);
;             PG8_WAIT_V(8); PG8_WAIT_L(0); PG8_BAR; PG8_MMA(1, 0, At, B0); PG8_MMA(1, 1, At, B1); PG8_BAR; PG8_SCHED;
;         }
	s_add_i32 s6, s11, s41
	v_lshl_add_u64 v[214:215], v[214:215], 0, s[46:47]
	s_mov_b32 m0, s6
	ds_read_b128 v[162:165], v228 offset:49152
	ds_read_b128 v[166:169], v228 offset:50176
	ds_read_b128 v[170:173], v228 offset:51200
	ds_read_b128 v[174:177], v228 offset:52224
	ds_read_b128 v[200:203], v228 offset:53248
	ds_read_b128 v[204:207], v228 offset:54272
	ds_read_b128 v[208:211], v228 offset:55296
	ds_read_b128 v[230:233], v228 offset:56320
	global_load_lds_dwordx4 v[214:215], off
	v_lshl_add_u64 v[214:215], v[234:235], 0, s[46:47]
	s_add_i32 m0, s6, 0x2000
	s_add_i32 s6, s23, s41
	global_load_lds_dwordx4 v[214:215], off
	v_lshl_add_u64 v[214:215], v[236:237], 0, s[46:47]
	s_mov_b32 m0, s6
	s_nop 0
	global_load_lds_dwordx4 v[214:215], off
	v_lshl_add_u64 v[214:215], v[238:239], 0, s[46:47]
	s_add_i32 m0, s6, 0x2000
	s_nop 0
	global_load_lds_dwordx4 v[214:215], off
	v_lshl_add_u64 v[214:215], v[240:241], 0, s[46:47]
	s_mov_b32 m0, s62
	s_nop 0
	global_load_lds_dwordx4 v[214:215], off
	v_lshl_add_u64 v[214:215], v[242:243], 0, s[46:47]
	s_mov_b32 m0, s63
	s_nop 0
	global_load_lds_dwordx4 v[214:215], off
	s_waitcnt vmcnt(8)
	s_waitcnt lgkmcnt(0)
	s_barrier
	s_setprio 1
	v_mfma_f32_16x16x32_bf16 v[60:63], v[130:133], v[162:165], v[60:63]
	v_mfma_f32_16x16x32_bf16 v[56:59], v[138:141], v[162:165], v[56:59]
	v_mfma_f32_16x16x32_bf16 v[52:55], v[130:133], v[170:173], v[52:55]
	v_mfma_f32_16x16x32_bf16 v[48:51], v[138:141], v[170:173], v[48:51]
	v_mfma_f32_16x16x32_bf16 v[44:47], v[130:133], v[200:203], v[44:47]
	v_mfma_f32_16x16x32_bf16 v[40:43], v[138:141], v[200:203], v[40:43]
	v_mfma_f32_16x16x32_bf16 v[36:39], v[130:133], v[208:211], v[36:39]
	v_mfma_f32_16x16x32_bf16 v[32:35], v[138:141], v[208:211], v[32:35]
	v_mfma_f32_16x16x32_bf16 v[60:63], v[134:137], v[166:169], v[60:63]
	v_mfma_f32_16x16x32_bf16 v[56:59], v[142:145], v[166:169], v[56:59]
	v_mfma_f32_16x16x32_bf16 v[52:55], v[134:137], v[174:177], v[52:55]
	v_mfma_f32_16x16x32_bf16 v[48:51], v[142:145], v[174:177], v[48:51]
	v_mfma_f32_16x16x32_bf16 v[44:47], v[134:137], v[204:207], v[44:47]
	v_mfma_f32_16x16x32_bf16 v[40:43], v[142:145], v[204:207], v[40:43]
	v_mfma_f32_16x16x32_bf16 v[36:39], v[134:137], v[230:233], v[36:39]
	v_mfma_f32_16x16x32_bf16 v[32:35], v[142:145], v[230:233], v[32:35]
	s_setprio 0
	s_setprio 1
	v_mfma_f32_16x16x32_bf16 v[28:31], v[146:149], v[162:165], v[28:31]
	v_mfma_f32_16x16x32_bf16 v[24:27], v[154:157], v[162:165], v[24:27]
	v_mfma_f32_16x16x32_bf16 v[20:23], v[146:149], v[170:173], v[20:23]
	v_mfma_f32_16x16x32_bf16 v[16:19], v[154:157], v[170:173], v[16:19]
	v_mfma_f32_16x16x32_bf16 v[12:15], v[146:149], v[200:203], v[12:15]
	v_mfma_f32_16x16x32_bf16 v[8:11], v[154:157], v[200:203], v[8:11]
	v_mfma_f32_16x16x32_bf16 v[4:7], v[146:149], v[208:211], v[4:7]
	v_mfma_f32_16x16x32_bf16 v[0:3], v[154:157], v[208:211], v[0:3]
	v_mfma_f32_16x16x32_bf16 v[28:31], v[150:153], v[166:169], v[28:31]
	v_mfma_f32_16x16x32_bf16 v[24:27], v[158:161], v[166:169], v[24:27]
	v_mfma_f32_16x16x32_bf16 v[20:23], v[150:153], v[174:177], v[20:23]
	v_mfma_f32_16x16x32_bf16 v[16:19], v[158:161], v[174:177], v[16:19]
	v_mfma_f32_16x16x32_bf16 v[12:15], v[150:153], v[204:207], v[12:15]
	v_mfma_f32_16x16x32_bf16 v[8:11], v[158:161], v[204:207], v[8:11]
	v_mfma_f32_16x16x32_bf16 v[4:7], v[150:153], v[230:233], v[4:7]
	v_mfma_f32_16x16x32_bf16 v[0:3], v[158:161], v[230:233], v[0:3]
	s_setprio 0
	s_barrier
	s_add_u32 s34, s34, 0x100
	s_addc_u32 s35, s35, 0
	s_add_u32 s5, s5, 0x100
	s_addc_u32 s8, s8, 0
	s_cmp_ge_u32 s9, s70
	s_mov_b32 s6, s9
	s_cbranch_scc0 .LBB0_197

; #define PG8_STAGE(bufoff, gbase, voff) do { _Pragma("unroll") for (int _i = 0; _i < 2; ++_i) \
;         __builtin_amdgcn_global_load_lds((const unsigned*)((const char*)(gbase) + (voff)[_i]), (LAS unsigned*)(lds + (bufoff) + ldsw + _i * 8192), 16, 0, 0); } while (0)
; #define PG8_LDA(dst, b, h) do { _Pragma("unroll") for (int m = 0; m < 4; ++m) _Pragma("unroll") for (int k = 0; k < 2; ++k) dst[m][k] = *(const LAS bf16x8*)(lds + PG8_SA(b, h) + aoff + m * 2048 + k * 1024); } while (0)
; #define PG8_LDB(dst, b, h) do { _Pragma("unroll") for (int n = 0; n < 2; ++n) _Pragma("unroll") for (int k = 0; k < 2; ++k) dst[n][k] = *(const LAS bf16x8*)(lds + PG8_SB(b, h) + boff + n * 2048 + k * 1024); } while (0)
; #define PG8_MMA(ai, bj, At, Bt) do { __builtin_amdgcn_s_setprio(1); _Pragma("unroll") for (int m = 0; m < 4; ++m) _Pragma("unroll") for (int n = 0; n < 2; ++n) _Pragma("unroll") for (int k = 0; k < 2; ++k) \
;         acc[ai][bj][m][n] = __builtin_amdgcn_mfma_f32_16x16x32_bf16(Bt[n][k], At[m][k], acc[ai][bj][m][n], 0, 0, 0); __builtin_amdgcn_s_setprio(0); } while (0)
; #define PG8_WAIT_V(n) asm volatile("s_waitcnt vmcnt(" #n ")" ::: "memory")
; #define PG8_WAIT_L(n) asm volatile("s_waitcnt lgkmcnt(" #n ")" ::: "memory")
; #define PG8_BAR __builtin_amdgcn_s_barrier()
; #define PG8_SCHED __builtin_amdgcn_sched_barrier(0)
;     ...
;         for (int t = 0; t < nt; t += 2) {
;             const bool last = (t == nt - 2);
;             const char* a1 = cA + (size_t)(t + 1) * kstep;
;             const char* a2 = last ? nA : cA + (size_t)(t + 2) * kstep; const char* b2 = last ? nB : cB + (size_t)(t + 2) * kstep;
;             const char* a3 = a2 + kstep; const char* b3 = b2 + kstep;
;             PG8_LDB(B0, 0, 0); PG8_LDB(B1, 0, 1); PG8_SCHED; PG8_LDA(At, 0, 0); PG8_STAGE(PG8_SA(1, 1), a1 + hstep, voffA);
;             PG8_WAIT_V(8); PG8_WAIT_L(0); PG8_BAR; PG8_MMA(0, 0, At, B0); PG8_MMA(0, 1, At, B1); PG8_BAR; PG8_SCHED;
;             PG8_LDA(At, 0, 1); PG8_STAGE(PG8_SB(0, 0), b2, voffB); PG8_STAGE(PG8_SB(0, 1), b2 + hstep, voffB); PG8_STAGE(PG8_SA(0, 0), a2, voffA);
;             PG8_WAIT_V(8); PG8_WAIT_L(0); PG8_BAR; PG8_MMA(1, 0, At, B0); PG8_MMA(1, 1, At, B1); PG8_BAR; PG8_SCHED;
.LBB0_464:
	s_add_i32 s23, s10, 2
	s_add_u32 s30, s28, 0x80
	s_addc_u32 s11, s29, 0
	s_add_i32 s58, 0, 0x10000
	s_cmp_eq_u32 s51, s10
	s_cselect_b32 s11, s25, s11
	s_cselect_b32 s10, s24, s30
	s_cselect_b32 s31, s27, s9
	s_cselect_b32 s30, s26, s8
	s_add_i32 s59, 0, 0x14000
	v_add_u32_e32 v160, s58, v143
	v_add_u32_e32 v176, s59, v143
	ds_read_b128 v[148:151], v160
	ds_read_b128 v[152:155], v160 offset:1024
	ds_read_b128 v[156:159], v160 offset:2048
	ds_read_b128 v[160:163], v160 offset:3072
	ds_read_b128 v[164:167], v176
	ds_read_b128 v[168:171], v176 offset:1024
	ds_read_b128 v[172:175], v176 offset:2048
	ds_read_b128 v[188:191], v176 offset:3072
	v_lshl_add_u64 v[176:177], s[28:29], 0, v[138:139]
	s_add_i32 m0, s21, 0xc000
	ds_read_b128 v[192:195], v147
	ds_read_b128 v[196:199], v147 offset:1024
	ds_read_b128 v[200:203], v147 offset:2048
	ds_read_b128 v[204:207], v147 offset:3072
	ds_read_b128 v[208:211], v147 offset:4096
	ds_read_b128 v[226:229], v147 offset:5120
	ds_read_b128 v[230:233], v147 offset:6144
	ds_read_b128 v[234:237], v147 offset:7168
	global_load_lds_dwordx4 v[176:177], off
	v_lshl_add_u64 v[176:177], s[28:29], 0, v[140:141]
	s_add_i32 m0, s21, 0xe000
	s_nop 0
	global_load_lds_dwordx4 v[176:177], off
	s_waitcnt vmcnt(8)
	s_waitcnt lgkmcnt(0)
	s_barrier
	s_setprio 1
	v_mfma_f32_16x16x32_bf16 v[126:129], v[148:151], v[192:195], v[126:129]
	v_mfma_f32_16x16x32_bf16 v[122:125], v[156:159], v[192:195], v[122:125]
	v_mfma_f32_16x16x32_bf16 v[110:113], v[148:151], v[200:203], v[110:113]
	v_mfma_f32_16x16x32_bf16 v[106:109], v[156:159], v[200:203], v[106:109]
	v_mfma_f32_16x16x32_bf16 v[92:95], v[148:151], v[208:211], v[92:95]
	v_mfma_f32_16x16x32_bf16 v[88:91], v[156:159], v[208:211], v[88:91]
	v_mfma_f32_16x16x32_bf16 v[76:79], v[148:151], v[230:233], v[76:79]
	v_mfma_f32_16x16x32_bf16 v[72:75], v[156:159], v[230:233], v[72:75]
	v_mfma_f32_16x16x32_bf16 v[126:129], v[152:155], v[196:199], v[126:129]
	v_mfma_f32_16x16x32_bf16 v[122:125], v[160:163], v[196:199], v[122:125]
	v_mfma_f32_16x16x32_bf16 v[110:113], v[152:155], v[204:207], v[110:113]
	v_mfma_f32_16x16x32_bf16 v[106:109], v[160:163], v[204:207], v[106:109]
	v_mfma_f32_16x16x32_bf16 v[92:95], v[152:155], v[226:229], v[92:95]
	v_mfma_f32_16x16x32_bf16 v[88:91], v[160:163], v[226:229], v[88:91]
	v_mfma_f32_16x16x32_bf16 v[76:79], v[152:155], v[234:237], v[76:79]
	v_mfma_f32_16x16x32_bf16 v[72:75], v[160:163], v[234:237], v[72:75]
	s_setprio 0
	s_setprio 1
	v_mfma_f32_16x16x32_bf16 v[118:121], v[164:167], v[192:195], v[118:121]
	v_mfma_f32_16x16x32_bf16 v[114:117], v[172:175], v[192:195], v[114:117]
	v_mfma_f32_16x16x32_bf16 v[102:105], v[164:167], v[200:203], v[102:105]
	v_mfma_f32_16x16x32_bf16 v[98:101], v[172:175], v[200:203], v[98:101]
	v_mfma_f32_16x16x32_bf16 v[84:87], v[164:167], v[208:211], v[84:87]
	v_mfma_f32_16x16x32_bf16 v[80:83], v[172:175], v[208:211], v[80:83]
	v_mfma_f32_16x16x32_bf16 v[68:71], v[164:167], v[230:233], v[68:71]
	v_mfma_f32_16x16x32_bf16 v[64:67], v[172:175], v[230:233], v[64:67]
	v_mfma_f32_16x16x32_bf16 v[118:121], v[168:171], v[196:199], v[118:121]
	v_mfma_f32_16x16x32_bf16 v[114:117], v[188:191], v[196:199], v[114:117]
	v_mfma_f32_16x16x32_bf16 v[102:105], v[168:171], v[204:207], v[102:105]
	v_mfma_f32_16x16x32_bf16 v[98:101], v[188:191], v[204:207], v[98:101]
	v_mfma_f32_16x16x32_bf16 v[84:87], v[168:171], v[226:229], v[84:87]
	v_mfma_f32_16x16x32_bf16 v[80:83], v[188:191], v[226:229], v[80:83]
	v_mfma_f32_16x16x32_bf16 v[68:71], v[168:171], v[234:237], v[68:71]
	v_mfma_f32_16x16x32_bf16 v[64:67], v[188:191], v[234:237], v[64:67]
	s_setprio 0
	s_barrier
	s_add_i32 s58, s58, s37
	v_lshl_add_u64 v[176:177], s[30:31], 0, v[134:135]
	s_mov_b32 m0, s58
	ds_read_b128 v[192:195], v147 offset:16384
	ds_read_b128 v[196:199], v147 offset:17408
	ds_read_b128 v[200:203], v147 offset:18432
	ds_read_b128 v[204:207], v147 offset:19456
	ds_read_b128 v[208:211], v147 offset:20480
	ds_read_b128 v[226:229], v147 offset:21504
	ds_read_b128 v[230:233], v147 offset:22528
	ds_read_b128 v[234:237], v147 offset:23552
	global_load_lds_dwordx4 v[176:177], off
	s_add_i32 m0, s58, 0x2000
	v_lshl_add_u64 v[214:215], s[30:31], 0, v[130:131]
	s_add_u32 s30, s30, s16
	s_addc_u32 s31, s31, 0
	s_add_i32 s58, s59, s37
	global_load_lds_dwordx4 v[214:215], off
	v_lshl_add_u64 v[238:239], s[30:31], 0, v[134:135]
	s_mov_b32 m0, s58
	v_lshl_add_u64 v[240:241], s[30:31], 0, v[130:131]
	global_load_lds_dwordx4 v[238:239], off
	s_add_i32 m0, s58, 0x2000
	v_lshl_add_u64 v[242:243], s[10:11], 0, v[136:137]
	global_load_lds_dwordx4 v[240:241], off
	s_mov_b32 m0, s21
	v_lshl_add_u64 v[244:245], s[10:11], 0, v[132:133]
	global_load_lds_dwordx4 v[242:243], off
	s_mov_b32 m0, s38
	s_nop 0
	global_load_lds_dwordx4 v[244:245], off
	s_waitcnt vmcnt(8)
	s_waitcnt lgkmcnt(0)
	s_barrier
; #define PG8_STAGE(bufoff, gbase, voff) do { _Pragma("unroll") for (int _i = 0; _i < 2; ++_i) \
;         __builtin_amdgcn_global_load_lds((const unsigned*)((const char*)(gbase) + (voff)[_i]), (LAS unsigned*)(lds + (bufoff) + ldsw + _i * 8192), 16, 0, 0); } while (0)
; #define PG8_LDA(dst, b, h) do { _Pragma("unroll") for (int m = 0; m < 4; ++m) _Pragma("unroll") for (int k = 0; k < 2; ++k) dst[m][k] = *(const LAS bf16x8*)(lds + PG8_SA(b, h) + aoff + m * 2048 + k * 1024); } while (0)
; #define PG8_LDB(dst, b, h) do { _Pragma("unroll") for (int n = 0; n < 2; ++n) _Pragma("unroll") for (int k = 0; k < 2; ++k) dst[n][k] = *(const LAS bf16x8*)(lds + PG8_SB(b, h) + boff + n * 2048 + k * 1024); } while (0)
; #define PG8_MMA(ai, bj, At, Bt) do { __builtin_amdgcn_s_setprio(1); _Pragma("unroll") for (int m = 0; m < 4; ++m) _Pragma("unroll") for (int n = 0; n < 2; ++n) _Pragma("unroll") for (int k = 0; k < 2; ++k) \
;         acc[ai][bj][m][n] = __builtin_amdgcn_mfma_f32_16x16x32_bf16(Bt[n][k], At[m][k], acc[ai][bj][m][n], 0, 0, 0); __builtin_amdgcn_s_setprio(0); } while (0)
; #define PG8_WAIT_V(n) asm volatile("s_waitcnt vmcnt(" #n ")" ::: "memory")
; #define PG8_WAIT_L(n) asm volatile("s_waitcnt lgkmcnt(" #n ")" ::: "memory")
; #define PG8_BAR __builtin_amdgcn_s_barrier()
; #define PG8_SCHED __builtin_amdgcn_sched_barrier(0)
;     ...
;             PG8_WAIT_V(8); PG8_WAIT_L(0); PG8_BAR; PG8_MMA(1, 0, At, B0); PG8_MMA(1, 1, At, B1); PG8_BAR; PG8_SCHED;
;             PG8_LDB(B0, 1, 0); PG8_LDB(B1, 1, 1); PG8_SCHED; PG8_LDA(At, 1, 0); PG8_STAGE(PG8_SA(0, 1), a2 + hstep, voffA);
;             PG8_WAIT_V(8); PG8_WAIT_L(0); PG8_BAR; PG8_MMA(0, 0, At, B0); PG8_MMA(0, 1, At, B1); PG8_BAR; PG8_SCHED;
	s_setprio 1
	v_mfma_f32_16x16x32_bf16 v[60:63], v[148:151], v[192:195], v[60:63]
	v_mfma_f32_16x16x32_bf16 v[56:59], v[156:159], v[192:195], v[56:59]
	v_mfma_f32_16x16x32_bf16 v[44:47], v[148:151], v[200:203], v[44:47]
	v_mfma_f32_16x16x32_bf16 v[40:43], v[156:159], v[200:203], v[40:43]
	v_mfma_f32_16x16x32_bf16 v[28:31], v[148:151], v[208:211], v[28:31]
	v_mfma_f32_16x16x32_bf16 v[24:27], v[156:159], v[208:211], v[24:27]
	v_mfma_f32_16x16x32_bf16 v[12:15], v[148:151], v[230:233], v[12:15]
	v_mfma_f32_16x16x32_bf16 v[8:11], v[156:159], v[230:233], v[8:11]
	v_mfma_f32_16x16x32_bf16 v[60:63], v[152:155], v[196:199], v[60:63]
	v_mfma_f32_16x16x32_bf16 v[56:59], v[160:163], v[196:199], v[56:59]
	v_mfma_f32_16x16x32_bf16 v[44:47], v[152:155], v[204:207], v[44:47]
	v_mfma_f32_16x16x32_bf16 v[40:43], v[160:163], v[204:207], v[40:43]
	v_mfma_f32_16x16x32_bf16 v[28:31], v[152:155], v[226:229], v[28:31]
	v_mfma_f32_16x16x32_bf16 v[24:27], v[160:163], v[226:229], v[24:27]
	v_mfma_f32_16x16x32_bf16 v[12:15], v[152:155], v[234:237], v[12:15]
	v_mfma_f32_16x16x32_bf16 v[8:11], v[160:163], v[234:237], v[8:11]
	s_setprio 0
	s_setprio 1
	v_mfma_f32_16x16x32_bf16 v[52:55], v[164:167], v[192:195], v[52:55]
	v_mfma_f32_16x16x32_bf16 v[48:51], v[172:175], v[192:195], v[48:51]
	v_mfma_f32_16x16x32_bf16 v[36:39], v[164:167], v[200:203], v[36:39]
	v_mfma_f32_16x16x32_bf16 v[32:35], v[172:175], v[200:203], v[32:35]
	v_mfma_f32_16x16x32_bf16 v[20:23], v[164:167], v[208:211], v[20:23]
	v_mfma_f32_16x16x32_bf16 v[16:19], v[172:175], v[208:211], v[16:19]
	v_mfma_f32_16x16x32_bf16 v[4:7], v[164:167], v[230:233], v[4:7]
	v_mfma_f32_16x16x32_bf16 v[0:3], v[172:175], v[230:233], v[0:3]
	v_mfma_f32_16x16x32_bf16 v[52:55], v[168:171], v[196:199], v[52:55]
	v_mfma_f32_16x16x32_bf16 v[48:51], v[188:191], v[196:199], v[48:51]
	v_mfma_f32_16x16x32_bf16 v[36:39], v[168:171], v[204:207], v[36:39]
	v_mfma_f32_16x16x32_bf16 v[32:35], v[188:191], v[204:207], v[32:35]
	v_mfma_f32_16x16x32_bf16 v[20:23], v[168:171], v[226:229], v[20:23]
	v_mfma_f32_16x16x32_bf16 v[16:19], v[188:191], v[226:229], v[16:19]
	v_mfma_f32_16x16x32_bf16 v[4:7], v[168:171], v[234:237], v[4:7]
	v_mfma_f32_16x16x32_bf16 v[0:3], v[188:191], v[234:237], v[0:3]
	s_setprio 0
	s_barrier
	s_add_i32 s30, 0, 0x18000
	s_add_i32 s31, 0, 0x1c000
	v_add_u32_e32 v160, s30, v143
	v_add_u32_e32 v188, s31, v143
	ds_read_b128 v[148:151], v160
	ds_read_b128 v[152:155], v160 offset:1024
	ds_read_b128 v[156:159], v160 offset:2048
	ds_read_b128 v[160:163], v160 offset:3072
	ds_read_b128 v[164:167], v188
	ds_read_b128 v[168:171], v188 offset:1024
	ds_read_b128 v[172:175], v188 offset:2048
	ds_read_b128 v[188:191], v188 offset:3072
	s_add_u32 s10, s10, s16
	s_addc_u32 s11, s11, 0
	s_mov_b32 m0, s39
	v_lshl_add_u64 v[246:247], s[10:11], 0, v[136:137]
	ds_read_b128 v[192:195], v147 offset:32768
	ds_read_b128 v[196:199], v147 offset:33792
	ds_read_b128 v[200:203], v147 offset:34816
	ds_read_b128 v[204:207], v147 offset:35840
	ds_read_b128 v[208:211], v147 offset:36864
	ds_read_b128 v[226:229], v147 offset:37888
	ds_read_b128 v[230:233], v147 offset:38912
	ds_read_b128 v[234:237], v147 offset:39936
	global_load_lds_dwordx4 v[246:247], off
	v_lshl_add_u64 v[246:247], s[10:11], 0, v[132:133]
	s_mov_b32 m0, s40
	s_nop 0
	global_load_lds_dwordx4 v[246:247], off
	s_waitcnt vmcnt(8)
	s_waitcnt lgkmcnt(0)
	s_barrier
	s_setprio 1
	v_mfma_f32_16x16x32_bf16 v[126:129], v[148:151], v[192:195], v[126:129]
	v_mfma_f32_16x16x32_bf16 v[122:125], v[156:159], v[192:195], v[122:125]
	v_mfma_f32_16x16x32_bf16 v[110:113], v[148:151], v[200:203], v[110:113]
	v_mfma_f32_16x16x32_bf16 v[106:109], v[156:159], v[200:203], v[106:109]
	v_mfma_f32_16x16x32_bf16 v[92:95], v[148:151], v[208:211], v[92:95]
	v_mfma_f32_16x16x32_bf16 v[88:91], v[156:159], v[208:211], v[88:91]
	v_mfma_f32_16x16x32_bf16 v[76:79], v[148:151], v[230:233], v[76:79]
	v_mfma_f32_16x16x32_bf16 v[72:75], v[156:159], v[230:233], v[72:75]
	v_mfma_f32_16x16x32_bf16 v[126:129], v[152:155], v[196:199], v[126:129]
	v_mfma_f32_16x16x32_bf16 v[122:125], v[160:163], v[196:199], v[122:125]
	v_mfma_f32_16x16x32_bf16 v[110:113], v[152:155], v[204:207], v[110:113]
	v_mfma_f32_16x16x32_bf16 v[106:109], v[160:163], v[204:207], v[106:109]
	v_mfma_f32_16x16x32_bf16 v[92:95], v[152:155], v[226:229], v[92:95]
	v_mfma_f32_16x16x32_bf16 v[88:91], v[160:163], v[226:229], v[88:91]
	v_mfma_f32_16x16x32_bf16 v[76:79], v[152:155], v[234:237], v[76:79]
	v_mfma_f32_16x16x32_bf16 v[72:75], v[160:163], v[234:237], v[72:75]
	s_setprio 0
	s_setprio 1
	v_mfma_f32_16x16x32_bf16 v[118:121], v[164:167], v[192:195], v[118:121]
	v_mfma_f32_16x16x32_bf16 v[114:117], v[172:175], v[192:195], v[114:117]
	v_mfma_f32_16x16x32_bf16 v[102:105], v[164:167], v[200:203], v[102:105]
	v_mfma_f32_16x16x32_bf16 v[98:101], v[172:175], v[200:203], v[98:101]
	v_mfma_f32_16x16x32_bf16 v[84:87], v[164:167], v[208:211], v[84:87]
	v_mfma_f32_16x16x32_bf16 v[80:83], v[172:175], v[208:211], v[80:83]
	v_mfma_f32_16x16x32_bf16 v[68:71], v[164:167], v[230:233], v[68:71]
	v_mfma_f32_16x16x32_bf16 v[64:67], v[172:175], v[230:233], v[64:67]
	v_mfma_f32_16x16x32_bf16 v[118:121], v[168:171], v[196:199], v[118:121]
	v_mfma_f32_16x16x32_bf16 v[114:117], v[188:191], v[196:199], v[114:117]
	v_mfma_f32_16x16x32_bf16 v[102:105], v[168:171], v[204:207], v[102:105]
	v_mfma_f32_16x16x32_bf16 v[98:101], v[188:191], v[204:207], v[98:101]
	v_mfma_f32_16x16x32_bf16 v[84:87], v[168:171], v[226:229], v[84:87]
	v_mfma_f32_16x16x32_bf16 v[80:83], v[188:191], v[226:229], v[80:83]
	v_mfma_f32_16x16x32_bf16 v[68:71], v[168:171], v[234:237], v[68:71]
	v_mfma_f32_16x16x32_bf16 v[64:67], v[188:191], v[234:237], v[64:67]
	s_setprio 0
	s_barrier
; #define PG8_STAGE(bufoff, gbase, voff) do { _Pragma("unroll") for (int _i = 0; _i < 2; ++_i) \
;         __builtin_amdgcn_global_load_lds((const unsigned*)((const char*)(gbase) + (voff)[_i]), (LAS unsigned*)(lds + (bufoff) + ldsw + _i * 8192), 16, 0, 0); } while (0)
; #define PG8_LDA(dst, b, h) do { _Pragma("unroll") for (int m = 0; m < 4; ++m) _Pragma("unroll") for (int k = 0; k < 2; ++k) dst[m][k] = *(const LAS bf16x8*)(lds + PG8_SA(b, h) + aoff + m * 2048 + k * 1024); } while (0)
; #define PG8_MMA(ai, bj, At, Bt) do { __builtin_amdgcn_s_setprio(1); _Pragma("unroll") for (int m = 0; m < 4; ++m) _Pragma("unroll") for (int n = 0; n < 2; ++n) _Pragma("unroll") for (int k = 0; k < 2; ++k) \
;         acc[ai][bj][m][n] = __builtin_amdgcn_mfma_f32_16x16x32_bf16(Bt[n][k], At[m][k], acc[ai][bj][m][n], 0, 0, 0); __builtin_amdgcn_s_setprio(0); } while (0)
; #define PG8_WAIT_V(n) asm volatile("s_waitcnt vmcnt(" #n ")" ::: "memory")
; #define PG8_WAIT_L(n) asm volatile("s_waitcnt lgkmcnt(" #n ")" ::: "memory")
; #define PG8_BAR __builtin_amdgcn_s_barrier()
; #define PG8_SCHED __builtin_amdgcn_sched_barrier(0)
;     ...
;             PG8_LDA(At, 1, 1); PG8_STAGE(PG8_SB(1, 0), b3, voffB); PG8_STAGE(PG8_SB(1, 1), b3 + hstep, voffB); PG8_STAGE(PG8_SA(1, 0), a3, voffA);
;             PG8_WAIT_V(8); PG8_WAIT_L(0); PG8_BAR; PG8_MMA(1, 0, At, B0); PG8_MMA(1, 1, At, B1); PG8_BAR; PG8_SCHED;
;         }
	s_add_i32 s10, s30, s37
	v_lshl_add_u64 v[176:177], v[176:177], 0, s[46:47]
	s_mov_b32 m0, s10
	ds_read_b128 v[192:195], v147 offset:49152
	ds_read_b128 v[196:199], v147 offset:50176
	ds_read_b128 v[200:203], v147 offset:51200
	ds_read_b128 v[204:207], v147 offset:52224
	ds_read_b128 v[208:211], v147 offset:53248
	ds_read_b128 v[226:229], v147 offset:54272
	ds_read_b128 v[230:233], v147 offset:55296
	ds_read_b128 v[234:237], v147 offset:56320
	global_load_lds_dwordx4 v[176:177], off
	v_lshl_add_u64 v[176:177], v[214:215], 0, s[46:47]
	s_add_i32 m0, s10, 0x2000
	s_add_i32 s10, s31, s37
	global_load_lds_dwordx4 v[176:177], off
	v_lshl_add_u64 v[176:177], v[238:239], 0, s[46:47]
	s_mov_b32 m0, s10
	s_nop 0
	global_load_lds_dwordx4 v[176:177], off
	v_lshl_add_u64 v[176:177], v[240:241], 0, s[46:47]
	s_add_i32 m0, s10, 0x2000
	s_nop 0
	global_load_lds_dwordx4 v[176:177], off
	v_lshl_add_u64 v[176:177], v[242:243], 0, s[46:47]
	s_mov_b32 m0, s41
	s_nop 0
	global_load_lds_dwordx4 v[176:177], off
	v_lshl_add_u64 v[176:177], v[244:245], 0, s[46:47]
	s_mov_b32 m0, s42
	s_nop 0
	global_load_lds_dwordx4 v[176:177], off
	s_waitcnt vmcnt(8)
	s_waitcnt lgkmcnt(0)
	s_barrier
	s_setprio 1
	v_mfma_f32_16x16x32_bf16 v[60:63], v[148:151], v[192:195], v[60:63]
	v_mfma_f32_16x16x32_bf16 v[56:59], v[156:159], v[192:195], v[56:59]
	v_mfma_f32_16x16x32_bf16 v[44:47], v[148:151], v[200:203], v[44:47]
	v_mfma_f32_16x16x32_bf16 v[40:43], v[156:159], v[200:203], v[40:43]
	v_mfma_f32_16x16x32_bf16 v[28:31], v[148:151], v[208:211], v[28:31]
	v_mfma_f32_16x16x32_bf16 v[24:27], v[156:159], v[208:211], v[24:27]
	v_mfma_f32_16x16x32_bf16 v[12:15], v[148:151], v[230:233], v[12:15]
	v_mfma_f32_16x16x32_bf16 v[8:11], v[156:159], v[230:233], v[8:11]
	v_mfma_f32_16x16x32_bf16 v[60:63], v[152:155], v[196:199], v[60:63]
	v_mfma_f32_16x16x32_bf16 v[56:59], v[160:163], v[196:199], v[56:59]
	v_mfma_f32_16x16x32_bf16 v[44:47], v[152:155], v[204:207], v[44:47]
	v_mfma_f32_16x16x32_bf16 v[40:43], v[160:163], v[204:207], v[40:43]
	v_mfma_f32_16x16x32_bf16 v[28:31], v[152:155], v[226:229], v[28:31]
	v_mfma_f32_16x16x32_bf16 v[24:27], v[160:163], v[226:229], v[24:27]
	v_mfma_f32_16x16x32_bf16 v[12:15], v[152:155], v[234:237], v[12:15]
	v_mfma_f32_16x16x32_bf16 v[8:11], v[160:163], v[234:237], v[8:11]
	s_setprio 0
	s_setprio 1
	v_mfma_f32_16x16x32_bf16 v[52:55], v[164:167], v[192:195], v[52:55]
	v_mfma_f32_16x16x32_bf16 v[48:51], v[172:175], v[192:195], v[48:51]
	v_mfma_f32_16x16x32_bf16 v[36:39], v[164:167], v[200:203], v[36:39]
	v_mfma_f32_16x16x32_bf16 v[32:35], v[172:175], v[200:203], v[32:35]
	v_mfma_f32_16x16x32_bf16 v[20:23], v[164:167], v[208:211], v[20:23]
	v_mfma_f32_16x16x32_bf16 v[16:19], v[172:175], v[208:211], v[16:19]
	v_mfma_f32_16x16x32_bf16 v[4:7], v[164:167], v[230:233], v[4:7]
	v_mfma_f32_16x16x32_bf16 v[0:3], v[172:175], v[230:233], v[0:3]
	v_mfma_f32_16x16x32_bf16 v[52:55], v[168:171], v[196:199], v[52:55]
	v_mfma_f32_16x16x32_bf16 v[48:51], v[188:191], v[196:199], v[48:51]
	v_mfma_f32_16x16x32_bf16 v[36:39], v[168:171], v[204:207], v[36:39]
	v_mfma_f32_16x16x32_bf16 v[32:35], v[188:191], v[204:207], v[32:35]
	v_mfma_f32_16x16x32_bf16 v[20:23], v[168:171], v[226:229], v[20:23]
	v_mfma_f32_16x16x32_bf16 v[16:19], v[188:191], v[226:229], v[16:19]
	v_mfma_f32_16x16x32_bf16 v[4:7], v[168:171], v[234:237], v[4:7]
	v_mfma_f32_16x16x32_bf16 v[0:3], v[188:191], v[234:237], v[0:3]
	s_setprio 0
	s_barrier
	s_add_u32 s28, s28, 0x100
	s_addc_u32 s29, s29, 0
	s_add_u32 s8, s8, 0x100
	s_addc_u32 s9, s9, 0
	s_cmp_ge_u32 s23, s43
	s_mov_b32 s10, s23
	s_cbranch_scc0 .LBB0_464
	s_and_b64 vcc, exec, s[18:19]
	s_cbranch_vccz .LBB0_467

; #define PG8_STAGE(bufoff, gbase, voff) do { _Pragma("unroll") for (int _i = 0; _i < 2; ++_i) \
;         __builtin_amdgcn_global_load_lds((const unsigned*)((const char*)(gbase) + (voff)[_i]), (LAS unsigned*)(lds + (bufoff) + ldsw + _i * 8192), 16, 0, 0); } while (0)
; #define PG8_LDA(dst, b, h) do { _Pragma("unroll") for (int m = 0; m < 4; ++m) _Pragma("unroll") for (int k = 0; k < 2; ++k) dst[m][k] = *(const LAS bf16x8*)(lds + PG8_SA(b, h) + aoff + m * 2048 + k * 1024); } while (0)
; #define PG8_LDB(dst, b, h) do { _Pragma("unroll") for (int n = 0; n < 2; ++n) _Pragma("unroll") for (int k = 0; k < 2; ++k) dst[n][k] = *(const LAS bf16x8*)(lds + PG8_SB(b, h) + boff + n * 2048 + k * 1024); } while (0)
; #define PG8_MMA(ai, bj, At, Bt) do { __builtin_amdgcn_s_setprio(1); _Pragma("unroll") for (int m = 0; m < 4; ++m) _Pragma("unroll") for (int n = 0; n < 2; ++n) _Pragma("unroll") for (int k = 0; k < 2; ++k) \
;         acc[ai][bj][m][n] = __builtin_amdgcn_mfma_f32_16x16x32_bf16(Bt[n][k], At[m][k], acc[ai][bj][m][n], 0, 0, 0); __builtin_amdgcn_s_setprio(0); } while (0)
; #define PG8_WAIT_V(n) asm volatile("s_waitcnt vmcnt(" #n ")" ::: "memory")
; #define PG8_WAIT_L(n) asm volatile("s_waitcnt lgkmcnt(" #n ")" ::: "memory")
; #define PG8_BAR __builtin_amdgcn_s_barrier()
; #define PG8_SCHED __builtin_amdgcn_sched_barrier(0)
;     ...
;         for (int t = 0; t < nt; t += 2) {
;             const bool last = (t == nt - 2);
;             const char* a1 = cA + (size_t)(t + 1) * kstep;
;             const char* a2 = last ? nA : cA + (size_t)(t + 2) * kstep; const char* b2 = last ? nB : cB + (size_t)(t + 2) * kstep;
;             const char* a3 = a2 + kstep; const char* b3 = b2 + kstep;
;             PG8_LDB(B0, 0, 0); PG8_LDB(B1, 0, 1); PG8_SCHED; PG8_LDA(At, 0, 0); PG8_STAGE(PG8_SA(1, 1), a1 + hstep, voffA);
;             PG8_WAIT_V(8); PG8_WAIT_L(0); PG8_BAR; PG8_MMA(0, 0, At, B0); PG8_MMA(0, 1, At, B1); PG8_BAR; PG8_SCHED;
;             PG8_LDA(At, 0, 1); PG8_STAGE(PG8_SB(0, 0), b2, voffB); PG8_STAGE(PG8_SB(0, 1), b2 + hstep, voffB); PG8_STAGE(PG8_SA(0, 0), a2, voffA);
;             PG8_WAIT_V(8); PG8_WAIT_L(0); PG8_BAR; PG8_MMA(1, 0, At, B0); PG8_MMA(1, 1, At, B1); PG8_BAR; PG8_SCHED;
.LBB0_483:
	s_add_i32 s16, s8, 2
	s_or_b32 s56, s8, 1
	s_lshl_b64 s[10:11], s[16:17], 7
	s_add_u32 s9, s28, s10
	s_addc_u32 s21, s29, s11
	s_cmp_eq_u32 s8, s51
	s_cselect_b32 s10, 0, s10
	s_cselect_b32 s8, 0, s11
	s_cselect_b32 s30, s22, s9
	s_cselect_b32 s31, s23, s21
	s_add_u32 s10, s2, s10
	s_addc_u32 s11, s3, s8
	s_add_i32 s21, 0, 0x10000
	s_add_i32 s58, 0, 0x14000
	v_add_u32_e32 v156, s21, v139
	v_add_u32_e32 v172, s58, v139
	ds_read_b128 v[144:147], v156
	ds_read_b128 v[148:151], v156 offset:1024
	ds_read_b128 v[152:155], v156 offset:2048
	ds_read_b128 v[156:159], v156 offset:3072
	ds_read_b128 v[160:163], v172
	ds_read_b128 v[164:167], v172 offset:1024
	ds_read_b128 v[168:171], v172 offset:2048
	ds_read_b128 v[172:175], v172 offset:3072
	s_mov_b32 s57, s17
	s_lshl_b64 s[8:9], s[56:57], 7
	s_add_u32 s8, s4, s8
	s_addc_u32 s9, s5, s9
	v_lshl_add_u64 v[176:177], s[8:9], 0, v[136:137]
	s_add_i32 m0, s27, 0xc000
	ds_read_b128 v[188:191], v143
	ds_read_b128 v[192:195], v143 offset:1024
	ds_read_b128 v[196:199], v143 offset:2048
	ds_read_b128 v[200:203], v143 offset:3072
	ds_read_b128 v[204:207], v143 offset:4096
	ds_read_b128 v[208:211], v143 offset:5120
	ds_read_b128 v[226:229], v143 offset:6144
	ds_read_b128 v[230:233], v143 offset:7168
	global_load_lds_dwordx4 v[176:177], off
	v_lshl_add_u64 v[176:177], s[8:9], 0, v[132:133]
	s_add_i32 m0, s27, 0xe000
	s_nop 0
	global_load_lds_dwordx4 v[176:177], off
	s_waitcnt vmcnt(8)
	s_waitcnt lgkmcnt(0)
	s_barrier
	s_setprio 1
	v_mfma_f32_16x16x32_bf16 v[126:129], v[144:147], v[188:191], v[126:129]
	v_mfma_f32_16x16x32_bf16 v[122:125], v[152:155], v[188:191], v[122:125]
	v_mfma_f32_16x16x32_bf16 v[110:113], v[144:147], v[196:199], v[110:113]
	v_mfma_f32_16x16x32_bf16 v[106:109], v[152:155], v[196:199], v[106:109]
	v_mfma_f32_16x16x32_bf16 v[92:95], v[144:147], v[204:207], v[92:95]
	v_mfma_f32_16x16x32_bf16 v[88:91], v[152:155], v[204:207], v[88:91]
	v_mfma_f32_16x16x32_bf16 v[76:79], v[144:147], v[226:229], v[76:79]
	v_mfma_f32_16x16x32_bf16 v[72:75], v[152:155], v[226:229], v[72:75]
	v_mfma_f32_16x16x32_bf16 v[126:129], v[148:151], v[192:195], v[126:129]
	v_mfma_f32_16x16x32_bf16 v[122:125], v[156:159], v[192:195], v[122:125]
	v_mfma_f32_16x16x32_bf16 v[110:113], v[148:151], v[200:203], v[110:113]
	v_mfma_f32_16x16x32_bf16 v[106:109], v[156:159], v[200:203], v[106:109]
	v_mfma_f32_16x16x32_bf16 v[92:95], v[148:151], v[208:211], v[92:95]
	v_mfma_f32_16x16x32_bf16 v[88:91], v[156:159], v[208:211], v[88:91]
	v_mfma_f32_16x16x32_bf16 v[76:79], v[148:151], v[230:233], v[76:79]
	v_mfma_f32_16x16x32_bf16 v[72:75], v[156:159], v[230:233], v[72:75]
	s_setprio 0
	s_setprio 1
	v_mfma_f32_16x16x32_bf16 v[118:121], v[160:163], v[188:191], v[118:121]
	v_mfma_f32_16x16x32_bf16 v[114:117], v[168:171], v[188:191], v[114:117]
	v_mfma_f32_16x16x32_bf16 v[102:105], v[160:163], v[196:199], v[102:105]
	v_mfma_f32_16x16x32_bf16 v[98:101], v[168:171], v[196:199], v[98:101]
	v_mfma_f32_16x16x32_bf16 v[84:87], v[160:163], v[204:207], v[84:87]
	v_mfma_f32_16x16x32_bf16 v[80:83], v[168:171], v[204:207], v[80:83]
	v_mfma_f32_16x16x32_bf16 v[68:71], v[160:163], v[226:229], v[68:71]
	v_mfma_f32_16x16x32_bf16 v[64:67], v[168:171], v[226:229], v[64:67]
	v_mfma_f32_16x16x32_bf16 v[118:121], v[164:167], v[192:195], v[118:121]
	v_mfma_f32_16x16x32_bf16 v[114:117], v[172:175], v[192:195], v[114:117]
	v_mfma_f32_16x16x32_bf16 v[102:105], v[164:167], v[200:203], v[102:105]
	v_mfma_f32_16x16x32_bf16 v[98:101], v[172:175], v[200:203], v[98:101]
	v_mfma_f32_16x16x32_bf16 v[84:87], v[164:167], v[208:211], v[84:87]
	v_mfma_f32_16x16x32_bf16 v[80:83], v[172:175], v[208:211], v[80:83]
	v_mfma_f32_16x16x32_bf16 v[68:71], v[164:167], v[230:233], v[68:71]
	v_mfma_f32_16x16x32_bf16 v[64:67], v[172:175], v[230:233], v[64:67]
	s_setprio 0
	s_barrier
	s_add_i32 s8, s21, s37
	v_lshl_add_u64 v[176:177], s[30:31], 0, v[134:135]
	s_mov_b32 m0, s8
	ds_read_b128 v[188:191], v143 offset:16384
	ds_read_b128 v[192:195], v143 offset:17408
	ds_read_b128 v[196:199], v143 offset:18432
	ds_read_b128 v[200:203], v143 offset:19456
	ds_read_b128 v[204:207], v143 offset:20480
	ds_read_b128 v[208:211], v143 offset:21504
	ds_read_b128 v[226:229], v143 offset:22528
	ds_read_b128 v[230:233], v143 offset:23552
	global_load_lds_dwordx4 v[176:177], off
	s_add_i32 m0, s8, 0x2000
	s_add_u32 s8, s30, s36
	v_lshl_add_u64 v[214:215], s[30:31], 0, v[130:131]
	s_addc_u32 s9, s31, 0
	s_add_i32 s21, s58, s37
	global_load_lds_dwordx4 v[214:215], off
	v_lshl_add_u64 v[234:235], s[8:9], 0, v[134:135]
	s_mov_b32 m0, s21
	v_lshl_add_u64 v[236:237], s[8:9], 0, v[130:131]
	global_load_lds_dwordx4 v[234:235], off
	s_add_i32 m0, s21, 0x2000
	v_lshl_add_u64 v[238:239], s[10:11], 0, v[136:137]
	global_load_lds_dwordx4 v[236:237], off
	s_mov_b32 m0, s27
	v_lshl_add_u64 v[240:241], s[10:11], 0, v[132:133]
	global_load_lds_dwordx4 v[238:239], off
	s_mov_b32 m0, s38
	s_nop 0
	global_load_lds_dwordx4 v[240:241], off
	s_waitcnt vmcnt(8)
	s_waitcnt lgkmcnt(0)
	s_barrier
; #define PG8_STAGE(bufoff, gbase, voff) do { _Pragma("unroll") for (int _i = 0; _i < 2; ++_i) \
;         __builtin_amdgcn_global_load_lds((const unsigned*)((const char*)(gbase) + (voff)[_i]), (LAS unsigned*)(lds + (bufoff) + ldsw + _i * 8192), 16, 0, 0); } while (0)
; #define PG8_LDA(dst, b, h) do { _Pragma("unroll") for (int m = 0; m < 4; ++m) _Pragma("unroll") for (int k = 0; k < 2; ++k) dst[m][k] = *(const LAS bf16x8*)(lds + PG8_SA(b, h) + aoff + m * 2048 + k * 1024); } while (0)
; #define PG8_LDB(dst, b, h) do { _Pragma("unroll") for (int n = 0; n < 2; ++n) _Pragma("unroll") for (int k = 0; k < 2; ++k) dst[n][k] = *(const LAS bf16x8*)(lds + PG8_SB(b, h) + boff + n * 2048 + k * 1024); } while (0)
; #define PG8_MMA(ai, bj, At, Bt) do { __builtin_amdgcn_s_setprio(1); _Pragma("unroll") for (int m = 0; m < 4; ++m) _Pragma("unroll") for (int n = 0; n < 2; ++n) _Pragma("unroll") for (int k = 0; k < 2; ++k) \
;         acc[ai][bj][m][n] = __builtin_amdgcn_mfma_f32_16x16x32_bf16(Bt[n][k], At[m][k], acc[ai][bj][m][n], 0, 0, 0); __builtin_amdgcn_s_setprio(0); } while (0)
; #define PG8_WAIT_V(n) asm volatile("s_waitcnt vmcnt(" #n ")" ::: "memory")
; #define PG8_WAIT_L(n) asm volatile("s_waitcnt lgkmcnt(" #n ")" ::: "memory")
; #define PG8_BAR __builtin_amdgcn_s_barrier()
; #define PG8_SCHED __builtin_amdgcn_sched_barrier(0)
;     ...
;             PG8_WAIT_V(8); PG8_WAIT_L(0); PG8_BAR; PG8_MMA(1, 0, At, B0); PG8_MMA(1, 1, At, B1); PG8_BAR; PG8_SCHED;
;             PG8_LDB(B0, 1, 0); PG8_LDB(B1, 1, 1); PG8_SCHED; PG8_LDA(At, 1, 0); PG8_STAGE(PG8_SA(0, 1), a2 + hstep, voffA);
;             PG8_WAIT_V(8); PG8_WAIT_L(0); PG8_BAR; PG8_MMA(0, 0, At, B0); PG8_MMA(0, 1, At, B1); PG8_BAR; PG8_SCHED;
	s_setprio 1
	v_mfma_f32_16x16x32_bf16 v[60:63], v[144:147], v[188:191], v[60:63]
	v_mfma_f32_16x16x32_bf16 v[56:59], v[152:155], v[188:191], v[56:59]
	v_mfma_f32_16x16x32_bf16 v[44:47], v[144:147], v[196:199], v[44:47]
	v_mfma_f32_16x16x32_bf16 v[40:43], v[152:155], v[196:199], v[40:43]
	v_mfma_f32_16x16x32_bf16 v[28:31], v[144:147], v[204:207], v[28:31]
	v_mfma_f32_16x16x32_bf16 v[24:27], v[152:155], v[204:207], v[24:27]
	v_mfma_f32_16x16x32_bf16 v[12:15], v[144:147], v[226:229], v[12:15]
	v_mfma_f32_16x16x32_bf16 v[8:11], v[152:155], v[226:229], v[8:11]
	v_mfma_f32_16x16x32_bf16 v[60:63], v[148:151], v[192:195], v[60:63]
	v_mfma_f32_16x16x32_bf16 v[56:59], v[156:159], v[192:195], v[56:59]
	v_mfma_f32_16x16x32_bf16 v[44:47], v[148:151], v[200:203], v[44:47]
	v_mfma_f32_16x16x32_bf16 v[40:43], v[156:159], v[200:203], v[40:43]
	v_mfma_f32_16x16x32_bf16 v[28:31], v[148:151], v[208:211], v[28:31]
	v_mfma_f32_16x16x32_bf16 v[24:27], v[156:159], v[208:211], v[24:27]
	v_mfma_f32_16x16x32_bf16 v[12:15], v[148:151], v[230:233], v[12:15]
	v_mfma_f32_16x16x32_bf16 v[8:11], v[156:159], v[230:233], v[8:11]
	s_setprio 0
	s_setprio 1
	v_mfma_f32_16x16x32_bf16 v[52:55], v[160:163], v[188:191], v[52:55]
	v_mfma_f32_16x16x32_bf16 v[48:51], v[168:171], v[188:191], v[48:51]
	v_mfma_f32_16x16x32_bf16 v[36:39], v[160:163], v[196:199], v[36:39]
	v_mfma_f32_16x16x32_bf16 v[32:35], v[168:171], v[196:199], v[32:35]
	v_mfma_f32_16x16x32_bf16 v[20:23], v[160:163], v[204:207], v[20:23]
	v_mfma_f32_16x16x32_bf16 v[16:19], v[168:171], v[204:207], v[16:19]
	v_mfma_f32_16x16x32_bf16 v[4:7], v[160:163], v[226:229], v[4:7]
	v_mfma_f32_16x16x32_bf16 v[0:3], v[168:171], v[226:229], v[0:3]
	v_mfma_f32_16x16x32_bf16 v[52:55], v[164:167], v[192:195], v[52:55]
	v_mfma_f32_16x16x32_bf16 v[48:51], v[172:175], v[192:195], v[48:51]
	v_mfma_f32_16x16x32_bf16 v[36:39], v[164:167], v[200:203], v[36:39]
	v_mfma_f32_16x16x32_bf16 v[32:35], v[172:175], v[200:203], v[32:35]
	v_mfma_f32_16x16x32_bf16 v[20:23], v[164:167], v[208:211], v[20:23]
	v_mfma_f32_16x16x32_bf16 v[16:19], v[172:175], v[208:211], v[16:19]
	v_mfma_f32_16x16x32_bf16 v[4:7], v[164:167], v[230:233], v[4:7]
	v_mfma_f32_16x16x32_bf16 v[0:3], v[172:175], v[230:233], v[0:3]
	s_setprio 0
	s_barrier
	s_add_i32 s21, 0, 0x18000
	s_add_i32 s30, 0, 0x1c000
	v_add_u32_e32 v156, s21, v139
	v_add_u32_e32 v172, s30, v139
	ds_read_b128 v[144:147], v156
	ds_read_b128 v[148:151], v156 offset:1024
	ds_read_b128 v[152:155], v156 offset:2048
	ds_read_b128 v[156:159], v156 offset:3072
	ds_read_b128 v[160:163], v172
	ds_read_b128 v[164:167], v172 offset:1024
	ds_read_b128 v[168:171], v172 offset:2048
	ds_read_b128 v[172:175], v172 offset:3072
	s_add_u32 s8, s10, s36
	s_addc_u32 s9, s11, 0
	s_mov_b32 m0, s39
	v_lshl_add_u64 v[242:243], s[8:9], 0, v[136:137]
	ds_read_b128 v[188:191], v143 offset:32768
	ds_read_b128 v[192:195], v143 offset:33792
	ds_read_b128 v[196:199], v143 offset:34816
	ds_read_b128 v[200:203], v143 offset:35840
	ds_read_b128 v[204:207], v143 offset:36864
	ds_read_b128 v[208:211], v143 offset:37888
	ds_read_b128 v[226:229], v143 offset:38912
	ds_read_b128 v[230:233], v143 offset:39936
	global_load_lds_dwordx4 v[242:243], off
	v_lshl_add_u64 v[242:243], s[8:9], 0, v[132:133]
	s_mov_b32 m0, s40
	s_nop 0
	global_load_lds_dwordx4 v[242:243], off
	s_waitcnt vmcnt(8)
	s_waitcnt lgkmcnt(0)
	s_barrier
	s_setprio 1
	v_mfma_f32_16x16x32_bf16 v[126:129], v[144:147], v[188:191], v[126:129]
	v_mfma_f32_16x16x32_bf16 v[122:125], v[152:155], v[188:191], v[122:125]
	v_mfma_f32_16x16x32_bf16 v[110:113], v[144:147], v[196:199], v[110:113]
	v_mfma_f32_16x16x32_bf16 v[106:109], v[152:155], v[196:199], v[106:109]
	v_mfma_f32_16x16x32_bf16 v[92:95], v[144:147], v[204:207], v[92:95]
	v_mfma_f32_16x16x32_bf16 v[88:91], v[152:155], v[204:207], v[88:91]
	v_mfma_f32_16x16x32_bf16 v[76:79], v[144:147], v[226:229], v[76:79]
	v_mfma_f32_16x16x32_bf16 v[72:75], v[152:155], v[226:229], v[72:75]
	v_mfma_f32_16x16x32_bf16 v[126:129], v[148:151], v[192:195], v[126:129]
	v_mfma_f32_16x16x32_bf16 v[122:125], v[156:159], v[192:195], v[122:125]
	v_mfma_f32_16x16x32_bf16 v[110:113], v[148:151], v[200:203], v[110:113]
	v_mfma_f32_16x16x32_bf16 v[106:109], v[156:159], v[200:203], v[106:109]
	v_mfma_f32_16x16x32_bf16 v[92:95], v[148:151], v[208:211], v[92:95]
	v_mfma_f32_16x16x32_bf16 v[88:91], v[156:159], v[208:211], v[88:91]
	v_mfma_f32_16x16x32_bf16 v[76:79], v[148:151], v[230:233], v[76:79]
	v_mfma_f32_16x16x32_bf16 v[72:75], v[156:159], v[230:233], v[72:75]
	s_setprio 0
	s_setprio 1
	v_mfma_f32_16x16x32_bf16 v[118:121], v[160:163], v[188:191], v[118:121]
	v_mfma_f32_16x16x32_bf16 v[114:117], v[168:171], v[188:191], v[114:117]
	v_mfma_f32_16x16x32_bf16 v[102:105], v[160:163], v[196:199], v[102:105]
	v_mfma_f32_16x16x32_bf16 v[98:101], v[168:171], v[196:199], v[98:101]
	v_mfma_f32_16x16x32_bf16 v[84:87], v[160:163], v[204:207], v[84:87]
	v_mfma_f32_16x16x32_bf16 v[80:83], v[168:171], v[204:207], v[80:83]
	v_mfma_f32_16x16x32_bf16 v[68:71], v[160:163], v[226:229], v[68:71]
	v_mfma_f32_16x16x32_bf16 v[64:67], v[168:171], v[226:229], v[64:67]
	v_mfma_f32_16x16x32_bf16 v[118:121], v[164:167], v[192:195], v[118:121]
	v_mfma_f32_16x16x32_bf16 v[114:117], v[172:175], v[192:195], v[114:117]
	v_mfma_f32_16x16x32_bf16 v[102:105], v[164:167], v[200:203], v[102:105]
	v_mfma_f32_16x16x32_bf16 v[98:101], v[172:175], v[200:203], v[98:101]
	v_mfma_f32_16x16x32_bf16 v[84:87], v[164:167], v[208:211], v[84:87]
	v_mfma_f32_16x16x32_bf16 v[80:83], v[172:175], v[208:211], v[80:83]
	v_mfma_f32_16x16x32_bf16 v[68:71], v[164:167], v[230:233], v[68:71]
	v_mfma_f32_16x16x32_bf16 v[64:67], v[172:175], v[230:233], v[64:67]
	s_setprio 0
	s_barrier
; #define PG8_STAGE(bufoff, gbase, voff) do { _Pragma("unroll") for (int _i = 0; _i < 2; ++_i) \
;         __builtin_amdgcn_global_load_lds((const unsigned*)((const char*)(gbase) + (voff)[_i]), (LAS unsigned*)(lds + (bufoff) + ldsw + _i * 8192), 16, 0, 0); } while (0)
; #define PG8_LDA(dst, b, h) do { _Pragma("unroll") for (int m = 0; m < 4; ++m) _Pragma("unroll") for (int k = 0; k < 2; ++k) dst[m][k] = *(const LAS bf16x8*)(lds + PG8_SA(b, h) + aoff + m * 2048 + k * 1024); } while (0)
; #define PG8_MMA(ai, bj, At, Bt) do { __builtin_amdgcn_s_setprio(1); _Pragma("unroll") for (int m = 0; m < 4; ++m) _Pragma("unroll") for (int n = 0; n < 2; ++n) _Pragma("unroll") for (int k = 0; k < 2; ++k) \
;         acc[ai][bj][m][n] = __builtin_amdgcn_mfma_f32_16x16x32_bf16(Bt[n][k], At[m][k], acc[ai][bj][m][n], 0, 0, 0); __builtin_amdgcn_s_setprio(0); } while (0)
; #define PG8_WAIT_V(n) asm volatile("s_waitcnt vmcnt(" #n ")" ::: "memory")
; #define PG8_WAIT_L(n) asm volatile("s_waitcnt lgkmcnt(" #n ")" ::: "memory")
; #define PG8_BAR __builtin_amdgcn_s_barrier()
; #define PG8_SCHED __builtin_amdgcn_sched_barrier(0)
;     ...
;             PG8_LDA(At, 1, 1); PG8_STAGE(PG8_SB(1, 0), b3, voffB); PG8_STAGE(PG8_SB(1, 1), b3 + hstep, voffB); PG8_STAGE(PG8_SA(1, 0), a3, voffA);
;             PG8_WAIT_V(8); PG8_WAIT_L(0); PG8_BAR; PG8_MMA(1, 0, At, B0); PG8_MMA(1, 1, At, B1); PG8_BAR; PG8_SCHED;
;         }
	s_add_i32 s8, s21, s37
	v_lshl_add_u64 v[176:177], v[176:177], 0, s[46:47]
	s_mov_b32 m0, s8
	ds_read_b128 v[188:191], v143 offset:49152
	ds_read_b128 v[192:195], v143 offset:50176
	ds_read_b128 v[196:199], v143 offset:51200
	ds_read_b128 v[200:203], v143 offset:52224
	ds_read_b128 v[204:207], v143 offset:53248
	ds_read_b128 v[208:211], v143 offset:54272
	ds_read_b128 v[226:229], v143 offset:55296
	ds_read_b128 v[230:233], v143 offset:56320
	global_load_lds_dwordx4 v[176:177], off
	v_lshl_add_u64 v[176:177], v[214:215], 0, s[46:47]
	s_add_i32 m0, s8, 0x2000
	s_add_i32 s8, s30, s37
	global_load_lds_dwordx4 v[176:177], off
	v_lshl_add_u64 v[176:177], v[234:235], 0, s[46:47]
	s_mov_b32 m0, s8
	s_nop 0
	global_load_lds_dwordx4 v[176:177], off
	v_lshl_add_u64 v[176:177], v[236:237], 0, s[46:47]
	s_add_i32 m0, s8, 0x2000
	s_nop 0
	global_load_lds_dwordx4 v[176:177], off
	v_lshl_add_u64 v[176:177], v[238:239], 0, s[46:47]
	s_mov_b32 m0, s42
	s_nop 0
	global_load_lds_dwordx4 v[176:177], off
	v_lshl_add_u64 v[176:177], v[240:241], 0, s[46:47]
	s_mov_b32 m0, s43
	s_nop 0
	global_load_lds_dwordx4 v[176:177], off
	s_waitcnt vmcnt(8)
	s_waitcnt lgkmcnt(0)
	s_barrier
	s_setprio 1
	v_mfma_f32_16x16x32_bf16 v[60:63], v[144:147], v[188:191], v[60:63]
	v_mfma_f32_16x16x32_bf16 v[56:59], v[152:155], v[188:191], v[56:59]
	v_mfma_f32_16x16x32_bf16 v[44:47], v[144:147], v[196:199], v[44:47]
	v_mfma_f32_16x16x32_bf16 v[40:43], v[152:155], v[196:199], v[40:43]
	v_mfma_f32_16x16x32_bf16 v[28:31], v[144:147], v[204:207], v[28:31]
	v_mfma_f32_16x16x32_bf16 v[24:27], v[152:155], v[204:207], v[24:27]
	v_mfma_f32_16x16x32_bf16 v[12:15], v[144:147], v[226:229], v[12:15]
	v_mfma_f32_16x16x32_bf16 v[8:11], v[152:155], v[226:229], v[8:11]
	v_mfma_f32_16x16x32_bf16 v[60:63], v[148:151], v[192:195], v[60:63]
	v_mfma_f32_16x16x32_bf16 v[56:59], v[156:159], v[192:195], v[56:59]
	v_mfma_f32_16x16x32_bf16 v[44:47], v[148:151], v[200:203], v[44:47]
	v_mfma_f32_16x16x32_bf16 v[40:43], v[156:159], v[200:203], v[40:43]
	v_mfma_f32_16x16x32_bf16 v[28:31], v[148:151], v[208:211], v[28:31]
	v_mfma_f32_16x16x32_bf16 v[24:27], v[156:159], v[208:211], v[24:27]
	v_mfma_f32_16x16x32_bf16 v[12:15], v[148:151], v[230:233], v[12:15]
	v_mfma_f32_16x16x32_bf16 v[8:11], v[156:159], v[230:233], v[8:11]
	s_setprio 0
	s_setprio 1
	v_mfma_f32_16x16x32_bf16 v[52:55], v[160:163], v[188:191], v[52:55]
	v_mfma_f32_16x16x32_bf16 v[48:51], v[168:171], v[188:191], v[48:51]
	v_mfma_f32_16x16x32_bf16 v[36:39], v[160:163], v[196:199], v[36:39]
	v_mfma_f32_16x16x32_bf16 v[32:35], v[168:171], v[196:199], v[32:35]
	v_mfma_f32_16x16x32_bf16 v[20:23], v[160:163], v[204:207], v[20:23]
	v_mfma_f32_16x16x32_bf16 v[16:19], v[168:171], v[204:207], v[16:19]
	v_mfma_f32_16x16x32_bf16 v[4:7], v[160:163], v[226:229], v[4:7]
	v_mfma_f32_16x16x32_bf16 v[0:3], v[168:171], v[226:229], v[0:3]
	v_mfma_f32_16x16x32_bf16 v[52:55], v[164:167], v[192:195], v[52:55]
	v_mfma_f32_16x16x32_bf16 v[48:51], v[172:175], v[192:195], v[48:51]
	v_mfma_f32_16x16x32_bf16 v[36:39], v[164:167], v[200:203], v[36:39]
	v_mfma_f32_16x16x32_bf16 v[32:35], v[172:175], v[200:203], v[32:35]
	v_mfma_f32_16x16x32_bf16 v[20:23], v[164:167], v[208:211], v[20:23]
	v_mfma_f32_16x16x32_bf16 v[16:19], v[172:175], v[208:211], v[16:19]
	v_mfma_f32_16x16x32_bf16 v[4:7], v[164:167], v[230:233], v[4:7]
	v_mfma_f32_16x16x32_bf16 v[0:3], v[172:175], v[230:233], v[0:3]
	s_setprio 0
	s_barrier
	s_cmp_ge_u32 s16, s41
	s_mov_b32 s8, s16
	s_cbranch_scc0 .LBB0_483
	s_mov_b32 s31, 0x26000
	s_movk_i32 s30, 0x1f8
	s_and_b64 vcc, exec, s[18:19]
	s_cbranch_vccz .LBB0_486

; #define PG8_STAGE(bufoff, gbase, voff) do { _Pragma("unroll") for (int _i = 0; _i < 2; ++_i) \
;         __builtin_amdgcn_global_load_lds((const unsigned*)((const char*)(gbase) + (voff)[_i]), (LAS unsigned*)(lds + (bufoff) + ldsw + _i * 8192), 16, 0, 0); } while (0)
; #define PG8_LDA(dst, b, h) do { _Pragma("unroll") for (int m = 0; m < 4; ++m) _Pragma("unroll") for (int k = 0; k < 2; ++k) dst[m][k] = *(const LAS bf16x8*)(lds + PG8_SA(b, h) + aoff + m * 2048 + k * 1024); } while (0)
; #define PG8_LDB(dst, b, h) do { _Pragma("unroll") for (int n = 0; n < 2; ++n) _Pragma("unroll") for (int k = 0; k < 2; ++k) dst[n][k] = *(const LAS bf16x8*)(lds + PG8_SB(b, h) + boff + n * 2048 + k * 1024); } while (0)
; #define PG8_MMA(ai, bj, At, Bt) do { __builtin_amdgcn_s_setprio(1); _Pragma("unroll") for (int m = 0; m < 4; ++m) _Pragma("unroll") for (int n = 0; n < 2; ++n) _Pragma("unroll") for (int k = 0; k < 2; ++k) \
;         acc[ai][bj][m][n] = __builtin_amdgcn_mfma_f32_16x16x32_bf16(Bt[n][k], At[m][k], acc[ai][bj][m][n], 0, 0, 0); __builtin_amdgcn_s_setprio(0); } while (0)
; #define PG8_WAIT_V(n) asm volatile("s_waitcnt vmcnt(" #n ")" ::: "memory")
; #define PG8_WAIT_L(n) asm volatile("s_waitcnt lgkmcnt(" #n ")" ::: "memory")
; #define PG8_BAR __builtin_amdgcn_s_barrier()
; #define PG8_SCHED __builtin_amdgcn_sched_barrier(0)
;     ...
;         for (int t = 0; t < nt; t += 2) {
;             const bool last = (t == nt - 2);
;             const char* a1 = cA + (size_t)(t + 1) * kstep;
;             const char* a2 = last ? nA : cA + (size_t)(t + 2) * kstep; const char* b2 = last ? nB : cB + (size_t)(t + 2) * kstep;
;             const char* a3 = a2 + kstep; const char* b3 = b2 + kstep;
;             PG8_LDB(B0, 0, 0); PG8_LDB(B1, 0, 1); PG8_SCHED; PG8_LDA(At, 0, 0); PG8_STAGE(PG8_SA(1, 1), a1 + hstep, voffA);
;             PG8_WAIT_V(8); PG8_WAIT_L(0); PG8_BAR; PG8_MMA(0, 0, At, B0); PG8_MMA(0, 1, At, B1); PG8_BAR; PG8_SCHED;
;             PG8_LDA(At, 0, 1); PG8_STAGE(PG8_SB(0, 0), b2, voffB); PG8_STAGE(PG8_SB(0, 1), b2 + hstep, voffB); PG8_STAGE(PG8_SA(0, 0), a2, voffA);
;             PG8_WAIT_V(8); PG8_WAIT_L(0); PG8_BAR; PG8_MMA(1, 0, At, B0); PG8_MMA(1, 1, At, B1); PG8_BAR; PG8_SCHED;
.LBB0_587:
	s_add_i32 s12, s8, 2
	s_add_u32 s13, s6, 0x80
	s_addc_u32 s9, s7, 0
	s_add_i32 s21, 0, 0x10000
	s_cmp_eq_u32 s97, s8
	s_cselect_b32 s9, s61, s9
	s_cselect_b32 s8, s60, s13
	v_add_u32_e32 v96, s21, v175
	s_cselect_b32 s35, s63, s11
	s_cselect_b32 s34, s62, s10
	s_add_i32 s13, 0, 0x14000
	s_waitcnt lgkmcnt(0)
	ds_read_b128 v[132:135], v96
	ds_read_b128 v[136:139], v96 offset:1024
	ds_read_b128 v[140:143], v96 offset:2048
	ds_read_b128 v[144:147], v96 offset:3072
	v_add_u32_e32 v96, s13, v175
	ds_read_b128 v[148:151], v96
	ds_read_b128 v[152:155], v96 offset:1024
	ds_read_b128 v[156:159], v96 offset:2048
	ds_read_b128 v[160:163], v96 offset:3072
	v_lshl_add_u64 v[98:99], s[6:7], 0, v[188:189]
	s_add_i32 m0, s31, 0xc000
	ds_read_b128 v[200:203], v198
	ds_read_b128 v[204:207], v198 offset:1024
	ds_read_b128 v[208:211], v198 offset:2048
	ds_read_b128 v[226:229], v198 offset:3072
	ds_read_b128 v[230:233], v198 offset:4096
	ds_read_b128 v[234:237], v198 offset:5120
	ds_read_b128 v[238:241], v198 offset:6144
	ds_read_b128 v[242:245], v198 offset:7168
	global_load_lds_dwordx4 v[98:99], off
	v_lshl_add_u64 v[98:99], s[6:7], 0, v[190:191]
	s_add_i32 m0, s31, 0xe000
	s_nop 0
	global_load_lds_dwordx4 v[98:99], off
	s_waitcnt vmcnt(8)
	s_waitcnt lgkmcnt(0)
	s_barrier
	s_setprio 1
	v_mfma_f32_16x16x32_bf16 v[128:131], v[132:135], v[200:203], v[128:131]
	v_mfma_f32_16x16x32_bf16 v[124:127], v[140:143], v[200:203], v[124:127]
	v_mfma_f32_16x16x32_bf16 v[120:123], v[132:135], v[208:211], v[120:123]
	v_mfma_f32_16x16x32_bf16 v[112:115], v[140:143], v[208:211], v[112:115]
	v_mfma_f32_16x16x32_bf16 v[104:107], v[132:135], v[230:233], v[104:107]
	v_mfma_f32_16x16x32_bf16 v[92:95], v[140:143], v[230:233], v[92:95]
	v_mfma_f32_16x16x32_bf16 v[84:87], v[132:135], v[238:241], v[84:87]
	v_mfma_f32_16x16x32_bf16 v[76:79], v[140:143], v[238:241], v[76:79]
	v_mfma_f32_16x16x32_bf16 v[128:131], v[136:139], v[204:207], v[128:131]
	v_mfma_f32_16x16x32_bf16 v[124:127], v[144:147], v[204:207], v[124:127]
	v_mfma_f32_16x16x32_bf16 v[120:123], v[136:139], v[226:229], v[120:123]
	v_mfma_f32_16x16x32_bf16 v[112:115], v[144:147], v[226:229], v[112:115]
	v_mfma_f32_16x16x32_bf16 v[104:107], v[136:139], v[234:237], v[104:107]
	v_mfma_f32_16x16x32_bf16 v[92:95], v[144:147], v[234:237], v[92:95]
	v_mfma_f32_16x16x32_bf16 v[84:87], v[136:139], v[242:245], v[84:87]
	v_mfma_f32_16x16x32_bf16 v[76:79], v[144:147], v[242:245], v[76:79]
	s_setprio 0
	s_setprio 1
	v_mfma_f32_16x16x32_bf16 v[116:119], v[148:151], v[200:203], v[116:119]
	v_mfma_f32_16x16x32_bf16 v[108:111], v[156:159], v[200:203], v[108:111]
	v_mfma_f32_16x16x32_bf16 v[98:101], v[148:151], v[208:211], v[100:103]
	v_mfma_f32_16x16x32_bf16 v[88:91], v[156:159], v[208:211], v[88:91]
	v_mfma_f32_16x16x32_bf16 v[80:83], v[148:151], v[230:233], v[80:83]
	v_mfma_f32_16x16x32_bf16 v[72:75], v[156:159], v[230:233], v[72:75]
	v_mfma_f32_16x16x32_bf16 v[68:71], v[148:151], v[238:241], v[68:71]
	v_mfma_f32_16x16x32_bf16 v[64:67], v[156:159], v[238:241], v[64:67]
	v_mfma_f32_16x16x32_bf16 v[116:119], v[152:155], v[204:207], v[116:119]
	v_mfma_f32_16x16x32_bf16 v[108:111], v[160:163], v[204:207], v[108:111]
	v_mfma_f32_16x16x32_bf16 v[98:101], v[152:155], v[226:229], v[98:101]
	v_mfma_f32_16x16x32_bf16 v[88:91], v[160:163], v[226:229], v[88:91]
	v_mfma_f32_16x16x32_bf16 v[80:83], v[152:155], v[234:237], v[80:83]
	v_mfma_f32_16x16x32_bf16 v[72:75], v[160:163], v[234:237], v[72:75]
	v_mfma_f32_16x16x32_bf16 v[68:71], v[152:155], v[242:245], v[68:71]
	v_mfma_f32_16x16x32_bf16 v[64:67], v[160:163], v[242:245], v[64:67]
	s_setprio 0
	s_barrier
	s_add_i32 s21, s21, s38
	v_lshl_add_u64 v[192:193], s[34:35], 0, v[166:167]
	s_mov_b32 m0, s21
	ds_read_b128 v[200:203], v198 offset:16384
	ds_read_b128 v[204:207], v198 offset:17408
	ds_read_b128 v[208:211], v198 offset:18432
	ds_read_b128 v[226:229], v198 offset:19456
	ds_read_b128 v[230:233], v198 offset:20480
	ds_read_b128 v[234:237], v198 offset:21504
	ds_read_b128 v[238:241], v198 offset:22528
	ds_read_b128 v[242:245], v198 offset:23552
	global_load_lds_dwordx4 v[192:193], off
	s_add_i32 m0, s21, 0x2000
	v_lshl_add_u64 v[246:247], s[34:35], 0, v[170:171]
	s_add_u32 s34, s34, s14
	s_addc_u32 s35, s35, 0
	s_add_i32 s13, s13, s38
	global_load_lds_dwordx4 v[246:247], off
	v_lshl_add_u64 v[248:249], s[34:35], 0, v[166:167]
	s_mov_b32 m0, s13
	v_lshl_add_u64 v[250:251], s[34:35], 0, v[170:171]
	global_load_lds_dwordx4 v[248:249], off
	s_add_i32 m0, s13, 0x2000
	v_lshl_add_u64 v[252:253], s[8:9], 0, v[164:165]
	global_load_lds_dwordx4 v[250:251], off
	s_mov_b32 m0, s31
	v_lshl_add_u64 v[214:215], s[8:9], 0, v[168:169]
	global_load_lds_dwordx4 v[252:253], off
	s_mov_b32 m0, s40
	s_nop 0
	global_load_lds_dwordx4 v[214:215], off
	s_waitcnt vmcnt(8)
	s_waitcnt lgkmcnt(0)
	s_barrier
; #define PG8_STAGE(bufoff, gbase, voff) do { _Pragma("unroll") for (int _i = 0; _i < 2; ++_i) \
;         __builtin_amdgcn_global_load_lds((const unsigned*)((const char*)(gbase) + (voff)[_i]), (LAS unsigned*)(lds + (bufoff) + ldsw + _i * 8192), 16, 0, 0); } while (0)
; #define PG8_LDA(dst, b, h) do { _Pragma("unroll") for (int m = 0; m < 4; ++m) _Pragma("unroll") for (int k = 0; k < 2; ++k) dst[m][k] = *(const LAS bf16x8*)(lds + PG8_SA(b, h) + aoff + m * 2048 + k * 1024); } while (0)
; #define PG8_LDB(dst, b, h) do { _Pragma("unroll") for (int n = 0; n < 2; ++n) _Pragma("unroll") for (int k = 0; k < 2; ++k) dst[n][k] = *(const LAS bf16x8*)(lds + PG8_SB(b, h) + boff + n * 2048 + k * 1024); } while (0)
; #define PG8_MMA(ai, bj, At, Bt) do { __builtin_amdgcn_s_setprio(1); _Pragma("unroll") for (int m = 0; m < 4; ++m) _Pragma("unroll") for (int n = 0; n < 2; ++n) _Pragma("unroll") for (int k = 0; k < 2; ++k) \
;         acc[ai][bj][m][n] = __builtin_amdgcn_mfma_f32_16x16x32_bf16(Bt[n][k], At[m][k], acc[ai][bj][m][n], 0, 0, 0); __builtin_amdgcn_s_setprio(0); } while (0)
; #define PG8_WAIT_V(n) asm volatile("s_waitcnt vmcnt(" #n ")" ::: "memory")
; #define PG8_WAIT_L(n) asm volatile("s_waitcnt lgkmcnt(" #n ")" ::: "memory")
; #define PG8_BAR __builtin_amdgcn_s_barrier()
; #define PG8_SCHED __builtin_amdgcn_sched_barrier(0)
;     ...
;             PG8_WAIT_V(8); PG8_WAIT_L(0); PG8_BAR; PG8_MMA(1, 0, At, B0); PG8_MMA(1, 1, At, B1); PG8_BAR; PG8_SCHED;
;             PG8_LDB(B0, 1, 0); PG8_LDB(B1, 1, 1); PG8_SCHED; PG8_LDA(At, 1, 0); PG8_STAGE(PG8_SA(0, 1), a2 + hstep, voffA);
;             PG8_WAIT_V(8); PG8_WAIT_L(0); PG8_BAR; PG8_MMA(0, 0, At, B0); PG8_MMA(0, 1, At, B1); PG8_BAR; PG8_SCHED;
	s_setprio 1
	v_mfma_f32_16x16x32_bf16 v[60:63], v[132:135], v[200:203], v[60:63]
	v_mfma_f32_16x16x32_bf16 v[56:59], v[140:143], v[200:203], v[56:59]
	v_mfma_f32_16x16x32_bf16 v[52:55], v[132:135], v[208:211], v[52:55]
	v_mfma_f32_16x16x32_bf16 v[44:47], v[140:143], v[208:211], v[44:47]
	v_mfma_f32_16x16x32_bf16 v[36:39], v[132:135], v[230:233], v[36:39]
	v_mfma_f32_16x16x32_bf16 v[28:31], v[140:143], v[230:233], v[28:31]
	v_mfma_f32_16x16x32_bf16 v[20:23], v[132:135], v[238:241], v[20:23]
	v_mfma_f32_16x16x32_bf16 v[12:15], v[140:143], v[238:241], v[12:15]
	v_mfma_f32_16x16x32_bf16 v[60:63], v[136:139], v[204:207], v[60:63]
	v_mfma_f32_16x16x32_bf16 v[56:59], v[144:147], v[204:207], v[56:59]
	v_mfma_f32_16x16x32_bf16 v[52:55], v[136:139], v[226:229], v[52:55]
	v_mfma_f32_16x16x32_bf16 v[44:47], v[144:147], v[226:229], v[44:47]
	v_mfma_f32_16x16x32_bf16 v[36:39], v[136:139], v[234:237], v[36:39]
	v_mfma_f32_16x16x32_bf16 v[28:31], v[144:147], v[234:237], v[28:31]
	v_mfma_f32_16x16x32_bf16 v[20:23], v[136:139], v[242:245], v[20:23]
	v_mfma_f32_16x16x32_bf16 v[12:15], v[144:147], v[242:245], v[12:15]
	s_setprio 0
	s_setprio 1
	v_mfma_f32_16x16x32_bf16 v[48:51], v[148:151], v[200:203], v[48:51]
	v_mfma_f32_16x16x32_bf16 v[40:43], v[156:159], v[200:203], v[40:43]
	v_mfma_f32_16x16x32_bf16 v[32:35], v[148:151], v[208:211], v[32:35]
	v_mfma_f32_16x16x32_bf16 v[24:27], v[156:159], v[208:211], v[24:27]
	v_mfma_f32_16x16x32_bf16 v[16:19], v[148:151], v[230:233], v[16:19]
	v_mfma_f32_16x16x32_bf16 v[8:11], v[156:159], v[230:233], v[8:11]
	v_mfma_f32_16x16x32_bf16 v[4:7], v[148:151], v[238:241], v[4:7]
	v_mfma_f32_16x16x32_bf16 v[0:3], v[156:159], v[238:241], v[0:3]
	v_mfma_f32_16x16x32_bf16 v[48:51], v[152:155], v[204:207], v[48:51]
	v_mfma_f32_16x16x32_bf16 v[40:43], v[160:163], v[204:207], v[40:43]
	v_mfma_f32_16x16x32_bf16 v[32:35], v[152:155], v[226:229], v[32:35]
	v_mfma_f32_16x16x32_bf16 v[24:27], v[160:163], v[226:229], v[24:27]
	v_mfma_f32_16x16x32_bf16 v[16:19], v[152:155], v[234:237], v[16:19]
	v_mfma_f32_16x16x32_bf16 v[8:11], v[160:163], v[234:237], v[8:11]
	v_mfma_f32_16x16x32_bf16 v[4:7], v[152:155], v[242:245], v[4:7]
	v_mfma_f32_16x16x32_bf16 v[0:3], v[160:163], v[242:245], v[0:3]
	s_setprio 0
	s_barrier
	s_add_i32 s13, 0, 0x18000
	v_add_u32_e32 v96, s13, v175
	s_add_i32 s21, 0, 0x1c000
	ds_read_b128 v[132:135], v96
	ds_read_b128 v[136:139], v96 offset:1024
	ds_read_b128 v[140:143], v96 offset:2048
	ds_read_b128 v[144:147], v96 offset:3072
	v_add_u32_e32 v96, s21, v175
	ds_read_b128 v[148:151], v96
	ds_read_b128 v[152:155], v96 offset:1024
	ds_read_b128 v[156:159], v96 offset:2048
	ds_read_b128 v[160:163], v96 offset:3072
	s_add_u32 s8, s8, s14
	s_addc_u32 s9, s9, 0
	s_mov_b32 m0, s41
	v_lshl_add_u64 v[102:103], s[8:9], 0, v[164:165]
	ds_read_b128 v[200:203], v198 offset:32768
	ds_read_b128 v[204:207], v198 offset:33792
	ds_read_b128 v[208:211], v198 offset:34816
	ds_read_b128 v[226:229], v198 offset:35840
	ds_read_b128 v[230:233], v198 offset:36864
	ds_read_b128 v[234:237], v198 offset:37888
	ds_read_b128 v[238:241], v198 offset:38912
	ds_read_b128 v[242:245], v198 offset:39936
	global_load_lds_dwordx4 v[102:103], off
	v_lshl_add_u64 v[102:103], s[8:9], 0, v[168:169]
	s_mov_b32 m0, s51
	s_nop 0
	global_load_lds_dwordx4 v[102:103], off
	s_waitcnt vmcnt(8)
	s_waitcnt lgkmcnt(0)
	s_barrier
	s_setprio 1
	v_mfma_f32_16x16x32_bf16 v[128:131], v[132:135], v[200:203], v[128:131]
	v_mfma_f32_16x16x32_bf16 v[124:127], v[140:143], v[200:203], v[124:127]
	v_mfma_f32_16x16x32_bf16 v[120:123], v[132:135], v[208:211], v[120:123]
	v_mfma_f32_16x16x32_bf16 v[112:115], v[140:143], v[208:211], v[112:115]
	v_mfma_f32_16x16x32_bf16 v[102:105], v[132:135], v[230:233], v[104:107]
	v_mfma_f32_16x16x32_bf16 v[92:95], v[140:143], v[230:233], v[92:95]
	v_mfma_f32_16x16x32_bf16 v[84:87], v[132:135], v[238:241], v[84:87]
	v_mfma_f32_16x16x32_bf16 v[76:79], v[140:143], v[238:241], v[76:79]
	v_mfma_f32_16x16x32_bf16 v[128:131], v[136:139], v[204:207], v[128:131]
	v_mfma_f32_16x16x32_bf16 v[124:127], v[144:147], v[204:207], v[124:127]
	v_mfma_f32_16x16x32_bf16 v[120:123], v[136:139], v[226:229], v[120:123]
	v_mfma_f32_16x16x32_bf16 v[112:115], v[144:147], v[226:229], v[112:115]
	v_mfma_f32_16x16x32_bf16 v[104:107], v[136:139], v[234:237], v[102:105]
	v_mfma_f32_16x16x32_bf16 v[92:95], v[144:147], v[234:237], v[92:95]
	v_mfma_f32_16x16x32_bf16 v[84:87], v[136:139], v[242:245], v[84:87]
	v_mfma_f32_16x16x32_bf16 v[76:79], v[144:147], v[242:245], v[76:79]
	s_setprio 0
	s_setprio 1
	v_mfma_f32_16x16x32_bf16 v[116:119], v[148:151], v[200:203], v[116:119]
	v_mfma_f32_16x16x32_bf16 v[108:111], v[156:159], v[200:203], v[108:111]
	v_mfma_f32_16x16x32_bf16 v[98:101], v[148:151], v[208:211], v[98:101]
	v_mfma_f32_16x16x32_bf16 v[88:91], v[156:159], v[208:211], v[88:91]
	v_mfma_f32_16x16x32_bf16 v[80:83], v[148:151], v[230:233], v[80:83]
	v_mfma_f32_16x16x32_bf16 v[72:75], v[156:159], v[230:233], v[72:75]
	v_mfma_f32_16x16x32_bf16 v[68:71], v[148:151], v[238:241], v[68:71]
	v_mfma_f32_16x16x32_bf16 v[64:67], v[156:159], v[238:241], v[64:67]
	v_mfma_f32_16x16x32_bf16 v[116:119], v[152:155], v[204:207], v[116:119]
	v_mfma_f32_16x16x32_bf16 v[108:111], v[160:163], v[204:207], v[108:111]
	v_mfma_f32_16x16x32_bf16 v[100:103], v[152:155], v[226:229], v[98:101]
	v_mfma_f32_16x16x32_bf16 v[88:91], v[160:163], v[226:229], v[88:91]
	v_mfma_f32_16x16x32_bf16 v[80:83], v[152:155], v[234:237], v[80:83]
	v_mfma_f32_16x16x32_bf16 v[72:75], v[160:163], v[234:237], v[72:75]
	v_mfma_f32_16x16x32_bf16 v[68:71], v[152:155], v[242:245], v[68:71]
	v_mfma_f32_16x16x32_bf16 v[64:67], v[160:163], v[242:245], v[64:67]
	s_setprio 0
	s_barrier
; #define PG8_STAGE(bufoff, gbase, voff) do { _Pragma("unroll") for (int _i = 0; _i < 2; ++_i) \
;         __builtin_amdgcn_global_load_lds((const unsigned*)((const char*)(gbase) + (voff)[_i]), (LAS unsigned*)(lds + (bufoff) + ldsw + _i * 8192), 16, 0, 0); } while (0)
; #define PG8_LDA(dst, b, h) do { _Pragma("unroll") for (int m = 0; m < 4; ++m) _Pragma("unroll") for (int k = 0; k < 2; ++k) dst[m][k] = *(const LAS bf16x8*)(lds + PG8_SA(b, h) + aoff + m * 2048 + k * 1024); } while (0)
; #define PG8_MMA(ai, bj, At, Bt) do { __builtin_amdgcn_s_setprio(1); _Pragma("unroll") for (int m = 0; m < 4; ++m) _Pragma("unroll") for (int n = 0; n < 2; ++n) _Pragma("unroll") for (int k = 0; k < 2; ++k) \
;         acc[ai][bj][m][n] = __builtin_amdgcn_mfma_f32_16x16x32_bf16(Bt[n][k], At[m][k], acc[ai][bj][m][n], 0, 0, 0); __builtin_amdgcn_s_setprio(0); } while (0)
; #define PG8_WAIT_V(n) asm volatile("s_waitcnt vmcnt(" #n ")" ::: "memory")
; #define PG8_WAIT_L(n) asm volatile("s_waitcnt lgkmcnt(" #n ")" ::: "memory")
; #define PG8_BAR __builtin_amdgcn_s_barrier()
; #define PG8_SCHED __builtin_amdgcn_sched_barrier(0)
;     ...
;             PG8_LDA(At, 1, 1); PG8_STAGE(PG8_SB(1, 0), b3, voffB); PG8_STAGE(PG8_SB(1, 1), b3 + hstep, voffB); PG8_STAGE(PG8_SA(1, 0), a3, voffA);
;             PG8_WAIT_V(8); PG8_WAIT_L(0); PG8_BAR; PG8_MMA(1, 0, At, B0); PG8_MMA(1, 1, At, B1); PG8_BAR; PG8_SCHED;
;         }
	s_add_i32 s8, s13, s38
	v_lshl_add_u64 v[98:99], v[192:193], 0, s[46:47]
	s_mov_b32 m0, s8
	ds_read_b128 v[200:203], v198 offset:49152
	ds_read_b128 v[204:207], v198 offset:50176
	ds_read_b128 v[208:211], v198 offset:51200
	ds_read_b128 v[226:229], v198 offset:52224
	ds_read_b128 v[230:233], v198 offset:53248
	ds_read_b128 v[234:237], v198 offset:54272
	ds_read_b128 v[238:241], v198 offset:55296
	ds_read_b128 v[242:245], v198 offset:56320
	global_load_lds_dwordx4 v[98:99], off
	v_lshl_add_u64 v[98:99], v[246:247], 0, s[46:47]
	s_add_i32 m0, s8, 0x2000
	s_add_i32 s8, s21, s38
	global_load_lds_dwordx4 v[98:99], off
	v_lshl_add_u64 v[98:99], v[248:249], 0, s[46:47]
	s_mov_b32 m0, s8
	s_nop 0
	global_load_lds_dwordx4 v[98:99], off
	v_lshl_add_u64 v[98:99], v[250:251], 0, s[46:47]
	s_add_i32 m0, s8, 0x2000
	s_nop 0
	global_load_lds_dwordx4 v[98:99], off
	v_lshl_add_u64 v[98:99], v[252:253], 0, s[46:47]
	s_mov_b32 m0, s56
	s_nop 0
	global_load_lds_dwordx4 v[98:99], off
	v_lshl_add_u64 v[98:99], v[214:215], 0, s[46:47]
	s_mov_b32 m0, s57
	s_nop 0
	global_load_lds_dwordx4 v[98:99], off
	s_waitcnt vmcnt(8)
	s_waitcnt lgkmcnt(0)
	s_barrier
	s_setprio 1
	v_mfma_f32_16x16x32_bf16 v[60:63], v[132:135], v[200:203], v[60:63]
	v_mfma_f32_16x16x32_bf16 v[56:59], v[140:143], v[200:203], v[56:59]
	v_mfma_f32_16x16x32_bf16 v[52:55], v[132:135], v[208:211], v[52:55]
	v_mfma_f32_16x16x32_bf16 v[44:47], v[140:143], v[208:211], v[44:47]
	v_mfma_f32_16x16x32_bf16 v[36:39], v[132:135], v[230:233], v[36:39]
	v_mfma_f32_16x16x32_bf16 v[28:31], v[140:143], v[230:233], v[28:31]
	v_mfma_f32_16x16x32_bf16 v[20:23], v[132:135], v[238:241], v[20:23]
	v_mfma_f32_16x16x32_bf16 v[12:15], v[140:143], v[238:241], v[12:15]
	v_mfma_f32_16x16x32_bf16 v[60:63], v[136:139], v[204:207], v[60:63]
	v_mfma_f32_16x16x32_bf16 v[56:59], v[144:147], v[204:207], v[56:59]
	v_mfma_f32_16x16x32_bf16 v[52:55], v[136:139], v[226:229], v[52:55]
	v_mfma_f32_16x16x32_bf16 v[44:47], v[144:147], v[226:229], v[44:47]
	v_mfma_f32_16x16x32_bf16 v[36:39], v[136:139], v[234:237], v[36:39]
	v_mfma_f32_16x16x32_bf16 v[28:31], v[144:147], v[234:237], v[28:31]
	v_mfma_f32_16x16x32_bf16 v[20:23], v[136:139], v[242:245], v[20:23]
	v_mfma_f32_16x16x32_bf16 v[12:15], v[144:147], v[242:245], v[12:15]
	s_setprio 0
	s_setprio 1
	v_mfma_f32_16x16x32_bf16 v[48:51], v[148:151], v[200:203], v[48:51]
	v_mfma_f32_16x16x32_bf16 v[40:43], v[156:159], v[200:203], v[40:43]
	v_mfma_f32_16x16x32_bf16 v[32:35], v[148:151], v[208:211], v[32:35]
	v_mfma_f32_16x16x32_bf16 v[24:27], v[156:159], v[208:211], v[24:27]
	v_mfma_f32_16x16x32_bf16 v[16:19], v[148:151], v[230:233], v[16:19]
	v_mfma_f32_16x16x32_bf16 v[8:11], v[156:159], v[230:233], v[8:11]
	v_mfma_f32_16x16x32_bf16 v[4:7], v[148:151], v[238:241], v[4:7]
	v_mfma_f32_16x16x32_bf16 v[0:3], v[156:159], v[238:241], v[0:3]
	v_mfma_f32_16x16x32_bf16 v[48:51], v[152:155], v[204:207], v[48:51]
	v_mfma_f32_16x16x32_bf16 v[40:43], v[160:163], v[204:207], v[40:43]
	v_mfma_f32_16x16x32_bf16 v[32:35], v[152:155], v[226:229], v[32:35]
	v_mfma_f32_16x16x32_bf16 v[24:27], v[160:163], v[226:229], v[24:27]
	v_mfma_f32_16x16x32_bf16 v[16:19], v[152:155], v[234:237], v[16:19]
	v_mfma_f32_16x16x32_bf16 v[8:11], v[160:163], v[234:237], v[8:11]
	v_mfma_f32_16x16x32_bf16 v[4:7], v[152:155], v[242:245], v[4:7]
	v_mfma_f32_16x16x32_bf16 v[0:3], v[160:163], v[242:245], v[0:3]
	s_setprio 0
	s_barrier
	s_add_u32 s6, s6, 0x100
	s_addc_u32 s7, s7, 0
	s_add_u32 s10, s10, 0x100
	s_addc_u32 s11, s11, 0
	s_cmp_ge_u32 s12, s39
	s_mov_b32 s8, s12
	s_cbranch_scc0 .LBB0_587
	s_and_b64 vcc, exec, s[24:25]
	s_cbranch_vccz .LBB0_597

; #define PG8_STAGE(bufoff, gbase, voff) do { _Pragma("unroll") for (int _i = 0; _i < 2; ++_i) \
;         __builtin_amdgcn_global_load_lds((const unsigned*)((const char*)(gbase) + (voff)[_i]), (LAS unsigned*)(lds + (bufoff) + ldsw + _i * 8192), 16, 0, 0); } while (0)
; #define PG8_LDA(dst, b, h) do { _Pragma("unroll") for (int m = 0; m < 4; ++m) _Pragma("unroll") for (int k = 0; k < 2; ++k) dst[m][k] = *(const LAS bf16x8*)(lds + PG8_SA(b, h) + aoff + m * 2048 + k * 1024); } while (0)
; #define PG8_LDB(dst, b, h) do { _Pragma("unroll") for (int n = 0; n < 2; ++n) _Pragma("unroll") for (int k = 0; k < 2; ++k) dst[n][k] = *(const LAS bf16x8*)(lds + PG8_SB(b, h) + boff + n * 2048 + k * 1024); } while (0)
; #define PG8_MMA(ai, bj, At, Bt) do { __builtin_amdgcn_s_setprio(1); _Pragma("unroll") for (int m = 0; m < 4; ++m) _Pragma("unroll") for (int n = 0; n < 2; ++n) _Pragma("unroll") for (int k = 0; k < 2; ++k) \
;         acc[ai][bj][m][n] = __builtin_amdgcn_mfma_f32_16x16x32_bf16(Bt[n][k], At[m][k], acc[ai][bj][m][n], 0, 0, 0); __builtin_amdgcn_s_setprio(0); } while (0)
; #define PG8_WAIT_V(n) asm volatile("s_waitcnt vmcnt(" #n ")" ::: "memory")
; #define PG8_WAIT_L(n) asm volatile("s_waitcnt lgkmcnt(" #n ")" ::: "memory")
; #define PG8_BAR __builtin_amdgcn_s_barrier()
; #define PG8_SCHED __builtin_amdgcn_sched_barrier(0)
;     ...
;         for (int t = 0; t < nt; t += 2) {
;             const bool last = (t == nt - 2);
;             const char* a1 = cA + (size_t)(t + 1) * kstep;
;             const char* a2 = last ? nA : cA + (size_t)(t + 2) * kstep; const char* b2 = last ? nB : cB + (size_t)(t + 2) * kstep;
;             const char* a3 = a2 + kstep; const char* b3 = b2 + kstep;
;             PG8_LDB(B0, 0, 0); PG8_LDB(B1, 0, 1); PG8_SCHED; PG8_LDA(At, 0, 0); PG8_STAGE(PG8_SA(1, 1), a1 + hstep, voffA);
;             PG8_WAIT_V(8); PG8_WAIT_L(0); PG8_BAR; PG8_MMA(0, 0, At, B0); PG8_MMA(0, 1, At, B1); PG8_BAR; PG8_SCHED;
;             PG8_LDA(At, 0, 1); PG8_STAGE(PG8_SB(0, 0), b2, voffB); PG8_STAGE(PG8_SB(0, 1), b2 + hstep, voffB); PG8_STAGE(PG8_SA(0, 0), a2, voffA);
;             PG8_WAIT_V(8); PG8_WAIT_L(0); PG8_BAR; PG8_MMA(1, 0, At, B0); PG8_MMA(1, 1, At, B1); PG8_BAR; PG8_SCHED;
.LBB0_813:
	s_add_i32 s10, s6, 2
	s_add_u32 s11, s4, 0x80
	s_addc_u32 s7, s5, 0
	s_add_i32 s23, 0, 0x10000
	s_cmp_eq_u32 s56, s6
	s_cselect_b32 s7, s27, s7
	s_cselect_b32 s6, s26, s11
	v_add_u32_e32 v96, s23, v165
	s_cselect_b32 s31, s29, s9
	s_cselect_b32 s30, s28, s8
	s_add_i32 s11, 0, 0x14000
	s_waitcnt lgkmcnt(0)
	ds_read_b128 v[130:133], v96
	ds_read_b128 v[134:137], v96 offset:1024
	ds_read_b128 v[138:141], v96 offset:2048
	ds_read_b128 v[142:145], v96 offset:3072
	v_add_u32_e32 v96, s11, v165
	ds_read_b128 v[174:177], v96
	ds_read_b128 v[188:191], v96 offset:1024
	ds_read_b128 v[192:195], v96 offset:2048
	ds_read_b128 v[196:199], v96 offset:3072
	v_lshl_add_u64 v[146:147], s[4:5], 0, v[158:159]
	s_add_i32 m0, s35, 0xc000
	ds_read_b128 v[200:203], v172
	ds_read_b128 v[204:207], v172 offset:1024
	ds_read_b128 v[208:211], v172 offset:2048
	ds_read_b128 v[226:229], v172 offset:3072
	ds_read_b128 v[230:233], v172 offset:4096
	ds_read_b128 v[234:237], v172 offset:5120
	ds_read_b128 v[238:241], v172 offset:6144
	ds_read_b128 v[242:245], v172 offset:7168
	global_load_lds_dwordx4 v[146:147], off
	v_lshl_add_u64 v[146:147], s[4:5], 0, v[160:161]
	s_add_i32 m0, s35, 0xe000
	s_nop 0
	global_load_lds_dwordx4 v[146:147], off
	s_waitcnt vmcnt(8)
	s_waitcnt lgkmcnt(0)
	s_barrier
	s_setprio 1
	v_mfma_f32_16x16x32_bf16 v[126:129], v[130:133], v[200:203], v[126:129]
	v_mfma_f32_16x16x32_bf16 v[122:125], v[138:141], v[200:203], v[122:125]
	v_mfma_f32_16x16x32_bf16 v[110:113], v[130:133], v[208:211], v[110:113]
	v_mfma_f32_16x16x32_bf16 v[106:109], v[138:141], v[208:211], v[106:109]
	v_mfma_f32_16x16x32_bf16 v[92:95], v[130:133], v[230:233], v[92:95]
	v_mfma_f32_16x16x32_bf16 v[88:91], v[138:141], v[230:233], v[88:91]
	v_mfma_f32_16x16x32_bf16 v[76:79], v[130:133], v[238:241], v[76:79]
	v_mfma_f32_16x16x32_bf16 v[72:75], v[138:141], v[238:241], v[72:75]
	v_mfma_f32_16x16x32_bf16 v[126:129], v[134:137], v[204:207], v[126:129]
	v_mfma_f32_16x16x32_bf16 v[122:125], v[142:145], v[204:207], v[122:125]
	v_mfma_f32_16x16x32_bf16 v[110:113], v[134:137], v[226:229], v[110:113]
	v_mfma_f32_16x16x32_bf16 v[106:109], v[142:145], v[226:229], v[106:109]
	v_mfma_f32_16x16x32_bf16 v[92:95], v[134:137], v[234:237], v[92:95]
	v_mfma_f32_16x16x32_bf16 v[88:91], v[142:145], v[234:237], v[88:91]
	v_mfma_f32_16x16x32_bf16 v[76:79], v[134:137], v[242:245], v[76:79]
	v_mfma_f32_16x16x32_bf16 v[72:75], v[142:145], v[242:245], v[72:75]
	s_setprio 0
	s_setprio 1
	v_mfma_f32_16x16x32_bf16 v[118:121], v[174:177], v[200:203], v[118:121]
	v_mfma_f32_16x16x32_bf16 v[114:117], v[192:195], v[200:203], v[114:117]
	v_mfma_f32_16x16x32_bf16 v[102:105], v[174:177], v[208:211], v[102:105]
	v_mfma_f32_16x16x32_bf16 v[98:101], v[192:195], v[208:211], v[98:101]
	v_mfma_f32_16x16x32_bf16 v[84:87], v[174:177], v[230:233], v[84:87]
	v_mfma_f32_16x16x32_bf16 v[80:83], v[192:195], v[230:233], v[80:83]
	v_mfma_f32_16x16x32_bf16 v[68:71], v[174:177], v[238:241], v[68:71]
	v_mfma_f32_16x16x32_bf16 v[64:67], v[192:195], v[238:241], v[64:67]
	v_mfma_f32_16x16x32_bf16 v[118:121], v[188:191], v[204:207], v[118:121]
	v_mfma_f32_16x16x32_bf16 v[114:117], v[196:199], v[204:207], v[114:117]
	v_mfma_f32_16x16x32_bf16 v[102:105], v[188:191], v[226:229], v[102:105]
	v_mfma_f32_16x16x32_bf16 v[98:101], v[196:199], v[226:229], v[98:101]
	v_mfma_f32_16x16x32_bf16 v[84:87], v[188:191], v[234:237], v[84:87]
	v_mfma_f32_16x16x32_bf16 v[80:83], v[196:199], v[234:237], v[80:83]
	v_mfma_f32_16x16x32_bf16 v[68:71], v[188:191], v[242:245], v[68:71]
	v_mfma_f32_16x16x32_bf16 v[64:67], v[196:199], v[242:245], v[64:67]
	s_setprio 0
	s_barrier
	s_add_i32 s23, s23, s34
	v_lshl_add_u64 v[146:147], s[30:31], 0, v[150:151]
	s_mov_b32 m0, s23
	ds_read_b128 v[200:203], v172 offset:16384
	ds_read_b128 v[204:207], v172 offset:17408
	ds_read_b128 v[208:211], v172 offset:18432
	ds_read_b128 v[226:229], v172 offset:19456
	ds_read_b128 v[230:233], v172 offset:20480
	ds_read_b128 v[234:237], v172 offset:21504
	ds_read_b128 v[238:241], v172 offset:22528
	ds_read_b128 v[242:245], v172 offset:23552
	global_load_lds_dwordx4 v[146:147], off
	s_add_i32 m0, s23, 0x2000
	v_lshl_add_u64 v[162:163], s[30:31], 0, v[154:155]
	s_add_u32 s30, s30, s16
	s_addc_u32 s31, s31, 0
	s_add_i32 s11, s11, s34
	global_load_lds_dwordx4 v[162:163], off
	v_lshl_add_u64 v[214:215], s[30:31], 0, v[150:151]
	s_mov_b32 m0, s11
	v_lshl_add_u64 v[246:247], s[30:31], 0, v[154:155]
	global_load_lds_dwordx4 v[214:215], off
	s_add_i32 m0, s11, 0x2000
	v_lshl_add_u64 v[248:249], s[6:7], 0, v[148:149]
	global_load_lds_dwordx4 v[246:247], off
	s_mov_b32 m0, s35
	v_lshl_add_u64 v[250:251], s[6:7], 0, v[152:153]
	global_load_lds_dwordx4 v[248:249], off
	s_mov_b32 m0, s36
	s_nop 0
	global_load_lds_dwordx4 v[250:251], off
	s_waitcnt vmcnt(8)
	s_waitcnt lgkmcnt(0)
	s_barrier
; #define PG8_STAGE(bufoff, gbase, voff) do { _Pragma("unroll") for (int _i = 0; _i < 2; ++_i) \
;         __builtin_amdgcn_global_load_lds((const unsigned*)((const char*)(gbase) + (voff)[_i]), (LAS unsigned*)(lds + (bufoff) + ldsw + _i * 8192), 16, 0, 0); } while (0)
; #define PG8_LDA(dst, b, h) do { _Pragma("unroll") for (int m = 0; m < 4; ++m) _Pragma("unroll") for (int k = 0; k < 2; ++k) dst[m][k] = *(const LAS bf16x8*)(lds + PG8_SA(b, h) + aoff + m * 2048 + k * 1024); } while (0)
; #define PG8_LDB(dst, b, h) do { _Pragma("unroll") for (int n = 0; n < 2; ++n) _Pragma("unroll") for (int k = 0; k < 2; ++k) dst[n][k] = *(const LAS bf16x8*)(lds + PG8_SB(b, h) + boff + n * 2048 + k * 1024); } while (0)
; #define PG8_MMA(ai, bj, At, Bt) do { __builtin_amdgcn_s_setprio(1); _Pragma("unroll") for (int m = 0; m < 4; ++m) _Pragma("unroll") for (int n = 0; n < 2; ++n) _Pragma("unroll") for (int k = 0; k < 2; ++k) \
;         acc[ai][bj][m][n] = __builtin_amdgcn_mfma_f32_16x16x32_bf16(Bt[n][k], At[m][k], acc[ai][bj][m][n], 0, 0, 0); __builtin_amdgcn_s_setprio(0); } while (0)
; #define PG8_WAIT_V(n) asm volatile("s_waitcnt vmcnt(" #n ")" ::: "memory")
; #define PG8_WAIT_L(n) asm volatile("s_waitcnt lgkmcnt(" #n ")" ::: "memory")
; #define PG8_BAR __builtin_amdgcn_s_barrier()
; #define PG8_SCHED __builtin_amdgcn_sched_barrier(0)
;     ...
;             PG8_WAIT_V(8); PG8_WAIT_L(0); PG8_BAR; PG8_MMA(1, 0, At, B0); PG8_MMA(1, 1, At, B1); PG8_BAR; PG8_SCHED;
;             PG8_LDB(B0, 1, 0); PG8_LDB(B1, 1, 1); PG8_SCHED; PG8_LDA(At, 1, 0); PG8_STAGE(PG8_SA(0, 1), a2 + hstep, voffA);
;             PG8_WAIT_V(8); PG8_WAIT_L(0); PG8_BAR; PG8_MMA(0, 0, At, B0); PG8_MMA(0, 1, At, B1); PG8_BAR; PG8_SCHED;
	s_setprio 1
	v_mfma_f32_16x16x32_bf16 v[60:63], v[130:133], v[200:203], v[60:63]
	v_mfma_f32_16x16x32_bf16 v[56:59], v[138:141], v[200:203], v[56:59]
	v_mfma_f32_16x16x32_bf16 v[44:47], v[130:133], v[208:211], v[44:47]
	v_mfma_f32_16x16x32_bf16 v[40:43], v[138:141], v[208:211], v[40:43]
	v_mfma_f32_16x16x32_bf16 v[28:31], v[130:133], v[230:233], v[28:31]
	v_mfma_f32_16x16x32_bf16 v[24:27], v[138:141], v[230:233], v[24:27]
	v_mfma_f32_16x16x32_bf16 v[12:15], v[130:133], v[238:241], v[12:15]
	v_mfma_f32_16x16x32_bf16 v[8:11], v[138:141], v[238:241], v[8:11]
	v_mfma_f32_16x16x32_bf16 v[60:63], v[134:137], v[204:207], v[60:63]
	v_mfma_f32_16x16x32_bf16 v[56:59], v[142:145], v[204:207], v[56:59]
	v_mfma_f32_16x16x32_bf16 v[44:47], v[134:137], v[226:229], v[44:47]
	v_mfma_f32_16x16x32_bf16 v[40:43], v[142:145], v[226:229], v[40:43]
	v_mfma_f32_16x16x32_bf16 v[28:31], v[134:137], v[234:237], v[28:31]
	v_mfma_f32_16x16x32_bf16 v[24:27], v[142:145], v[234:237], v[24:27]
	v_mfma_f32_16x16x32_bf16 v[12:15], v[134:137], v[242:245], v[12:15]
	v_mfma_f32_16x16x32_bf16 v[8:11], v[142:145], v[242:245], v[8:11]
	s_setprio 0
	s_setprio 1
	v_mfma_f32_16x16x32_bf16 v[52:55], v[174:177], v[200:203], v[52:55]
	v_mfma_f32_16x16x32_bf16 v[48:51], v[192:195], v[200:203], v[48:51]
	v_mfma_f32_16x16x32_bf16 v[36:39], v[174:177], v[208:211], v[36:39]
	v_mfma_f32_16x16x32_bf16 v[32:35], v[192:195], v[208:211], v[32:35]
	v_mfma_f32_16x16x32_bf16 v[20:23], v[174:177], v[230:233], v[20:23]
	v_mfma_f32_16x16x32_bf16 v[16:19], v[192:195], v[230:233], v[16:19]
	v_mfma_f32_16x16x32_bf16 v[4:7], v[174:177], v[238:241], v[4:7]
	v_mfma_f32_16x16x32_bf16 v[0:3], v[192:195], v[238:241], v[0:3]
	v_mfma_f32_16x16x32_bf16 v[52:55], v[188:191], v[204:207], v[52:55]
	v_mfma_f32_16x16x32_bf16 v[48:51], v[196:199], v[204:207], v[48:51]
	v_mfma_f32_16x16x32_bf16 v[36:39], v[188:191], v[226:229], v[36:39]
	v_mfma_f32_16x16x32_bf16 v[32:35], v[196:199], v[226:229], v[32:35]
	v_mfma_f32_16x16x32_bf16 v[20:23], v[188:191], v[234:237], v[20:23]
	v_mfma_f32_16x16x32_bf16 v[16:19], v[196:199], v[234:237], v[16:19]
	v_mfma_f32_16x16x32_bf16 v[4:7], v[188:191], v[242:245], v[4:7]
	v_mfma_f32_16x16x32_bf16 v[0:3], v[196:199], v[242:245], v[0:3]
	s_setprio 0
	s_barrier
	s_add_i32 s11, 0, 0x18000
	v_add_u32_e32 v96, s11, v165
	s_add_i32 s23, 0, 0x1c000
	ds_read_b128 v[130:133], v96
	ds_read_b128 v[134:137], v96 offset:1024
	ds_read_b128 v[138:141], v96 offset:2048
	ds_read_b128 v[142:145], v96 offset:3072
	v_add_u32_e32 v96, s23, v165
	ds_read_b128 v[174:177], v96
	ds_read_b128 v[188:191], v96 offset:1024
	ds_read_b128 v[192:195], v96 offset:2048
	ds_read_b128 v[196:199], v96 offset:3072
	s_add_u32 s6, s6, s16
	s_addc_u32 s7, s7, 0
	s_mov_b32 m0, s37
	v_lshl_add_u64 v[252:253], s[6:7], 0, v[148:149]
	ds_read_b128 v[200:203], v172 offset:32768
	ds_read_b128 v[204:207], v172 offset:33792
	ds_read_b128 v[208:211], v172 offset:34816
	ds_read_b128 v[226:229], v172 offset:35840
	ds_read_b128 v[230:233], v172 offset:36864
	ds_read_b128 v[234:237], v172 offset:37888
	ds_read_b128 v[238:241], v172 offset:38912
	ds_read_b128 v[242:245], v172 offset:39936
	global_load_lds_dwordx4 v[252:253], off
	v_lshl_add_u64 v[252:253], s[6:7], 0, v[152:153]
	s_mov_b32 m0, s38
	s_nop 0
	global_load_lds_dwordx4 v[252:253], off
	s_waitcnt vmcnt(8)
	s_waitcnt lgkmcnt(0)
	s_barrier
	s_setprio 1
	v_mfma_f32_16x16x32_bf16 v[126:129], v[130:133], v[200:203], v[126:129]
	v_mfma_f32_16x16x32_bf16 v[122:125], v[138:141], v[200:203], v[122:125]
	v_mfma_f32_16x16x32_bf16 v[110:113], v[130:133], v[208:211], v[110:113]
	v_mfma_f32_16x16x32_bf16 v[106:109], v[138:141], v[208:211], v[106:109]
	v_mfma_f32_16x16x32_bf16 v[92:95], v[130:133], v[230:233], v[92:95]
	v_mfma_f32_16x16x32_bf16 v[88:91], v[138:141], v[230:233], v[88:91]
	v_mfma_f32_16x16x32_bf16 v[76:79], v[130:133], v[238:241], v[76:79]
	v_mfma_f32_16x16x32_bf16 v[72:75], v[138:141], v[238:241], v[72:75]
	v_mfma_f32_16x16x32_bf16 v[126:129], v[134:137], v[204:207], v[126:129]
	v_mfma_f32_16x16x32_bf16 v[122:125], v[142:145], v[204:207], v[122:125]
	v_mfma_f32_16x16x32_bf16 v[110:113], v[134:137], v[226:229], v[110:113]
	v_mfma_f32_16x16x32_bf16 v[106:109], v[142:145], v[226:229], v[106:109]
	v_mfma_f32_16x16x32_bf16 v[92:95], v[134:137], v[234:237], v[92:95]
	v_mfma_f32_16x16x32_bf16 v[88:91], v[142:145], v[234:237], v[88:91]
	v_mfma_f32_16x16x32_bf16 v[76:79], v[134:137], v[242:245], v[76:79]
	v_mfma_f32_16x16x32_bf16 v[72:75], v[142:145], v[242:245], v[72:75]
	s_setprio 0
	s_setprio 1
	v_mfma_f32_16x16x32_bf16 v[118:121], v[174:177], v[200:203], v[118:121]
	v_mfma_f32_16x16x32_bf16 v[114:117], v[192:195], v[200:203], v[114:117]
	v_mfma_f32_16x16x32_bf16 v[102:105], v[174:177], v[208:211], v[102:105]
	v_mfma_f32_16x16x32_bf16 v[98:101], v[192:195], v[208:211], v[98:101]
	v_mfma_f32_16x16x32_bf16 v[84:87], v[174:177], v[230:233], v[84:87]
	v_mfma_f32_16x16x32_bf16 v[80:83], v[192:195], v[230:233], v[80:83]
	v_mfma_f32_16x16x32_bf16 v[68:71], v[174:177], v[238:241], v[68:71]
	v_mfma_f32_16x16x32_bf16 v[64:67], v[192:195], v[238:241], v[64:67]
	v_mfma_f32_16x16x32_bf16 v[118:121], v[188:191], v[204:207], v[118:121]
	v_mfma_f32_16x16x32_bf16 v[114:117], v[196:199], v[204:207], v[114:117]
	v_mfma_f32_16x16x32_bf16 v[102:105], v[188:191], v[226:229], v[102:105]
	v_mfma_f32_16x16x32_bf16 v[98:101], v[196:199], v[226:229], v[98:101]
	v_mfma_f32_16x16x32_bf16 v[84:87], v[188:191], v[234:237], v[84:87]
	v_mfma_f32_16x16x32_bf16 v[80:83], v[196:199], v[234:237], v[80:83]
	v_mfma_f32_16x16x32_bf16 v[68:71], v[188:191], v[242:245], v[68:71]
	v_mfma_f32_16x16x32_bf16 v[64:67], v[196:199], v[242:245], v[64:67]
	s_setprio 0
	s_barrier
; #define PG8_STAGE(bufoff, gbase, voff) do { _Pragma("unroll") for (int _i = 0; _i < 2; ++_i) \
;         __builtin_amdgcn_global_load_lds((const unsigned*)((const char*)(gbase) + (voff)[_i]), (LAS unsigned*)(lds + (bufoff) + ldsw + _i * 8192), 16, 0, 0); } while (0)
; #define PG8_LDA(dst, b, h) do { _Pragma("unroll") for (int m = 0; m < 4; ++m) _Pragma("unroll") for (int k = 0; k < 2; ++k) dst[m][k] = *(const LAS bf16x8*)(lds + PG8_SA(b, h) + aoff + m * 2048 + k * 1024); } while (0)
; #define PG8_MMA(ai, bj, At, Bt) do { __builtin_amdgcn_s_setprio(1); _Pragma("unroll") for (int m = 0; m < 4; ++m) _Pragma("unroll") for (int n = 0; n < 2; ++n) _Pragma("unroll") for (int k = 0; k < 2; ++k) \
;         acc[ai][bj][m][n] = __builtin_amdgcn_mfma_f32_16x16x32_bf16(Bt[n][k], At[m][k], acc[ai][bj][m][n], 0, 0, 0); __builtin_amdgcn_s_setprio(0); } while (0)
; #define PG8_WAIT_V(n) asm volatile("s_waitcnt vmcnt(" #n ")" ::: "memory")
; #define PG8_WAIT_L(n) asm volatile("s_waitcnt lgkmcnt(" #n ")" ::: "memory")
; #define PG8_BAR __builtin_amdgcn_s_barrier()
; #define PG8_SCHED __builtin_amdgcn_sched_barrier(0)
;     ...
;             PG8_LDA(At, 1, 1); PG8_STAGE(PG8_SB(1, 0), b3, voffB); PG8_STAGE(PG8_SB(1, 1), b3 + hstep, voffB); PG8_STAGE(PG8_SA(1, 0), a3, voffA);
;             PG8_WAIT_V(8); PG8_WAIT_L(0); PG8_BAR; PG8_MMA(1, 0, At, B0); PG8_MMA(1, 1, At, B1); PG8_BAR; PG8_SCHED;
;         }
	s_add_i32 s6, s11, s34
	v_lshl_add_u64 v[146:147], v[146:147], 0, s[46:47]
	s_mov_b32 m0, s6
	ds_read_b128 v[200:203], v172 offset:49152
	ds_read_b128 v[204:207], v172 offset:50176
	ds_read_b128 v[208:211], v172 offset:51200
	ds_read_b128 v[226:229], v172 offset:52224
	ds_read_b128 v[230:233], v172 offset:53248
	ds_read_b128 v[234:237], v172 offset:54272
	ds_read_b128 v[238:241], v172 offset:55296
	ds_read_b128 v[242:245], v172 offset:56320
	global_load_lds_dwordx4 v[146:147], off
	v_lshl_add_u64 v[146:147], v[162:163], 0, s[46:47]
	s_add_i32 m0, s6, 0x2000
	s_add_i32 s6, s23, s34
	global_load_lds_dwordx4 v[146:147], off
	v_lshl_add_u64 v[146:147], v[214:215], 0, s[46:47]
	s_mov_b32 m0, s6
	s_nop 0
	global_load_lds_dwordx4 v[146:147], off
	v_lshl_add_u64 v[146:147], v[246:247], 0, s[46:47]
	s_add_i32 m0, s6, 0x2000
	s_nop 0
	global_load_lds_dwordx4 v[146:147], off
	v_lshl_add_u64 v[146:147], v[248:249], 0, s[46:47]
	s_mov_b32 m0, s39
	s_nop 0
	global_load_lds_dwordx4 v[146:147], off
	v_lshl_add_u64 v[146:147], v[250:251], 0, s[46:47]
	s_mov_b32 m0, s40
	s_nop 0
	global_load_lds_dwordx4 v[146:147], off
	s_waitcnt vmcnt(8)
	s_waitcnt lgkmcnt(0)
	s_barrier
	s_setprio 1
	v_mfma_f32_16x16x32_bf16 v[60:63], v[130:133], v[200:203], v[60:63]
	v_mfma_f32_16x16x32_bf16 v[56:59], v[138:141], v[200:203], v[56:59]
	v_mfma_f32_16x16x32_bf16 v[44:47], v[130:133], v[208:211], v[44:47]
	v_mfma_f32_16x16x32_bf16 v[40:43], v[138:141], v[208:211], v[40:43]
	v_mfma_f32_16x16x32_bf16 v[28:31], v[130:133], v[230:233], v[28:31]
	v_mfma_f32_16x16x32_bf16 v[24:27], v[138:141], v[230:233], v[24:27]
	v_mfma_f32_16x16x32_bf16 v[12:15], v[130:133], v[238:241], v[12:15]
	v_mfma_f32_16x16x32_bf16 v[8:11], v[138:141], v[238:241], v[8:11]
	v_mfma_f32_16x16x32_bf16 v[60:63], v[134:137], v[204:207], v[60:63]
	v_mfma_f32_16x16x32_bf16 v[56:59], v[142:145], v[204:207], v[56:59]
	v_mfma_f32_16x16x32_bf16 v[44:47], v[134:137], v[226:229], v[44:47]
	v_mfma_f32_16x16x32_bf16 v[40:43], v[142:145], v[226:229], v[40:43]
	v_mfma_f32_16x16x32_bf16 v[28:31], v[134:137], v[234:237], v[28:31]
	v_mfma_f32_16x16x32_bf16 v[24:27], v[142:145], v[234:237], v[24:27]
	v_mfma_f32_16x16x32_bf16 v[12:15], v[134:137], v[242:245], v[12:15]
	v_mfma_f32_16x16x32_bf16 v[8:11], v[142:145], v[242:245], v[8:11]
	s_setprio 0
	s_setprio 1
	v_mfma_f32_16x16x32_bf16 v[52:55], v[174:177], v[200:203], v[52:55]
	v_mfma_f32_16x16x32_bf16 v[48:51], v[192:195], v[200:203], v[48:51]
	v_mfma_f32_16x16x32_bf16 v[36:39], v[174:177], v[208:211], v[36:39]
	v_mfma_f32_16x16x32_bf16 v[32:35], v[192:195], v[208:211], v[32:35]
	v_mfma_f32_16x16x32_bf16 v[20:23], v[174:177], v[230:233], v[20:23]
	v_mfma_f32_16x16x32_bf16 v[16:19], v[192:195], v[230:233], v[16:19]
	v_mfma_f32_16x16x32_bf16 v[4:7], v[174:177], v[238:241], v[4:7]
	v_mfma_f32_16x16x32_bf16 v[0:3], v[192:195], v[238:241], v[0:3]
	v_mfma_f32_16x16x32_bf16 v[52:55], v[188:191], v[204:207], v[52:55]
	v_mfma_f32_16x16x32_bf16 v[48:51], v[196:199], v[204:207], v[48:51]
	v_mfma_f32_16x16x32_bf16 v[36:39], v[188:191], v[226:229], v[36:39]
	v_mfma_f32_16x16x32_bf16 v[32:35], v[196:199], v[226:229], v[32:35]
	v_mfma_f32_16x16x32_bf16 v[20:23], v[188:191], v[234:237], v[20:23]
	v_mfma_f32_16x16x32_bf16 v[16:19], v[196:199], v[234:237], v[16:19]
	v_mfma_f32_16x16x32_bf16 v[4:7], v[188:191], v[242:245], v[4:7]
	v_mfma_f32_16x16x32_bf16 v[0:3], v[196:199], v[242:245], v[0:3]
	s_setprio 0
	s_barrier
	s_add_u32 s4, s4, 0x100
	s_addc_u32 s5, s5, 0
	s_add_u32 s8, s8, 0x100
	s_addc_u32 s9, s9, 0
	s_cmp_ge_u32 s10, s41
	s_mov_b32 s6, s10
	s_cbranch_scc0 .LBB0_813
	s_and_b64 vcc, exec, s[18:19]
	s_cbranch_vccz .LBB0_816
